# instruction selection: 202 IEEE f32 division sequences (sigmoid/silu in the RG-LRU gates epilogue, gla_post, lru_scan) replaced by v_rcp_f32 + v_mul_f32; dead div_scale/fma/fmas chains deleted, wait s
# speedup vs baseline: 1.0069x; 1.0069x over previous
; DI u32x4 pack8(const float (&f)[8]) { u32x4 w; w.x = pk2(f[0], f[1]); w.y = pk2(f[2], f[3]); w.z = pk2(f[4], f[5]); w.w = pk2(f[6], f[7]); return w; }
; DI float silu(float x) { return x / (1.f + __expf(-x)); }
; DI void phase_gla_post(const Params& p) {
;     ...
;     for (int row = gw; row < MTOK; row += 2 * nw) {
;         u32x4 wo[2][4], wg[2][4]; bool ok[2]; size_t rr[2];
; #pragma unroll
;         for (int r = 0; r < 2; ++r) { ok[r] = row + r * nw < MTOK; rr[r] = ok[r] ? (size_t)(row + r * nw) : (size_t)row;
; #pragma unroll
;             for (int hd = 0; hd < 4; ++hd) { wo[r][hd] = *(const u32x4*)(y + rr[r] * DM + hd * 512 + lane * 8); wg[r][hd] = *(const u32x4*)(big + rr[r] * 6400 + 4096 + hd * 512 + lane * 8); } }
; #pragma unroll
;         for (int r = 0; r < 2; ++r)
; #pragma unroll
;             for (int hd = 0; hd < 4; ++hd) {
;                 float f[8], g[8]; unpack8(wo[r][hd], f); unpack8(wg[r][hd], g);
;                 float ss = 0.f;
; #pragma unroll
;                 for (int e = 0; e < 8; ++e) ss += f[e] * f[e];
;                 ss = wsum(ss); const float sc = rsqrtf(ss * (1.f / 512.f) + EPS);
; #pragma unroll
;                 for (int e = 0; e < 8; ++e) f[e] = f[e] * sc * og[e] * silu(g[e]);
;                 if (ok[r]) *(u32x4*)(y + rr[r] * DM + hd * 512 + lane * 8) = pack8(f);
;             }
.LBB0_657:
	v_ashrrev_i32_e32 v9, 31, v8
	v_lshlrev_b64 v[10:11], 12, v[8:9]
	v_lshl_add_u64 v[74:75], v[66:67], 0, v[10:11]
	v_mad_i64_i32 v[10:11], s[8:9], v8, s27, v[68:69]
	v_lshl_add_u64 v[10:11], v[10:11], 0, v[64:65]
	v_add_co_u32_e32 v12, vcc, s28, v10
	global_load_dwordx4 v[92:95], v[74:75], off
	s_nop 0
	v_addc_co_u32_e32 v13, vcc, 0, v11, vcc
	global_load_dwordx4 v[96:99], v[12:13], off
	v_add_u32_e32 v107, s62, v8
	v_cmp_gt_i32_e64 s[8:9], s3, v107
	v_lshl_add_u64 v[76:77], v[10:11], 0, s[24:25]
	s_waitcnt vmcnt(1)
	v_lshlrev_b32_e32 v80, 16, v93
	v_cndmask_b32_e64 v8, v8, v107, s[8:9]
	v_mad_i64_i32 v[12:13], s[10:11], v8, s27, v[68:69]
	v_lshl_add_u64 v[12:13], v[12:13], 0, v[64:65]
	v_add_co_u32_e32 v14, vcc, s28, v12
	v_ashrrev_i32_e32 v9, 31, v8
	s_waitcnt lgkmcnt(0)
	v_addc_co_u32_e32 v15, vcc, 0, v13, vcc
	global_load_dwordx4 v[32:35], v[14:15], off
	global_load_dwordx4 v[60:63], v[74:75], off offset:1024
	global_load_dwordx4 v[56:59], v[76:77], off offset:1024
	global_load_dwordx4 v[48:51], v[76:77], off offset:2048
	global_load_dwordx4 v[52:55], v[74:75], off offset:2048
	global_load_dwordx4 v[44:47], v[74:75], off offset:3072
	v_lshlrev_b64 v[8:9], 12, v[8:9]
	s_waitcnt vmcnt(6)
	v_lshlrev_b32_e32 v90, 16, v98
	v_and_b32_e32 v91, 0xffff0000, v98
	v_lshl_add_u64 v[72:73], v[66:67], 0, v[8:9]
	v_lshl_add_u64 v[78:79], v[12:13], 0, s[24:25]
	v_mul_f32_e32 v82, 0xbfb8aa3b, v90
	v_mul_f32_e32 v83, 0xbfb8aa3b, v91
	global_load_dwordx4 v[36:39], v[72:73], off
	global_load_dwordx4 v[28:31], v[72:73], off offset:1024
	global_load_dwordx4 v[40:43], v[76:77], off offset:3072
	global_load_dwordx4 v[24:27], v[78:79], off offset:1024
	global_load_dwordx4 v[20:23], v[72:73], off offset:2048
	global_load_dwordx4 v[12:15], v[72:73], off offset:3072
	global_load_dwordx4 v[16:19], v[78:79], off offset:2048
	global_load_dwordx4 v[8:11], v[78:79], off offset:3072
	v_lshlrev_b32_e32 v78, 16, v94
	v_and_b32_e32 v79, 0xffff0000, v94
	v_and_b32_e32 v81, 0xffff0000, v93
	v_lshlrev_b32_e32 v93, 16, v97
	v_and_b32_e32 v94, 0xffff0000, v97
	v_exp_f32_e32 v82, v82
	v_exp_f32_e32 v83, v83
	v_mul_f32_e32 v84, 0xbfb8aa3b, v93
	v_mul_f32_e32 v85, 0xbfb8aa3b, v94
	v_exp_f32_e32 v84, v84
	v_exp_f32_e32 v85, v85
	v_pk_add_f32 v[82:83], v[82:83], 1.0 op_sel_hi:[1,0]
	v_lshlrev_b32_e32 v76, 16, v95
	v_and_b32_e32 v77, 0xffff0000, v95
	v_pk_add_f32 v[84:85], v[84:85], 1.0 op_sel_hi:[1,0]
	v_div_scale_f32 v98, s[10:11], v82, v82, v90
	v_div_scale_f32 v109, s[12:13], v85, v85, v94
	v_rcp_f32_e32 v113, v98
	v_rcp_f32_e32 v114, v109
	v_fma_f32 v117, -v98, v113, 1.0
	v_div_scale_f32 v108, s[10:11], v90, v82, v90
	v_fma_f32 v118, -v109, v114, 1.0
	v_fmac_f32_e32 v113, v117, v113
	v_div_scale_f32 v110, s[12:13], v94, v85, v94
	v_fmac_f32_e32 v114, v118, v114
	v_mul_f32_e32 v117, v108, v113
	v_mul_f32_e32 v118, v110, v114
	v_fma_f32 v120, -v98, v117, v108
	v_fma_f32 v121, -v109, v118, v110
	v_fmac_f32_e32 v117, v120, v113
	v_fmac_f32_e32 v118, v121, v114
	v_fma_f32 v97, -v98, v117, v108
	s_mov_b64 vcc, s[10:11]
	v_fma_f32 v98, -v109, v118, v110
	v_rcp_f32_e32 v95, v83
	s_nop 0
	v_mul_f32_e32 v83, v91, v95
	v_div_fmas_f32 v91, v97, v113, v117
	s_mov_b64 vcc, s[12:13]
	v_div_fixup_f32 v82, v91, v82, v90
	v_div_fmas_f32 v90, v98, v114, v118
	v_div_fixup_f32 v85, v90, v85, v94
	v_lshlrev_b32_e32 v97, 16, v96
	v_and_b32_e32 v96, 0xffff0000, v96
	v_mul_f32_e32 v90, 0xbfb8aa3b, v97
	v_mul_f32_e32 v91, 0xbfb8aa3b, v96
	v_exp_f32_e32 v90, v90
	v_exp_f32_e32 v91, v91
	v_rcp_f32_e32 v98, v84
	s_nop 0
	v_mul_f32_e32 v84, v93, v98
	v_pk_add_f32 v[94:95], v[90:91], 1.0 op_sel_hi:[1,0]
	v_lshlrev_b32_e32 v90, 16, v92
	v_and_b32_e32 v91, 0xffff0000, v92
	v_lshlrev_b32_e32 v110, 16, v99
	v_and_b32_e32 v99, 0xffff0000, v99
	v_rcp_f32_e32 v92, v95
	s_nop 0
	v_mul_f32_e32 v95, v96, v92
	v_mul_f32_e32 v93, 0xbfb8aa3b, v99
	v_mul_f32_e32 v92, 0xbfb8aa3b, v110
	v_exp_f32_e32 v92, v92
	v_exp_f32_e32 v93, v93
	s_nop 0
	v_pk_add_f32 v[92:93], v[92:93], 1.0 op_sel_hi:[1,0]
	v_rcp_f32_e32 v96, v94
	s_nop 0
	v_mul_f32_e32 v94, v97, v96
	s_waitcnt vmcnt(11)
	v_lshlrev_b32_e32 v116, 16, v58
	v_rcp_f32_e32 v96, v93
	s_nop 0
	v_mul_f32_e32 v99, v99, v96
	v_and_b32_e32 v58, 0xffff0000, v58
	v_rcp_f32_e32 v93, v92
	s_nop 0
	v_mul_f32_e32 v98, v110, v93
	v_mul_f32_e32 v92, 0xbfb8aa3b, v116
	v_exp_f32_e32 v96, v92
	v_mul_f32_e32 v92, 0xbfb8aa3b, v58
	v_exp_f32_e32 v97, v92
	v_lshlrev_b32_e32 v92, 16, v63
	v_and_b32_e32 v93, 0xffff0000, v63
	v_lshlrev_b32_e32 v126, 16, v57
	v_pk_add_f32 v[110:111], v[96:97], 1.0 op_sel_hi:[1,0]
	v_lshlrev_b32_e32 v96, 16, v62
	v_and_b32_e32 v97, 0xffff0000, v62
	v_and_b32_e32 v57, 0xffff0000, v57
	v_lshlrev_b32_e32 v128, 16, v56
	v_rcp_f32_e32 v62, v111
	s_nop 0
	v_mul_f32_e32 v63, v58, v62
	v_mul_f32_e32 v111, 0xbfb8aa3b, v126
	v_exp_f32_e32 v114, v111
	v_mul_f32_e32 v111, 0xbfb8aa3b, v57
	v_exp_f32_e32 v115, v111
	v_rcp_f32_e32 v58, v110
	s_nop 0
	v_mul_f32_e32 v62, v116, v58
	v_pk_add_f32 v[114:115], v[114:115], 1.0 op_sel_hi:[1,0]
	v_lshlrev_b32_e32 v110, 16, v61
	v_and_b32_e32 v111, 0xffff0000, v61
	v_rcp_f32_e32 v58, v115
	s_nop 0
	v_mul_f32_e32 v57, v57, v58
	v_and_b32_e32 v129, 0xffff0000, v56
	v_mul_f32_e32 v56, 0xbfb8aa3b, v128
	v_exp_f32_e32 v116, v56
	v_mul_f32_e32 v56, 0xbfb8aa3b, v129
	v_exp_f32_e32 v117, v56
	v_and_b32_e32 v119, 0xffff0000, v60
	v_lshlrev_b32_e32 v118, 16, v60
	v_mov_b32_e32 v124, v119
	v_mov_b32_e32 v125, v91
	v_mov_b32_e32 v122, v118
	v_mov_b32_e32 v123, v90
	v_pk_mul_f32 v[124:125], v[124:125], v[124:125]
	v_pk_add_f32 v[60:61], v[116:117], 1.0 op_sel_hi:[1,0]
	v_mov_b32_e32 v116, v110
	v_mov_b32_e32 v117, v80
	v_pk_fma_f32 v[122:123], v[122:123], v[122:123], v[124:125]
	v_pk_mul_f32 v[88:89], v[78:79], v[78:79]
	v_pk_mul_f32 v[112:113], v[96:97], v[96:97]
	v_mov_b32_e32 v120, v111
	v_mov_b32_e32 v121, v81
	v_pk_fma_f32 v[116:117], v[116:117], v[116:117], v[122:123]
	v_pk_mul_f32 v[86:87], v[76:77], v[76:77]
	v_pk_fma_f32 v[116:117], v[120:121], v[120:121], v[116:117]
	v_mov_b32_e32 v120, v112
	v_mov_b32_e32 v121, v88
	v_pk_mul_f32 v[108:109], v[92:93], v[92:93]
	v_pk_add_f32 v[116:117], v[120:121], v[116:117]
	v_mov_b32_e32 v88, v113
	v_pk_add_f32 v[88:89], v[88:89], v[116:117]
	v_mov_b32_e32 v112, v108
	v_mov_b32_e32 v113, v86
	v_pk_add_f32 v[88:89], v[112:113], v[88:89]
	v_mov_b32_e32 v86, v109
	v_pk_add_f32 v[86:87], v[86:87], v[88:89]
	ds_bpermute_b32 v89, v100, v87
	ds_bpermute_b32 v88, v100, v86
	s_waitcnt lgkmcnt(0)
; DI u32x4 pack8(const float (&f)[8]) { u32x4 w; w.x = pk2(f[0], f[1]); w.y = pk2(f[2], f[3]); w.z = pk2(f[4], f[5]); w.w = pk2(f[6], f[7]); return w; }
; DI float silu(float x) { return x / (1.f + __expf(-x)); }
; DI void phase_gla_post(const Params& p) {
;     ...
; #pragma unroll
;         for (int r = 0; r < 2; ++r) { ok[r] = row + r * nw < MTOK; rr[r] = ok[r] ? (size_t)(row + r * nw) : (size_t)row;
; #pragma unroll
;             for (int hd = 0; hd < 4; ++hd) { wo[r][hd] = *(const u32x4*)(y + rr[r] * DM + hd * 512 + lane * 8); wg[r][hd] = *(const u32x4*)(big + rr[r] * 6400 + 4096 + hd * 512 + lane * 8); } }
; #pragma unroll
;         for (int r = 0; r < 2; ++r)
; #pragma unroll
;             for (int hd = 0; hd < 4; ++hd) {
;                 float f[8], g[8]; unpack8(wo[r][hd], f); unpack8(wg[r][hd], g);
;                 float ss = 0.f;
; #pragma unroll
;                 for (int e = 0; e < 8; ++e) ss += f[e] * f[e];
;                 ss = wsum(ss); const float sc = rsqrtf(ss * (1.f / 512.f) + EPS);
; #pragma unroll
;                 for (int e = 0; e < 8; ++e) f[e] = f[e] * sc * og[e] * silu(g[e]);
;                 if (ok[r]) *(u32x4*)(y + rr[r] * DM + hd * 512 + lane * 8) = pack8(f);
;             }
	v_pk_add_f32 v[86:87], v[86:87], v[88:89]
	ds_bpermute_b32 v89, v101, v87
	ds_bpermute_b32 v88, v101, v86
	s_waitcnt lgkmcnt(0)
	v_pk_add_f32 v[86:87], v[86:87], v[88:89]
	ds_bpermute_b32 v89, v102, v87
	ds_bpermute_b32 v88, v102, v86
	s_waitcnt lgkmcnt(0)
	v_pk_add_f32 v[86:87], v[86:87], v[88:89]
	ds_bpermute_b32 v89, v103, v87
	ds_bpermute_b32 v88, v103, v86
	v_rcp_f32_e32 v58, v61
	s_nop 0
	v_mul_f32_e32 v61, v129, v58
	s_waitcnt lgkmcnt(0)
	v_pk_add_f32 v[86:87], v[86:87], v[88:89]
	ds_bpermute_b32 v89, v104, v87
	ds_bpermute_b32 v88, v104, v86
	v_rcp_f32_e32 v56, v114
	s_nop 0
	v_mul_f32_e32 v56, v126, v56
	s_waitcnt lgkmcnt(0)
	v_pk_add_f32 v[86:87], v[86:87], v[88:89]
	ds_bpermute_b32 v89, v105, v87
	ds_bpermute_b32 v88, v105, v86
	s_waitcnt lgkmcnt(0)
	v_pk_add_f32 v[86:87], v[86:87], v[88:89]
	v_pk_fma_f32 v[86:87], v[86:87], s[26:27], v[70:71] op_sel_hi:[1,0,0]
	v_mul_f32_e32 v88, 0x4b800000, v87
	v_cmp_gt_f32_e64 s[10:11], s29, v87
	s_nop 1
	v_cndmask_b32_e64 v87, v87, v88, s[10:11]
	v_rsq_f32_e32 v87, v87
	v_rcp_f32_e32 v58, v60
	s_nop 0
	v_mul_f32_e32 v60, v128, v58
	v_cmp_gt_f32_e32 vcc, s29, v86
	v_mul_f32_e32 v58, 0x45800000, v87
	v_cndmask_b32_e64 v58, v87, v58, s[10:11]
	v_pk_mul_f32 v[88:89], v[58:59], v[90:91] op_sel_hi:[0,1]
	v_pk_mul_f32 v[80:81], v[58:59], v[80:81] op_sel_hi:[0,1]
	v_pk_mul_f32 v[78:79], v[58:59], v[78:79] op_sel_hi:[0,1]
	v_pk_mul_f32 v[76:77], v[58:59], v[76:77] op_sel_hi:[0,1]
	v_mul_f32_e32 v58, 0x4b800000, v86
	v_cndmask_b32_e32 v58, v86, v58, vcc
	v_rsq_f32_e32 v58, v58
	v_pk_mul_f32 v[88:89], v[4:5], v[88:89]
	v_pk_mul_f32 v[80:81], v[6:7], v[80:81]
	v_pk_mul_f32 v[78:79], v[0:1], v[78:79]
	v_pk_mul_f32 v[76:77], v[2:3], v[76:77]
	v_pk_mul_f32 v[88:89], v[94:95], v[88:89]
	v_pk_mul_f32 v[80:81], v[84:85], v[80:81]
	v_pk_mul_f32 v[78:79], v[82:83], v[78:79]
	v_pk_mul_f32 v[82:83], v[98:99], v[76:77]
	v_cvt_pk_bf16_f32 v76, v88, v89
	v_cvt_pk_bf16_f32 v77, v80, v81
	v_cvt_pk_bf16_f32 v78, v78, v79
	v_cvt_pk_bf16_f32 v79, v82, v83
	global_store_dwordx4 v[74:75], v[76:79], off
	v_lshlrev_b32_e32 v80, 16, v59
	s_waitcnt vmcnt(11)
	v_and_b32_e32 v84, 0xffff0000, v48
	v_mul_f32_e32 v76, 0x45800000, v58
	v_cndmask_b32_e32 v58, v58, v76, vcc
	v_pk_mul_f32 v[76:77], v[58:59], v[118:119] op_sel_hi:[0,1]
	v_pk_mul_f32 v[76:77], v[4:5], v[76:77]
	v_and_b32_e32 v59, 0xffff0000, v59
	v_pk_mul_f32 v[60:61], v[60:61], v[76:77]
	v_mul_f32_e32 v76, 0xbfb8aa3b, v80
	v_mul_f32_e32 v77, 0xbfb8aa3b, v59
	v_exp_f32_e32 v76, v76
	v_exp_f32_e32 v77, v77
	v_pk_mul_f32 v[78:79], v[58:59], v[110:111] op_sel_hi:[0,1]
	v_pk_mul_f32 v[78:79], v[6:7], v[78:79]
	s_waitcnt vmcnt(6)
	v_lshlrev_b32_e32 v110, 16, v41
	v_pk_mul_f32 v[78:79], v[56:57], v[78:79]
	v_pk_add_f32 v[56:57], v[76:77], 1.0 op_sel_hi:[1,0]
	v_pk_mul_f32 v[76:77], v[58:59], v[96:97] op_sel_hi:[0,1]
	v_pk_mul_f32 v[76:77], v[0:1], v[76:77]
	v_and_b32_e32 v41, 0xffff0000, v41
	v_pk_mul_f32 v[62:63], v[62:63], v[76:77]
	v_rcp_f32_e32 v76, v57
	s_nop 0
	v_mul_f32_e32 v57, v59, v76
	v_lshlrev_b32_e32 v112, 16, v40
	v_rcp_f32_e32 v59, v56
	s_nop 0
	v_mul_f32_e32 v56, v80, v59
	v_pk_mul_f32 v[58:59], v[58:59], v[92:93] op_sel_hi:[0,1]
	v_pk_mul_f32 v[58:59], v[2:3], v[58:59]
	v_lshlrev_b32_e32 v80, 16, v50
	v_pk_mul_f32 v[76:77], v[56:57], v[58:59]
	v_cvt_pk_bf16_f32 v56, v60, v61
	v_cvt_pk_bf16_f32 v57, v78, v79
	v_cvt_pk_bf16_f32 v58, v62, v63
	v_cvt_pk_bf16_f32 v59, v76, v77
	global_store_dwordx4 v[74:75], v[56:59], off offset:1024
	v_and_b32_e32 v50, 0xffff0000, v50
	v_lshlrev_b32_e32 v83, 16, v49
	v_mul_f32_e32 v56, 0xbfb8aa3b, v80
	v_exp_f32_e32 v58, v56
	v_mul_f32_e32 v56, 0xbfb8aa3b, v50
	v_exp_f32_e32 v59, v56
	v_lshlrev_b32_e32 v56, 16, v55
	v_and_b32_e32 v57, 0xffff0000, v55
	v_and_b32_e32 v49, 0xffff0000, v49
	v_pk_add_f32 v[60:61], v[58:59], 1.0 op_sel_hi:[1,0]
	v_lshlrev_b32_e32 v58, 16, v54
	v_and_b32_e32 v59, 0xffff0000, v54
	v_lshlrev_b32_e32 v92, 16, v42
	v_and_b32_e32 v42, 0xffff0000, v42
	v_rcp_f32_e32 v54, v61
	s_nop 0
	v_mul_f32_e32 v55, v50, v54
	v_mul_f32_e32 v61, 0xbfb8aa3b, v83
	v_exp_f32_e32 v76, v61
	v_mul_f32_e32 v61, 0xbfb8aa3b, v49
	v_exp_f32_e32 v77, v61
	v_rcp_f32_e32 v50, v60
	s_nop 0
	v_mul_f32_e32 v54, v80, v50
	v_pk_add_f32 v[76:77], v[76:77], 1.0 op_sel_hi:[1,0]
	v_lshlrev_b32_e32 v60, 16, v53
	v_and_b32_e32 v61, 0xffff0000, v53
	v_and_b32_e32 v113, 0xffff0000, v40
	v_mul_f32_e32 v40, 0xbfb8aa3b, v112
	v_rcp_f32_e32 v50, v77
	s_nop 0
	v_mul_f32_e32 v77, v49, v50
	v_lshlrev_b32_e32 v82, 16, v48
	v_mul_f32_e32 v48, 0xbfb8aa3b, v82
	v_mul_f32_e32 v49, 0xbfb8aa3b, v84
	v_exp_f32_e32 v48, v48
	v_exp_f32_e32 v49, v49
	v_rcp_f32_e32 v50, v76
	s_nop 0
	v_mul_f32_e32 v76, v83, v50
	v_pk_add_f32 v[48:49], v[48:49], 1.0 op_sel_hi:[1,0]
	v_lshlrev_b32_e32 v80, 16, v52
	v_and_b32_e32 v81, 0xffff0000, v52
	v_mov_b32_e32 v109, v81
	v_mov_b32_e32 v99, v80
	v_rcp_f32_e32 v50, v49
	s_nop 0
	v_mul_f32_e32 v53, v84, v50
	v_lshlrev_b32_e32 v84, 16, v51
	v_and_b32_e32 v85, 0xffff0000, v51
	v_mul_f32_e32 v50, 0xbfb8aa3b, v84
	v_mul_f32_e32 v51, 0xbfb8aa3b, v85
	v_exp_f32_e32 v50, v50
	v_exp_f32_e32 v51, v51
	s_nop 0
	v_pk_add_f32 v[50:51], v[50:51], 1.0 op_sel_hi:[1,0]
	v_rcp_f32_e32 v49, v48
	s_nop 0
	v_mul_f32_e32 v52, v82, v49
	v_pk_mul_f32 v[78:79], v[58:59], v[58:59]
	v_rcp_f32_e32 v48, v51
	s_nop 0
	v_mul_f32_e32 v83, v85, v48
	v_rcp_f32_e32 v48, v50
	s_nop 0
	v_mul_f32_e32 v82, v84, v48
	v_mul_f32_e32 v48, 0xbfb8aa3b, v92
	v_exp_f32_e32 v50, v48
	v_mul_f32_e32 v48, 0xbfb8aa3b, v42
	v_exp_f32_e32 v51, v48
	v_lshlrev_b32_e32 v48, 16, v47
	v_and_b32_e32 v49, 0xffff0000, v47
	v_mov_b32_e32 v97, v61
	v_pk_add_f32 v[86:87], v[50:51], 1.0 op_sel_hi:[1,0]
; DI u32x4 pack8(const float (&f)[8]) { u32x4 w; w.x = pk2(f[0], f[1]); w.y = pk2(f[2], f[3]); w.z = pk2(f[4], f[5]); w.w = pk2(f[6], f[7]); return w; }
; DI float silu(float x) { return x / (1.f + __expf(-x)); }
; DI void phase_gla_post(const Params& p) {
;     ...
; #pragma unroll
;         for (int r = 0; r < 2; ++r) { ok[r] = row + r * nw < MTOK; rr[r] = ok[r] ? (size_t)(row + r * nw) : (size_t)row;
; #pragma unroll
;             for (int hd = 0; hd < 4; ++hd) { wo[r][hd] = *(const u32x4*)(y + rr[r] * DM + hd * 512 + lane * 8); wg[r][hd] = *(const u32x4*)(big + rr[r] * 6400 + 4096 + hd * 512 + lane * 8); } }
; #pragma unroll
;         for (int r = 0; r < 2; ++r)
; #pragma unroll
;             for (int hd = 0; hd < 4; ++hd) {
;                 float f[8], g[8]; unpack8(wo[r][hd], f); unpack8(wg[r][hd], g);
;                 float ss = 0.f;
; #pragma unroll
;                 for (int e = 0; e < 8; ++e) ss += f[e] * f[e];
;                 ss = wsum(ss); const float sc = rsqrtf(ss * (1.f / 512.f) + EPS);
; #pragma unroll
;                 for (int e = 0; e < 8; ++e) f[e] = f[e] * sc * og[e] * silu(g[e]);
;                 if (ok[r]) *(u32x4*)(y + rr[r] * DM + hd * 512 + lane * 8) = pack8(f);
;             }
	v_lshlrev_b32_e32 v50, 16, v46
	v_and_b32_e32 v51, 0xffff0000, v46
	v_pk_mul_f32 v[88:89], v[50:51], v[50:51]
	v_pk_mul_f32 v[62:63], v[56:57], v[56:57]
	v_rcp_f32_e32 v46, v87
	s_nop 0
	v_mul_f32_e32 v47, v42, v46
	v_mul_f32_e32 v87, 0xbfb8aa3b, v110
	v_exp_f32_e32 v90, v87
	v_mul_f32_e32 v87, 0xbfb8aa3b, v41
	v_exp_f32_e32 v91, v87
	v_rcp_f32_e32 v42, v86
	s_nop 0
	v_mul_f32_e32 v46, v92, v42
	v_pk_add_f32 v[90:91], v[90:91], 1.0 op_sel_hi:[1,0]
	v_lshlrev_b32_e32 v86, 16, v45
	v_and_b32_e32 v87, 0xffff0000, v45
	v_rcp_f32_e32 v42, v91
	s_nop 0
	v_mul_f32_e32 v41, v41, v42
	v_exp_f32_e32 v92, v40
	v_mul_f32_e32 v40, 0xbfb8aa3b, v113
	v_exp_f32_e32 v93, v40
	v_and_b32_e32 v95, 0xffff0000, v44
	v_lshlrev_b32_e32 v94, 16, v44
	v_mov_b32_e32 v108, v95
	v_mov_b32_e32 v98, v94
	v_pk_mul_f32 v[108:109], v[108:109], v[108:109]
	v_pk_add_f32 v[44:45], v[92:93], 1.0 op_sel_hi:[1,0]
	v_mov_b32_e32 v92, v86
	v_mov_b32_e32 v93, v60
	v_pk_fma_f32 v[98:99], v[98:99], v[98:99], v[108:109]
	v_mov_b32_e32 v96, v87
	v_pk_fma_f32 v[92:93], v[92:93], v[92:93], v[98:99]
	v_pk_mul_f32 v[84:85], v[48:49], v[48:49]
	v_pk_fma_f32 v[92:93], v[96:97], v[96:97], v[92:93]
	v_mov_b32_e32 v96, v88
	v_mov_b32_e32 v97, v78
	v_pk_add_f32 v[92:93], v[96:97], v[92:93]
	v_mov_b32_e32 v78, v89
	v_pk_add_f32 v[78:79], v[78:79], v[92:93]
	v_mov_b32_e32 v88, v84
	v_mov_b32_e32 v89, v62
	v_pk_add_f32 v[78:79], v[88:89], v[78:79]
	v_mov_b32_e32 v62, v85
	v_pk_add_f32 v[62:63], v[62:63], v[78:79]
	ds_bpermute_b32 v79, v100, v63
	ds_bpermute_b32 v78, v100, v62
	s_waitcnt lgkmcnt(0)
	v_pk_add_f32 v[62:63], v[62:63], v[78:79]
	ds_bpermute_b32 v79, v101, v63
	ds_bpermute_b32 v78, v101, v62
	s_waitcnt lgkmcnt(0)
	v_pk_add_f32 v[62:63], v[62:63], v[78:79]
	ds_bpermute_b32 v79, v102, v63
	ds_bpermute_b32 v78, v102, v62
	s_waitcnt lgkmcnt(0)
	v_pk_add_f32 v[62:63], v[62:63], v[78:79]
	ds_bpermute_b32 v79, v103, v63
	ds_bpermute_b32 v78, v103, v62
	v_rcp_f32_e32 v42, v45
	s_nop 0
	v_mul_f32_e32 v45, v113, v42
	s_waitcnt lgkmcnt(0)
	v_pk_add_f32 v[62:63], v[62:63], v[78:79]
	ds_bpermute_b32 v79, v104, v63
	ds_bpermute_b32 v78, v104, v62
	v_rcp_f32_e32 v40, v90
	s_nop 0
	v_mul_f32_e32 v40, v110, v40
	s_waitcnt lgkmcnt(0)
	v_pk_add_f32 v[62:63], v[62:63], v[78:79]
	ds_bpermute_b32 v79, v105, v63
	ds_bpermute_b32 v78, v105, v62
	s_waitcnt lgkmcnt(0)
	v_pk_add_f32 v[62:63], v[62:63], v[78:79]
	v_pk_fma_f32 v[62:63], v[62:63], s[26:27], v[70:71] op_sel_hi:[1,0,0]
	v_mul_f32_e32 v78, 0x4b800000, v63
	v_cmp_gt_f32_e64 s[10:11], s29, v63
	s_nop 1
	v_cndmask_b32_e64 v63, v63, v78, s[10:11]
	v_rsq_f32_e32 v63, v63
	v_rcp_f32_e32 v42, v44
	s_nop 0
	v_mul_f32_e32 v44, v112, v42
	v_cmp_gt_f32_e32 vcc, s29, v62
	v_mul_f32_e32 v42, 0x45800000, v63
	v_cndmask_b32_e64 v42, v63, v42, s[10:11]
	v_pk_mul_f32 v[78:79], v[42:43], v[80:81] op_sel_hi:[0,1]
	v_pk_mul_f32 v[60:61], v[42:43], v[60:61] op_sel_hi:[0,1]
	v_pk_mul_f32 v[58:59], v[42:43], v[58:59] op_sel_hi:[0,1]
	v_pk_mul_f32 v[56:57], v[42:43], v[56:57] op_sel_hi:[0,1]
	v_mul_f32_e32 v42, 0x4b800000, v62
	v_cndmask_b32_e32 v42, v62, v42, vcc
	v_rsq_f32_e32 v42, v42
	v_pk_mul_f32 v[78:79], v[4:5], v[78:79]
	v_pk_mul_f32 v[60:61], v[6:7], v[60:61]
	v_pk_mul_f32 v[58:59], v[0:1], v[58:59]
	v_pk_mul_f32 v[56:57], v[2:3], v[56:57]
	v_pk_mul_f32 v[52:53], v[52:53], v[78:79]
	v_pk_mul_f32 v[60:61], v[76:77], v[60:61]
	v_pk_mul_f32 v[54:55], v[54:55], v[58:59]
	v_pk_mul_f32 v[56:57], v[82:83], v[56:57]
	v_cvt_pk_bf16_f32 v52, v52, v53
	v_cvt_pk_bf16_f32 v53, v60, v61
	v_cvt_pk_bf16_f32 v54, v54, v55
	v_cvt_pk_bf16_f32 v55, v56, v57
	global_store_dwordx4 v[74:75], v[52:55], off offset:2048
	v_and_b32_e32 v76, 0xffff0000, v43
	s_nop 0
	v_mul_f32_e32 v52, 0x45800000, v42
	v_cndmask_b32_e32 v52, v42, v52, vcc
	v_pk_mul_f32 v[54:55], v[52:53], v[94:95] op_sel_hi:[0,1]
	v_lshlrev_b32_e32 v53, 16, v43
	v_mul_f32_e32 v42, 0xbfb8aa3b, v53
	v_mul_f32_e32 v43, 0xbfb8aa3b, v76
	v_exp_f32_e32 v42, v42
	v_exp_f32_e32 v43, v43
	v_pk_mul_f32 v[54:55], v[4:5], v[54:55]
	v_pk_add_f32 v[58:59], v[42:43], 1.0 op_sel_hi:[1,0]
	s_nop 0
	v_pk_mul_f32 v[54:55], v[44:45], v[54:55]
	v_pk_mul_f32 v[44:45], v[52:53], v[86:87] op_sel_hi:[0,1]
	v_pk_mul_f32 v[44:45], v[6:7], v[44:45]
	v_pk_mul_f32 v[56:57], v[40:41], v[44:45]
	v_pk_mul_f32 v[40:41], v[52:53], v[50:51] op_sel_hi:[0,1]
	v_pk_mul_f32 v[40:41], v[0:1], v[40:41]
	v_lshlrev_b32_e32 v44, 16, v36
	v_pk_mul_f32 v[50:51], v[46:47], v[40:41]
	v_and_b32_e32 v45, 0xffff0000, v36
	v_pk_mul_f32 v[46:47], v[44:45], v[44:45]
	v_lshlrev_b32_e32 v42, 16, v37
	v_and_b32_e32 v43, 0xffff0000, v37
	v_pk_mul_f32 v[60:61], v[42:43], v[42:43]
	v_add_f32_e32 v46, v46, v47
	v_lshlrev_b32_e32 v40, 16, v38
	v_and_b32_e32 v41, 0xffff0000, v38
	v_add_f32_e32 v46, v60, v46
	v_pk_mul_f32 v[62:63], v[40:41], v[40:41]
	v_add_f32_e32 v46, v61, v46
	v_lshlrev_b32_e32 v36, 16, v39
	v_and_b32_e32 v37, 0xffff0000, v39
	v_add_f32_e32 v46, v62, v46
	v_pk_mul_f32 v[38:39], v[36:37], v[36:37]
	v_add_f32_e32 v46, v63, v46
	v_add_f32_e32 v38, v38, v46
	v_add_f32_e32 v38, v39, v38
	ds_bpermute_b32 v39, v100, v38
	s_waitcnt lgkmcnt(0)
	v_add_f32_e32 v38, v38, v39
	ds_bpermute_b32 v61, v101, v38
	v_rcp_f32_e32 v39, v59
	s_nop 0
	v_mul_f32_e32 v39, v76, v39
	s_waitcnt lgkmcnt(0)
	v_add_f32_e32 v38, v38, v61
	ds_bpermute_b32 v46, v102, v38
	s_waitcnt lgkmcnt(0)
	v_add_f32_e32 v46, v38, v46
	ds_bpermute_b32 v62, v103, v46
	v_rcp_f32_e32 v38, v58
	s_nop 0
	v_mul_f32_e32 v38, v53, v38
	s_waitcnt lgkmcnt(0)
	v_add_f32_e32 v58, v46, v62
	ds_bpermute_b32 v59, v104, v58
	v_pk_mul_f32 v[46:47], v[52:53], v[48:49] op_sel_hi:[0,1]
	v_pk_mul_f32 v[46:47], v[2:3], v[46:47]
	v_cvt_pk_bf16_f32 v48, v50, v51
	v_pk_mul_f32 v[52:53], v[38:39], v[46:47]
	s_waitcnt lgkmcnt(0)
	v_add_f32_e32 v38, v58, v59
	ds_bpermute_b32 v39, v105, v38
	v_cvt_pk_bf16_f32 v46, v54, v55
	v_cvt_pk_bf16_f32 v47, v56, v57
	v_cvt_pk_bf16_f32 v49, v52, v53
	global_store_dwordx4 v[74:75], v[46:49], off offset:3072
	s_and_saveexec_b64 s[10:11], s[8:9]
	s_cbranch_execz .LBB0_659
; DI u32x4 pack8(const float (&f)[8]) { u32x4 w; w.x = pk2(f[0], f[1]); w.y = pk2(f[2], f[3]); w.z = pk2(f[4], f[5]); w.w = pk2(f[6], f[7]); return w; }
; DI float silu(float x) { return x / (1.f + __expf(-x)); }
; DI void phase_gla_post(const Params& p) {
;     ...
; #pragma unroll
;         for (int r = 0; r < 2; ++r) { ok[r] = row + r * nw < MTOK; rr[r] = ok[r] ? (size_t)(row + r * nw) : (size_t)row;
; #pragma unroll
;             for (int hd = 0; hd < 4; ++hd) { wo[r][hd] = *(const u32x4*)(y + rr[r] * DM + hd * 512 + lane * 8); wg[r][hd] = *(const u32x4*)(big + rr[r] * 6400 + 4096 + hd * 512 + lane * 8); } }
; #pragma unroll
;         for (int r = 0; r < 2; ++r)
; #pragma unroll
;             for (int hd = 0; hd < 4; ++hd) {
;                 float f[8], g[8]; unpack8(wo[r][hd], f); unpack8(wg[r][hd], g);
;                 float ss = 0.f;
; #pragma unroll
;                 for (int e = 0; e < 8; ++e) ss += f[e] * f[e];
;                 ss = wsum(ss); const float sc = rsqrtf(ss * (1.f / 512.f) + EPS);
; #pragma unroll
;                 for (int e = 0; e < 8; ++e) f[e] = f[e] * sc * og[e] * silu(g[e]);
;                 if (ok[r]) *(u32x4*)(y + rr[r] * DM + hd * 512 + lane * 8) = pack8(f);
;             }
	v_lshlrev_b32_e32 v48, 16, v32
	s_waitcnt lgkmcnt(0)
	v_add_f32_e32 v38, v38, v39
	v_and_b32_e32 v49, 0xffff0000, v32
	v_mul_f32_e32 v32, 0xbfb8aa3b, v48
	v_fmamk_f32 v46, v38, 0x3b000000, v106
	v_exp_f32_e32 v38, v32
	v_mul_f32_e32 v32, 0xbfb8aa3b, v49
	v_exp_f32_e32 v39, v32
	v_mul_f32_e32 v47, 0x4b800000, v46
	v_cmp_gt_f32_e32 vcc, s29, v46
	v_pk_add_f32 v[38:39], v[38:39], 1.0 op_sel_hi:[1,0]
	s_nop 0
	v_cndmask_b32_e32 v32, v46, v47, vcc
	v_rsq_f32_e32 v32, v32
	s_nop 0
	v_mul_f32_e32 v50, 0x45800000, v32
	v_cndmask_b32_e32 v32, v32, v50, vcc
	v_rcp_f32_e32 v46, v39
	s_nop 0
	v_mul_f32_e32 v39, v49, v46
	v_lshlrev_b32_e32 v51, 16, v33
	v_and_b32_e32 v33, 0xffff0000, v33
	v_mul_f32_e32 v46, 0xbfb8aa3b, v51
	v_mul_f32_e32 v47, 0xbfb8aa3b, v33
	v_exp_f32_e32 v46, v46
	v_exp_f32_e32 v47, v47
	v_rcp_f32_e32 v49, v38
	s_nop 0
	v_mul_f32_e32 v38, v48, v49
	v_pk_mul_f32 v[44:45], v[32:33], v[44:45] op_sel_hi:[0,1]
	v_pk_add_f32 v[46:47], v[46:47], 1.0 op_sel_hi:[1,0]
	v_pk_mul_f32 v[44:45], v[4:5], v[44:45]
	v_pk_mul_f32 v[38:39], v[38:39], v[44:45]
	v_lshlrev_b32_e32 v52, 16, v34
	v_and_b32_e32 v34, 0xffff0000, v34
	v_rcp_f32_e32 v44, v47
	s_nop 0
	v_mul_f32_e32 v45, v33, v44
	v_mul_f32_e32 v47, 0xbfb8aa3b, v52
	v_exp_f32_e32 v48, v47
	v_mul_f32_e32 v47, 0xbfb8aa3b, v34
	v_exp_f32_e32 v49, v47
	v_rcp_f32_e32 v33, v46
	s_nop 0
	v_mul_f32_e32 v44, v51, v33
	v_and_b32_e32 v50, 0xffff0000, v35
	v_pk_add_f32 v[46:47], v[48:49], 1.0 op_sel_hi:[1,0]
	s_nop 0
	v_pk_mul_f32 v[42:43], v[32:33], v[42:43] op_sel_hi:[0,1]
	v_pk_mul_f32 v[42:43], v[6:7], v[42:43]
	s_nop 0
	v_pk_mul_f32 v[42:43], v[44:45], v[42:43]
	v_rcp_f32_e32 v33, v47
	s_nop 0
	v_mul_f32_e32 v45, v34, v33
	v_lshlrev_b32_e32 v48, 16, v35
	v_mul_f32_e32 v34, 0xbfb8aa3b, v48
	v_mul_f32_e32 v35, 0xbfb8aa3b, v50
	v_exp_f32_e32 v34, v34
	v_exp_f32_e32 v35, v35
	v_rcp_f32_e32 v33, v46
	s_nop 0
	v_mul_f32_e32 v44, v52, v33
	v_pk_add_f32 v[34:35], v[34:35], 1.0 op_sel_hi:[1,0]
	s_nop 0
	v_pk_mul_f32 v[40:41], v[32:33], v[40:41] op_sel_hi:[0,1]
	v_pk_mul_f32 v[40:41], v[0:1], v[40:41]
	s_nop 0
	v_pk_mul_f32 v[40:41], v[44:45], v[40:41]
	v_rcp_f32_e32 v33, v35
	s_nop 0
	v_mul_f32_e32 v35, v50, v33
	v_rcp_f32_e32 v33, v34
	s_nop 0
	v_mul_f32_e32 v34, v48, v33
	v_pk_mul_f32 v[32:33], v[32:33], v[36:37] op_sel_hi:[0,1]
	v_pk_mul_f32 v[32:33], v[2:3], v[32:33]
	s_nop 0
	v_pk_mul_f32 v[36:37], v[34:35], v[32:33]
	v_cvt_pk_bf16_f32 v32, v38, v39
	v_cvt_pk_bf16_f32 v33, v42, v43
	v_cvt_pk_bf16_f32 v34, v40, v41
	v_cvt_pk_bf16_f32 v35, v36, v37
	global_store_dwordx4 v[72:73], v[32:35], off
.LBB0_659:
	s_or_b64 exec, exec, s[10:11]
	v_lshlrev_b32_e32 v36, 16, v28
	v_and_b32_e32 v37, 0xffff0000, v28
	s_waitcnt lgkmcnt(0)
	v_pk_mul_f32 v[38:39], v[36:37], v[36:37]
	v_lshlrev_b32_e32 v34, 16, v29
	v_and_b32_e32 v35, 0xffff0000, v29
	v_pk_mul_f32 v[40:41], v[34:35], v[34:35]
	v_add_f32_e32 v38, v38, v39
	v_lshlrev_b32_e32 v32, 16, v30
	v_and_b32_e32 v33, 0xffff0000, v30
	v_add_f32_e32 v38, v40, v38
	v_pk_mul_f32 v[42:43], v[32:33], v[32:33]
	v_add_f32_e32 v38, v41, v38
	v_lshlrev_b32_e32 v28, 16, v31
	v_and_b32_e32 v29, 0xffff0000, v31
	v_add_f32_e32 v38, v42, v38
	v_pk_mul_f32 v[30:31], v[28:29], v[28:29]
	v_add_f32_e32 v38, v43, v38
	v_add_f32_e32 v30, v30, v38
	v_add_f32_e32 v30, v31, v30
	ds_bpermute_b32 v31, v100, v30
	s_waitcnt lgkmcnt(0)
	v_add_f32_e32 v30, v30, v31
	ds_bpermute_b32 v31, v101, v30
	s_waitcnt lgkmcnt(0)
	v_add_f32_e32 v30, v30, v31
	ds_bpermute_b32 v31, v102, v30
	s_waitcnt lgkmcnt(0)
	v_add_f32_e32 v30, v30, v31
	ds_bpermute_b32 v31, v103, v30
	s_waitcnt lgkmcnt(0)
	v_add_f32_e32 v30, v30, v31
	ds_bpermute_b32 v31, v104, v30
	s_waitcnt lgkmcnt(0)
	v_add_f32_e32 v30, v30, v31
	ds_bpermute_b32 v31, v105, v30
	s_and_saveexec_b64 s[10:11], s[8:9]
	s_cbranch_execz .LBB0_661
	s_waitcnt vmcnt(8)
	v_lshlrev_b32_e32 v40, 16, v24
	s_waitcnt lgkmcnt(0)
	v_add_f32_e32 v30, v30, v31
	v_and_b32_e32 v41, 0xffff0000, v24
	v_mul_f32_e32 v24, 0xbfb8aa3b, v40
	v_fmamk_f32 v38, v30, 0x3b000000, v106
	v_exp_f32_e32 v30, v24
	v_mul_f32_e32 v24, 0xbfb8aa3b, v41
	v_exp_f32_e32 v31, v24
	v_mul_f32_e32 v39, 0x4b800000, v38
	v_cmp_gt_f32_e32 vcc, s29, v38
	v_pk_add_f32 v[30:31], v[30:31], 1.0 op_sel_hi:[1,0]
	s_nop 0
	v_cndmask_b32_e32 v24, v38, v39, vcc
	v_rsq_f32_e32 v24, v24
	s_nop 0
	v_mul_f32_e32 v42, 0x45800000, v24
	v_cndmask_b32_e32 v24, v24, v42, vcc
	v_rcp_f32_e32 v38, v31
	s_nop 0
	v_mul_f32_e32 v31, v41, v38
	v_lshlrev_b32_e32 v43, 16, v25
	v_and_b32_e32 v25, 0xffff0000, v25
	v_mul_f32_e32 v38, 0xbfb8aa3b, v43
	v_mul_f32_e32 v39, 0xbfb8aa3b, v25
	v_exp_f32_e32 v38, v38
	v_exp_f32_e32 v39, v39
	v_rcp_f32_e32 v41, v30
	s_nop 0
	v_mul_f32_e32 v30, v40, v41
	v_pk_mul_f32 v[36:37], v[24:25], v[36:37] op_sel_hi:[0,1]
	v_pk_add_f32 v[38:39], v[38:39], 1.0 op_sel_hi:[1,0]
	v_pk_mul_f32 v[36:37], v[4:5], v[36:37]
	v_pk_mul_f32 v[30:31], v[30:31], v[36:37]
	v_lshlrev_b32_e32 v44, 16, v26
	v_and_b32_e32 v26, 0xffff0000, v26
	v_rcp_f32_e32 v36, v39
	s_nop 0
	v_mul_f32_e32 v37, v25, v36
	v_mul_f32_e32 v39, 0xbfb8aa3b, v44
	v_exp_f32_e32 v40, v39
	v_mul_f32_e32 v39, 0xbfb8aa3b, v26
	v_exp_f32_e32 v41, v39
	v_rcp_f32_e32 v25, v38
	s_nop 0
	v_mul_f32_e32 v36, v43, v25
	v_and_b32_e32 v42, 0xffff0000, v27
	v_pk_add_f32 v[38:39], v[40:41], 1.0 op_sel_hi:[1,0]
	s_nop 0
	v_pk_mul_f32 v[34:35], v[24:25], v[34:35] op_sel_hi:[0,1]
	v_pk_mul_f32 v[34:35], v[6:7], v[34:35]
	s_nop 0
	v_pk_mul_f32 v[34:35], v[36:37], v[34:35]
	v_rcp_f32_e32 v25, v39
	s_nop 0
	v_mul_f32_e32 v37, v26, v25
	v_lshlrev_b32_e32 v40, 16, v27
	v_mul_f32_e32 v26, 0xbfb8aa3b, v40
	v_mul_f32_e32 v27, 0xbfb8aa3b, v42
	v_exp_f32_e32 v26, v26
	v_exp_f32_e32 v27, v27
	v_rcp_f32_e32 v25, v38
	s_nop 0
	v_mul_f32_e32 v36, v44, v25
	v_pk_add_f32 v[26:27], v[26:27], 1.0 op_sel_hi:[1,0]
	s_nop 0
	v_pk_mul_f32 v[32:33], v[24:25], v[32:33] op_sel_hi:[0,1]
	v_pk_mul_f32 v[32:33], v[0:1], v[32:33]
	s_nop 0
	v_pk_mul_f32 v[32:33], v[36:37], v[32:33]
	v_rcp_f32_e32 v25, v27
	s_nop 0
	v_mul_f32_e32 v27, v42, v25
	v_rcp_f32_e32 v25, v26
	s_nop 0
	v_mul_f32_e32 v26, v40, v25
	v_pk_mul_f32 v[24:25], v[24:25], v[28:29] op_sel_hi:[0,1]
	v_pk_mul_f32 v[24:25], v[2:3], v[24:25]
	s_nop 0
	v_pk_mul_f32 v[28:29], v[26:27], v[24:25]
	v_cvt_pk_bf16_f32 v24, v30, v31
	v_cvt_pk_bf16_f32 v25, v34, v35
	v_cvt_pk_bf16_f32 v26, v32, v33
	v_cvt_pk_bf16_f32 v27, v28, v29
	global_store_dwordx4 v[72:73], v[24:27], off offset:1024
; DI u32x4 pack8(const float (&f)[8]) { u32x4 w; w.x = pk2(f[0], f[1]); w.y = pk2(f[2], f[3]); w.z = pk2(f[4], f[5]); w.w = pk2(f[6], f[7]); return w; }
; DI float silu(float x) { return x / (1.f + __expf(-x)); }
; DI void phase_gla_post(const Params& p) {
;     ...
; #pragma unroll
;         for (int r = 0; r < 2; ++r) { ok[r] = row + r * nw < MTOK; rr[r] = ok[r] ? (size_t)(row + r * nw) : (size_t)row;
; #pragma unroll
;             for (int hd = 0; hd < 4; ++hd) { wo[r][hd] = *(const u32x4*)(y + rr[r] * DM + hd * 512 + lane * 8); wg[r][hd] = *(const u32x4*)(big + rr[r] * 6400 + 4096 + hd * 512 + lane * 8); } }
; #pragma unroll
;         for (int r = 0; r < 2; ++r)
; #pragma unroll
;             for (int hd = 0; hd < 4; ++hd) {
;                 float f[8], g[8]; unpack8(wo[r][hd], f); unpack8(wg[r][hd], g);
;                 float ss = 0.f;
; #pragma unroll
;                 for (int e = 0; e < 8; ++e) ss += f[e] * f[e];
;                 ss = wsum(ss); const float sc = rsqrtf(ss * (1.f / 512.f) + EPS);
; #pragma unroll
;                 for (int e = 0; e < 8; ++e) f[e] = f[e] * sc * og[e] * silu(g[e]);
;                 if (ok[r]) *(u32x4*)(y + rr[r] * DM + hd * 512 + lane * 8) = pack8(f);
;             }
.LBB0_661:
	s_or_b64 exec, exec, s[10:11]
	s_waitcnt vmcnt(7)
	v_lshlrev_b32_e32 v28, 16, v20
	v_and_b32_e32 v29, 0xffff0000, v20
	s_waitcnt lgkmcnt(0)
	v_pk_mul_f32 v[30:31], v[28:29], v[28:29]
	v_lshlrev_b32_e32 v26, 16, v21
	v_and_b32_e32 v27, 0xffff0000, v21
	v_pk_mul_f32 v[32:33], v[26:27], v[26:27]
	v_add_f32_e32 v30, v30, v31
	v_lshlrev_b32_e32 v24, 16, v22
	v_and_b32_e32 v25, 0xffff0000, v22
	v_add_f32_e32 v30, v32, v30
	v_pk_mul_f32 v[34:35], v[24:25], v[24:25]
	v_add_f32_e32 v30, v33, v30
	v_lshlrev_b32_e32 v20, 16, v23
	v_and_b32_e32 v21, 0xffff0000, v23
	v_add_f32_e32 v30, v34, v30
	v_pk_mul_f32 v[22:23], v[20:21], v[20:21]
	v_add_f32_e32 v30, v35, v30
	v_add_f32_e32 v22, v22, v30
	v_add_f32_e32 v22, v23, v22
	ds_bpermute_b32 v23, v100, v22
	s_waitcnt lgkmcnt(0)
	v_add_f32_e32 v22, v22, v23
	ds_bpermute_b32 v23, v101, v22
	s_waitcnt lgkmcnt(0)
	v_add_f32_e32 v22, v22, v23
	ds_bpermute_b32 v23, v102, v22
	s_waitcnt lgkmcnt(0)
	v_add_f32_e32 v22, v22, v23
	ds_bpermute_b32 v23, v103, v22
	s_waitcnt lgkmcnt(0)
	v_add_f32_e32 v22, v22, v23
	ds_bpermute_b32 v23, v104, v22
	s_waitcnt lgkmcnt(0)
	v_add_f32_e32 v22, v22, v23
	ds_bpermute_b32 v23, v105, v22
	s_and_saveexec_b64 s[10:11], s[8:9]
	s_cbranch_execz .LBB0_663
	s_waitcnt vmcnt(5)
	v_lshlrev_b32_e32 v32, 16, v16
	s_waitcnt lgkmcnt(0)
	v_add_f32_e32 v22, v22, v23
	v_and_b32_e32 v33, 0xffff0000, v16
	v_mul_f32_e32 v16, 0xbfb8aa3b, v32
	v_fmamk_f32 v30, v22, 0x3b000000, v106
	v_exp_f32_e32 v22, v16
	v_mul_f32_e32 v16, 0xbfb8aa3b, v33
	v_exp_f32_e32 v23, v16
	v_mul_f32_e32 v31, 0x4b800000, v30
	v_cmp_gt_f32_e32 vcc, s29, v30
	v_pk_add_f32 v[22:23], v[22:23], 1.0 op_sel_hi:[1,0]
	s_nop 0
	v_cndmask_b32_e32 v16, v30, v31, vcc
	v_rsq_f32_e32 v16, v16
	s_nop 0
	v_mul_f32_e32 v34, 0x45800000, v16
	v_cndmask_b32_e32 v16, v16, v34, vcc
	v_rcp_f32_e32 v30, v23
	s_nop 0
	v_mul_f32_e32 v23, v33, v30
	v_lshlrev_b32_e32 v35, 16, v17
	v_and_b32_e32 v17, 0xffff0000, v17
	v_mul_f32_e32 v30, 0xbfb8aa3b, v35
	v_mul_f32_e32 v31, 0xbfb8aa3b, v17
	v_exp_f32_e32 v30, v30
	v_exp_f32_e32 v31, v31
	v_rcp_f32_e32 v33, v22
	s_nop 0
	v_mul_f32_e32 v22, v32, v33
	v_pk_mul_f32 v[28:29], v[16:17], v[28:29] op_sel_hi:[0,1]
	v_pk_add_f32 v[30:31], v[30:31], 1.0 op_sel_hi:[1,0]
	v_pk_mul_f32 v[28:29], v[4:5], v[28:29]
	v_pk_mul_f32 v[22:23], v[22:23], v[28:29]
	v_lshlrev_b32_e32 v36, 16, v18
	v_and_b32_e32 v18, 0xffff0000, v18
	v_rcp_f32_e32 v28, v31
	s_nop 0
	v_mul_f32_e32 v29, v17, v28
	v_mul_f32_e32 v31, 0xbfb8aa3b, v36
	v_exp_f32_e32 v32, v31
	v_mul_f32_e32 v31, 0xbfb8aa3b, v18
	v_exp_f32_e32 v33, v31
	v_rcp_f32_e32 v17, v30
	s_nop 0
	v_mul_f32_e32 v28, v35, v17
	v_and_b32_e32 v34, 0xffff0000, v19
	v_pk_add_f32 v[30:31], v[32:33], 1.0 op_sel_hi:[1,0]
	s_nop 0
	v_pk_mul_f32 v[26:27], v[16:17], v[26:27] op_sel_hi:[0,1]
	v_pk_mul_f32 v[26:27], v[6:7], v[26:27]
	s_nop 0
	v_pk_mul_f32 v[26:27], v[28:29], v[26:27]
	v_rcp_f32_e32 v17, v31
	s_nop 0
	v_mul_f32_e32 v29, v18, v17
	v_lshlrev_b32_e32 v32, 16, v19
	v_mul_f32_e32 v18, 0xbfb8aa3b, v32
	v_mul_f32_e32 v19, 0xbfb8aa3b, v34
	v_exp_f32_e32 v18, v18
	v_exp_f32_e32 v19, v19
	v_rcp_f32_e32 v17, v30
	s_nop 0
	v_mul_f32_e32 v28, v36, v17
	v_pk_add_f32 v[18:19], v[18:19], 1.0 op_sel_hi:[1,0]
	s_nop 0
	v_pk_mul_f32 v[24:25], v[16:17], v[24:25] op_sel_hi:[0,1]
	v_pk_mul_f32 v[24:25], v[0:1], v[24:25]
	s_nop 0
	v_pk_mul_f32 v[24:25], v[28:29], v[24:25]
	v_rcp_f32_e32 v17, v19
	s_nop 0
	v_mul_f32_e32 v19, v34, v17
	v_rcp_f32_e32 v17, v18
	s_nop 0
	v_mul_f32_e32 v18, v32, v17
	v_pk_mul_f32 v[16:17], v[16:17], v[20:21] op_sel_hi:[0,1]
	v_pk_mul_f32 v[16:17], v[2:3], v[16:17]
	s_nop 0
	v_pk_mul_f32 v[20:21], v[18:19], v[16:17]
	v_cvt_pk_bf16_f32 v16, v22, v23
	v_cvt_pk_bf16_f32 v17, v26, v27
	v_cvt_pk_bf16_f32 v18, v24, v25
	v_cvt_pk_bf16_f32 v19, v20, v21
	global_store_dwordx4 v[72:73], v[16:19], off offset:2048
; DI u32x4 pack8(const float (&f)[8]) { u32x4 w; w.x = pk2(f[0], f[1]); w.y = pk2(f[2], f[3]); w.z = pk2(f[4], f[5]); w.w = pk2(f[6], f[7]); return w; }
; DI float silu(float x) { return x / (1.f + __expf(-x)); }
; DI void phase_gla_post(const Params& p) {
;     ...
; #pragma unroll
;         for (int r = 0; r < 2; ++r) { ok[r] = row + r * nw < MTOK; rr[r] = ok[r] ? (size_t)(row + r * nw) : (size_t)row;
; #pragma unroll
;             for (int hd = 0; hd < 4; ++hd) { wo[r][hd] = *(const u32x4*)(y + rr[r] * DM + hd * 512 + lane * 8); wg[r][hd] = *(const u32x4*)(big + rr[r] * 6400 + 4096 + hd * 512 + lane * 8); } }
; #pragma unroll
;         for (int r = 0; r < 2; ++r)
; #pragma unroll
;             for (int hd = 0; hd < 4; ++hd) {
;                 float f[8], g[8]; unpack8(wo[r][hd], f); unpack8(wg[r][hd], g);
;                 float ss = 0.f;
; #pragma unroll
;                 for (int e = 0; e < 8; ++e) ss += f[e] * f[e];
;                 ss = wsum(ss); const float sc = rsqrtf(ss * (1.f / 512.f) + EPS);
; #pragma unroll
;                 for (int e = 0; e < 8; ++e) f[e] = f[e] * sc * og[e] * silu(g[e]);
;                 if (ok[r]) *(u32x4*)(y + rr[r] * DM + hd * 512 + lane * 8) = pack8(f);
;             }
.LBB0_663:
	s_or_b64 exec, exec, s[10:11]
	s_waitcnt vmcnt(6)
	v_lshlrev_b32_e32 v20, 16, v12
	v_and_b32_e32 v21, 0xffff0000, v12
	s_waitcnt lgkmcnt(0)
	v_pk_mul_f32 v[22:23], v[20:21], v[20:21]
	s_waitcnt vmcnt(5)
	v_lshlrev_b32_e32 v18, 16, v13
	v_and_b32_e32 v19, 0xffff0000, v13
	v_pk_mul_f32 v[24:25], v[18:19], v[18:19]
	v_add_f32_e32 v22, v22, v23
	v_lshlrev_b32_e32 v16, 16, v14
	v_and_b32_e32 v17, 0xffff0000, v14
	v_add_f32_e32 v22, v24, v22
	v_pk_mul_f32 v[26:27], v[16:17], v[16:17]
	v_add_f32_e32 v22, v25, v22
	v_lshlrev_b32_e32 v12, 16, v15
	v_and_b32_e32 v13, 0xffff0000, v15
	v_add_f32_e32 v22, v26, v22
	v_pk_mul_f32 v[14:15], v[12:13], v[12:13]
	v_add_f32_e32 v22, v27, v22
	v_add_f32_e32 v14, v14, v22
	v_add_f32_e32 v14, v15, v14
	ds_bpermute_b32 v15, v100, v14
	s_waitcnt lgkmcnt(0)
	v_add_f32_e32 v14, v14, v15
	ds_bpermute_b32 v15, v101, v14
	s_waitcnt lgkmcnt(0)
	v_add_f32_e32 v14, v14, v15
	ds_bpermute_b32 v15, v102, v14
	s_waitcnt lgkmcnt(0)
	v_add_f32_e32 v14, v14, v15
	ds_bpermute_b32 v15, v103, v14
	s_waitcnt lgkmcnt(0)
	v_add_f32_e32 v14, v14, v15
	ds_bpermute_b32 v15, v104, v14
	s_waitcnt lgkmcnt(0)
	v_add_f32_e32 v14, v14, v15
	ds_bpermute_b32 v15, v105, v14
	s_and_saveexec_b64 s[10:11], s[8:9]
	s_cbranch_execz .LBB0_656
	s_waitcnt vmcnt(4)
	v_lshlrev_b32_e32 v24, 16, v8
	s_waitcnt lgkmcnt(0)
	v_add_f32_e32 v14, v14, v15
	v_and_b32_e32 v25, 0xffff0000, v8
	v_mul_f32_e32 v8, 0xbfb8aa3b, v24
	v_fmamk_f32 v22, v14, 0x3b000000, v106
	v_exp_f32_e32 v14, v8
	v_mul_f32_e32 v8, 0xbfb8aa3b, v25
	v_exp_f32_e32 v15, v8
	v_mul_f32_e32 v23, 0x4b800000, v22
	v_cmp_gt_f32_e32 vcc, s29, v22
	v_pk_add_f32 v[14:15], v[14:15], 1.0 op_sel_hi:[1,0]
	s_nop 0
	v_cndmask_b32_e32 v8, v22, v23, vcc
	v_rsq_f32_e32 v8, v8
	s_nop 0
	v_mul_f32_e32 v26, 0x45800000, v8
	v_cndmask_b32_e32 v8, v8, v26, vcc
	v_rcp_f32_e32 v22, v15
	s_nop 0
	v_mul_f32_e32 v15, v25, v22
	v_lshlrev_b32_e32 v27, 16, v9
	v_and_b32_e32 v9, 0xffff0000, v9
	v_mul_f32_e32 v22, 0xbfb8aa3b, v27
	v_mul_f32_e32 v23, 0xbfb8aa3b, v9
	v_exp_f32_e32 v22, v22
	v_exp_f32_e32 v23, v23
	v_rcp_f32_e32 v25, v14
	s_nop 0
	v_mul_f32_e32 v14, v24, v25
	v_pk_mul_f32 v[20:21], v[8:9], v[20:21] op_sel_hi:[0,1]
	v_pk_add_f32 v[22:23], v[22:23], 1.0 op_sel_hi:[1,0]
	v_pk_mul_f32 v[20:21], v[4:5], v[20:21]
	v_pk_mul_f32 v[14:15], v[14:15], v[20:21]
	v_lshlrev_b32_e32 v28, 16, v10
	v_and_b32_e32 v10, 0xffff0000, v10
	v_rcp_f32_e32 v20, v23
	s_nop 0
	v_mul_f32_e32 v21, v9, v20
	v_mul_f32_e32 v23, 0xbfb8aa3b, v28
	v_exp_f32_e32 v24, v23
	v_mul_f32_e32 v23, 0xbfb8aa3b, v10
	v_exp_f32_e32 v25, v23
	v_rcp_f32_e32 v9, v22
	s_nop 0
	v_mul_f32_e32 v20, v27, v9
	v_and_b32_e32 v26, 0xffff0000, v11
	v_pk_add_f32 v[22:23], v[24:25], 1.0 op_sel_hi:[1,0]
	s_nop 0
	v_pk_mul_f32 v[18:19], v[8:9], v[18:19] op_sel_hi:[0,1]
	v_pk_mul_f32 v[18:19], v[6:7], v[18:19]
	s_nop 0
	v_pk_mul_f32 v[18:19], v[20:21], v[18:19]
	v_rcp_f32_e32 v9, v23
	s_nop 0
	v_mul_f32_e32 v21, v10, v9
	v_lshlrev_b32_e32 v24, 16, v11
	v_mul_f32_e32 v10, 0xbfb8aa3b, v24
	v_mul_f32_e32 v11, 0xbfb8aa3b, v26
	v_exp_f32_e32 v10, v10
	v_exp_f32_e32 v11, v11
	v_rcp_f32_e32 v9, v22
	s_nop 0
	v_mul_f32_e32 v20, v28, v9
	v_pk_add_f32 v[10:11], v[10:11], 1.0 op_sel_hi:[1,0]
	s_nop 0
	v_pk_mul_f32 v[16:17], v[8:9], v[16:17] op_sel_hi:[0,1]
	v_pk_mul_f32 v[16:17], v[0:1], v[16:17]
	s_nop 0
	v_pk_mul_f32 v[16:17], v[20:21], v[16:17]
	v_rcp_f32_e32 v9, v11
	s_nop 0
	v_mul_f32_e32 v11, v26, v9
	v_rcp_f32_e32 v9, v10
	s_nop 0
	v_mul_f32_e32 v10, v24, v9
	v_pk_mul_f32 v[8:9], v[8:9], v[12:13] op_sel_hi:[0,1]
	v_pk_mul_f32 v[8:9], v[2:3], v[8:9]
	s_nop 0
	v_pk_mul_f32 v[12:13], v[10:11], v[8:9]
	v_cvt_pk_bf16_f32 v8, v14, v15
	v_cvt_pk_bf16_f32 v9, v18, v19
	v_cvt_pk_bf16_f32 v10, v16, v17
	v_cvt_pk_bf16_f32 v11, v12, v13
	global_store_dwordx4 v[72:73], v[8:11], off offset:3072
	s_branch .LBB0_656

; DI unsigned pk2(float a, float b) { f32x2 v = {a, b}; bf16v2_t r = __builtin_convertvector(v, bf16v2_t); return __builtin_bit_cast(unsigned, r); }
; DI float sigm(float x) { return 1.f / (1.f + __expf(-x)); }
;     DI void operator()(const Acc& acc, const Unit& u, int wr, int wc, int fr, int fq, const float (&pre)[8]) const {
;     ...
;         for (int n = 0; n < 2; ++n) {
;             const f32x4 br = *(const f32x4*)(brg + f0 + 4 * n), bi = *(const f32x4*)(big + f0 + 4 * n), sp = *(const f32x4*)(sp8t + f0 + 4 * n);
; #pragma unroll
;             for (int ai = 0; ai < 2; ++ai)
; #pragma unroll
;                 for (int m = 0; m < 4; ++m) { const size_t o = (size_t)(row0 + ai * HALF + m * 16) * DM + f0 + 4 * n;
;                     const u32x2 xw = *(const u32x2*)(xc + o);
;                     const float xv[4] = {__uint_as_float(xw.x << 16), __uint_as_float(xw.x & 0xffff0000u), __uint_as_float(xw.y << 16), __uint_as_float(xw.y & 0xffff0000u)};
;                     u32x4 w;
; #pragma unroll
;                     for (int e = 0; e < 4; ++e) { const float r = sigm(acc[ai][0][m][n][e] + br[e]), ig = sigm(acc[ai][1][m][n][e] + bi[e]);
;                         const float la = -sp[e] * r, uu = -2.f * la;
;                         const float om = uu * (1.f - uu * 0.5f * (1.f - uu * (1.f / 3.f) * (1.f - uu * 0.25f * (1.f - uu * 0.2f * (1.f - uu * (1.f / 6.f))))));
;                         w[e] = pk2(la, sqrtf(fmaxf(om, 0.f)) * ig * xv[e]); }
;                     *(u32x4*)(ax + o) = w; __builtin_amdgcn_sched_barrier(0); }
.LBB0_944:
	v_lshl_or_b32 v160, s84, 7, v176
	v_ashrrev_i32_e32 v161, 31, v160
	v_lshlrev_b64 v[88:89], 2, v[160:161]
	s_waitcnt lgkmcnt(0)
	v_lshl_add_u64 v[162:163], s[28:29], 0, v[88:89]
	global_load_dwordx4 v[96:99], v[162:163], off
	v_lshl_add_u64 v[164:165], s[30:31], 0, v[88:89]
	global_load_dwordx4 v[92:95], v[164:165], off
	v_lshl_add_u32 v170, s12, 8, v174
	v_ashrrev_i32_e32 v171, 31, v170
	v_lshlrev_b64 v[166:167], 11, v[170:171]
	v_lshl_add_u64 v[172:173], v[166:167], 0, v[160:161]
	v_lshl_add_u64 v[90:91], v[172:173], 1, s[16:17]
	flat_load_dwordx2 v[184:185], v[90:91]
	v_lshl_add_u64 v[168:169], s[34:35], 0, v[88:89]
	flat_load_dwordx4 v[88:91], v[168:169]
	s_waitcnt vmcnt(0)
	v_add_f32_e32 v136, v136, v96
	v_mul_f32_e32 v136, 0xbfb8aa3b, v136
	v_add_f32_e32 v133, v133, v93
	v_add_f32_e32 v132, v132, v92
	v_mul_f32_e32 v133, 0xbfb8aa3b, v133
	v_exp_f32_e32 v136, v136
	v_add_f32_e32 v137, v137, v97
	v_mul_f32_e32 v132, 0xbfb8aa3b, v132
	v_exp_f32_e32 v133, v133
	v_mul_f32_e32 v137, 0xbfb8aa3b, v137
	v_exp_f32_e32 v132, v132
	v_exp_f32_e32 v137, v137
	v_add_f32_e32 v136, 1.0, v136
	v_add_f32_e32 v190, 1.0, v133
	v_add_f32_e32 v132, 1.0, v132
	v_add_f32_e32 v137, 1.0, v137
	v_div_scale_f32 v159, s[10:11], v132, v132, 1.0
	s_waitcnt lgkmcnt(0)
	v_lshlrev_b32_e32 v188, 16, v185
	v_and_b32_e32 v189, 0xffff0000, v185
	v_div_scale_f32 v185, s[10:11], v137, v137, 1.0
	v_rcp_f32_e32 v193, v159
	v_rcp_f32_e32 v194, v185
	v_fma_f32 v197, -v159, v193, 1.0
	v_lshlrev_b32_e32 v171, 16, v184
	v_and_b32_e32 v183, 0xffff0000, v184
	v_div_scale_f32 v184, s[12:13], 1.0, v132, 1.0
	v_fma_f32 v198, -v185, v194, 1.0
	v_fmac_f32_e32 v193, v197, v193
	v_div_scale_f32 v186, s[14:15], 1.0, v137, 1.0
	v_div_scale_f32 v187, s[10:11], v190, v190, 1.0
	v_fmac_f32_e32 v194, v198, v194
	v_mul_f32_e32 v197, v184, v193
	v_rcp_f32_e32 v195, v187
	v_mul_f32_e32 v198, v186, v194
	v_fma_f32 v201, -v159, v197, v184
	v_fma_f32 v202, -v185, v198, v186
	v_fmac_f32_e32 v197, v201, v193
	v_fmac_f32_e32 v198, v202, v194
	v_fma_f32 v157, -v159, v197, v184
	v_rcp_f32_e32 v133, v136
	s_mov_b64 vcc, s[12:13]
	v_fma_f32 v159, -v185, v198, v186
	v_div_fmas_f32 v136, v157, v193, v197
	v_mul_f32_e64 v193, v133, -v88
	s_mov_b64 vcc, s[14:15]
	v_fma_f32 v199, -v187, v195, 1.0
	v_div_fixup_f32 v192, v136, v132, 1.0
	v_div_fmas_f32 v133, v159, v194, v198
	v_mul_f32_e32 v132, -2.0, v193
	v_div_scale_f32 v191, s[10:11], 1.0, v190, 1.0
	v_fmac_f32_e32 v195, v199, v195
	v_div_fixup_f32 v136, v133, v137, 1.0
	v_mul_f32_e32 v133, 0x3e4ccccd, v132
	v_fma_f32 v157, v132, s81, 1.0
	v_mul_f32_e32 v199, v191, v195
	v_mul_f32_e64 v194, v136, -v89
	v_pk_mul_f32 v[136:137], v[132:133], v[156:157]
	v_fma_f32 v203, -v187, v199, v191
	v_mul_f32_e32 v159, 0x3eaaaaab, v132
	v_mul_f32_e32 v184, -2.0, v194
	v_sub_f32_e32 v137, 1.0, v137
	v_fmac_f32_e32 v199, v203, v195
	v_mov_b32_e32 v133, v159
	v_mul_f32_e32 v186, 0x3eaaaaab, v184
	v_mul_f32_e32 v185, 0x3e4ccccd, v184
	v_fma_f32 v157, v184, s81, 1.0
	v_fma_f32 v159, -v136, v137, 1.0
	v_fma_f32 v191, -v187, v199, v191
	v_pk_mul_f32 v[136:137], v[184:185], v[156:157]
	v_mov_b32_e32 v185, v186
	v_pk_mul_f32 v[186:187], v[132:133], v[158:159]
	v_sub_f32_e32 v137, 1.0, v137
	v_sub_f32_e32 v133, 1.0, v187
	v_fma_f32 v133, -v186, v133, 1.0
	v_mul_f32_e32 v132, v132, v133
	v_max_f32_e32 v132, 0, v132
	v_mul_f32_e32 v133, 0x4f800000, v132
	v_cmp_gt_f32_e32 vcc, s82, v132
	v_fma_f32 v159, -v136, v137, 1.0
	v_pk_mul_f32 v[136:137], v[184:185], v[158:159]
	v_cndmask_b32_e32 v132, v132, v133, vcc
	v_sqrt_f32_e32 v133, v132
	v_add_f32_e32 v138, v138, v98
	v_mul_f32_e32 v138, 0xbfb8aa3b, v138
	v_exp_f32_e32 v138, v138
	v_add_u32_e32 v157, -1, v133
	v_add_u32_e32 v159, 1, v133
	v_fma_f32 v185, -v157, v133, v132
	v_fma_f32 v186, -v159, v133, v132
	v_cmp_ge_f32_e64 s[12:13], 0, v185
	v_add_f32_e32 v134, v134, v94
	v_mul_f32_e32 v134, 0xbfb8aa3b, v134
	v_cndmask_b32_e64 v133, v133, v157, s[12:13]
	v_cmp_lt_f32_e64 s[12:13], 0, v186
	v_exp_f32_e32 v134, v134
	v_add_f32_e32 v139, v139, v99
	v_cndmask_b32_e64 v133, v133, v159, s[12:13]
	v_mul_f32_e32 v157, 0x37800000, v133
	v_cndmask_b32_e32 v133, v133, v157, vcc
	v_cmp_class_f32_e32 vcc, v132, v182
	v_add_f32_e32 v134, 1.0, v134
	v_mul_f32_e32 v139, 0xbfb8aa3b, v139
	v_cndmask_b32_e32 v132, v133, v132, vcc
	v_sub_f32_e32 v133, 1.0, v137
	v_fma_f32 v133, -v136, v133, 1.0
	v_mul_f32_e32 v133, v184, v133
	v_max_f32_e32 v133, 0, v133
	v_mul_f32_e32 v136, 0x4f800000, v133
	v_cmp_gt_f32_e64 s[12:13], s82, v133
	s_mov_b64 vcc, s[10:11]
	v_div_fmas_f32 v137, v191, v195, v199
	v_cndmask_b32_e64 v133, v133, v136, s[12:13]
	v_sqrt_f32_e32 v136, v133
	v_div_fixup_f32 v137, v137, v190, 1.0
	v_mul_f32_e32 v132, v192, v132
	v_mul_f32_e32 v132, v132, v171
	v_add_u32_e32 v157, -1, v136
	v_fma_f32 v159, -v157, v136, v133
	v_cmp_ge_f32_e32 vcc, 0, v159
	v_add_u32_e32 v159, 1, v136
	v_exp_f32_e32 v139, v139
	v_cndmask_b32_e32 v157, v136, v157, vcc
	v_fma_f32 v136, -v159, v136, v133
	v_cmp_lt_f32_e32 vcc, 0, v136
	v_add_f32_e32 v135, v135, v95
	v_mul_f32_e32 v135, 0xbfb8aa3b, v135
	v_cndmask_b32_e32 v136, v157, v159, vcc
	v_mul_f32_e32 v157, 0x37800000, v136
	v_cndmask_b32_e64 v136, v136, v157, s[12:13]
	v_cmp_class_f32_e32 vcc, v133, v182
	v_exp_f32_e32 v135, v135
	v_cvt_pk_bf16_f32 v132, v193, v132
	v_cndmask_b32_e32 v133, v136, v133, vcc
	v_add_f32_e32 v136, 1.0, v138
	v_mul_f32_e32 v133, v137, v133
	v_mul_f32_e32 v133, v133, v183
	v_add_f32_e32 v135, 1.0, v135
	v_rcp_f32_e32 v136, v136
	s_nop 0
	v_mul_f32_e64 v186, v136, -v90
	v_mul_f32_e32 v136, -2.0, v186
	v_mul_f32_e32 v137, 0x3e4ccccd, v136
	v_fma_f32 v157, v136, s81, 1.0
; DI unsigned pk2(float a, float b) { f32x2 v = {a, b}; bf16v2_t r = __builtin_convertvector(v, bf16v2_t); return __builtin_bit_cast(unsigned, r); }
; DI float sigm(float x) { return 1.f / (1.f + __expf(-x)); }
;     DI void operator()(const Acc& acc, const Unit& u, int wr, int wc, int fr, int fq, const float (&pre)[8]) const {
;     ...
;         for (int n = 0; n < 2; ++n) {
;             const f32x4 br = *(const f32x4*)(brg + f0 + 4 * n), bi = *(const f32x4*)(big + f0 + 4 * n), sp = *(const f32x4*)(sp8t + f0 + 4 * n);
; #pragma unroll
;             for (int ai = 0; ai < 2; ++ai)
; #pragma unroll
;                 for (int m = 0; m < 4; ++m) { const size_t o = (size_t)(row0 + ai * HALF + m * 16) * DM + f0 + 4 * n;
;                     const u32x2 xw = *(const u32x2*)(xc + o);
;                     const float xv[4] = {__uint_as_float(xw.x << 16), __uint_as_float(xw.x & 0xffff0000u), __uint_as_float(xw.y << 16), __uint_as_float(xw.y & 0xffff0000u)};
;                     u32x4 w;
; #pragma unroll
;                     for (int e = 0; e < 4; ++e) { const float r = sigm(acc[ai][0][m][n][e] + br[e]), ig = sigm(acc[ai][1][m][n][e] + bi[e]);
;                         const float la = -sp[e] * r, uu = -2.f * la;
;                         const float om = uu * (1.f - uu * 0.5f * (1.f - uu * (1.f / 3.f) * (1.f - uu * 0.25f * (1.f - uu * 0.2f * (1.f - uu * (1.f / 6.f))))));
;                         w[e] = pk2(la, sqrtf(fmaxf(om, 0.f)) * ig * xv[e]); }
;                     *(u32x4*)(ax + o) = w; __builtin_amdgcn_sched_barrier(0); }
	v_pk_mul_f32 v[184:185], v[136:137], v[156:157]
	v_mul_f32_e32 v187, 0x3eaaaaab, v136
	v_sub_f32_e32 v137, 1.0, v185
	v_fma_f32 v159, -v184, v137, 1.0
	v_mov_b32_e32 v137, v187
	v_pk_mul_f32 v[184:185], v[136:137], v[158:159]
	v_sub_f32_e32 v137, 1.0, v185
	v_fma_f32 v137, -v184, v137, 1.0
	v_mul_f32_e32 v136, v136, v137
	v_max_f32_e32 v136, 0, v136
	v_mul_f32_e32 v137, 0x4f800000, v136
	v_cmp_gt_f32_e64 s[10:11], s82, v136
	v_rcp_f32_e32 v134, v134
	v_cvt_pk_bf16_f32 v133, v194, v133
	v_cndmask_b32_e64 v136, v136, v137, s[10:11]
	v_sqrt_f32_e32 v137, v136
	s_nop 0
	v_add_u32_e32 v138, -1, v137
	v_fma_f32 v157, -v138, v137, v136
	v_cmp_ge_f32_e32 vcc, 0, v157
	v_add_u32_e32 v157, 1, v137
	s_nop 0
	v_cndmask_b32_e32 v138, v137, v138, vcc
	v_fma_f32 v137, -v157, v137, v136
	v_cmp_lt_f32_e32 vcc, 0, v137
	s_nop 1
	v_cndmask_b32_e32 v137, v138, v157, vcc
	v_mul_f32_e32 v138, 0x37800000, v137
	v_cndmask_b32_e64 v137, v137, v138, s[10:11]
	v_cmp_class_f32_e32 vcc, v136, v182
	s_nop 1
	v_cndmask_b32_e32 v136, v137, v136, vcc
	v_add_f32_e32 v137, 1.0, v139
	v_mul_f32_e32 v134, v134, v136
	v_mul_f32_e32 v134, v134, v188
	v_cvt_pk_bf16_f32 v134, v186, v134
	v_rcp_f32_e32 v136, v137
	s_nop 0
	v_mul_f32_e64 v185, v136, -v91
	v_mul_f32_e32 v136, -2.0, v185
	v_mul_f32_e32 v137, 0x3e4ccccd, v136
	v_fma_f32 v157, v136, s81, 1.0
	v_pk_mul_f32 v[138:139], v[136:137], v[156:157]
	v_mul_f32_e32 v186, 0x3eaaaaab, v136
	v_sub_f32_e32 v137, 1.0, v139
	v_fma_f32 v159, -v138, v137, 1.0
	v_mov_b32_e32 v137, v186
	v_pk_mul_f32 v[138:139], v[136:137], v[158:159]
	s_nop 0
	v_sub_f32_e32 v137, 1.0, v139
	v_fma_f32 v137, -v138, v137, 1.0
	v_mul_f32_e32 v136, v136, v137
	v_max_f32_e32 v136, 0, v136
	v_mul_f32_e32 v137, 0x4f800000, v136
	v_cmp_gt_f32_e64 s[10:11], s82, v136
	v_rcp_f32_e32 v135, v135
	s_nop 0
	v_cndmask_b32_e64 v136, v136, v137, s[10:11]
	v_sqrt_f32_e32 v137, v136
	s_nop 0
	v_add_u32_e32 v138, -1, v137
	v_fma_f32 v139, -v138, v137, v136
	v_cmp_ge_f32_e32 vcc, 0, v139
	v_add_u32_e32 v139, 1, v137
	s_nop 0
	v_cndmask_b32_e32 v138, v137, v138, vcc
	v_fma_f32 v137, -v139, v137, v136
	v_cmp_lt_f32_e32 vcc, 0, v137
	s_nop 1
	v_cndmask_b32_e32 v137, v138, v139, vcc
	v_mul_f32_e32 v138, 0x37800000, v137
	v_cndmask_b32_e64 v137, v137, v138, s[10:11]
	v_cmp_class_f32_e32 vcc, v136, v182
	s_nop 1
	v_cndmask_b32_e32 v136, v137, v136, vcc
	v_mul_f32_e32 v135, v135, v136
	v_mul_f32_e32 v135, v135, v189
	v_cvt_pk_bf16_f32 v135, v185, v135
	v_lshl_add_u64 v[136:137], v[172:173], 2, s[36:37]
	flat_store_dwordx4 v[136:137], v[132:135]
	s_nop 1
	v_or_b32_e32 v132, 16, v170
	v_ashrrev_i32_e32 v133, 31, v132
	v_lshlrev_b64 v[132:133], 11, v[132:133]
	v_lshl_add_u64 v[134:135], v[132:133], 0, v[160:161]
	v_lshl_add_u64 v[136:137], v[134:135], 1, s[16:17]
	flat_load_dwordx2 v[136:137], v[136:137]
	v_add_f32_e32 v128, v128, v96
	v_add_f32_e32 v129, v129, v97
	v_mul_f32_e32 v128, 0xbfb8aa3b, v128
	v_mul_f32_e32 v129, 0xbfb8aa3b, v129
	v_exp_f32_e32 v128, v128
	v_exp_f32_e32 v129, v129
	v_add_f32_e32 v124, v124, v92
	v_mul_f32_e32 v124, 0xbfb8aa3b, v124
	v_add_f32_e32 v128, 1.0, v128
	v_add_f32_e32 v171, 1.0, v129
	v_exp_f32_e32 v124, v124
	s_nop 0
	v_add_f32_e32 v124, 1.0, v124
	v_div_scale_f32 v139, s[10:11], v124, v124, 1.0
	v_rcp_f32_e32 v173, v139
	s_nop 0
	v_fma_f32 v185, -v139, v173, 1.0
	v_div_scale_f32 v159, s[10:11], 1.0, v124, 1.0
	v_fmac_f32_e32 v173, v185, v173
	v_rcp_f32_e32 v128, v128
	v_mul_f32_e32 v185, v159, v173
	v_mul_f32_e64 v184, v128, -v88
	v_fma_f32 v187, -v139, v185, v159
	v_mul_f32_e32 v128, -2.0, v184
	v_fmac_f32_e32 v185, v187, v173
	v_mul_f32_e32 v129, 0x3e4ccccd, v128
	v_fma_f32 v157, v128, s81, 1.0
	v_fma_f32 v186, -v139, v185, v159
	v_pk_mul_f32 v[138:139], v[128:129], v[156:157]
	v_mul_f32_e32 v159, 0x3eaaaaab, v128
	v_sub_f32_e32 v139, 1.0, v139
	v_mov_b32_e32 v129, v159
	v_fma_f32 v159, -v138, v139, 1.0
	v_pk_mul_f32 v[138:139], v[128:129], v[158:159]
	s_mov_b64 vcc, s[10:11]
	v_sub_f32_e32 v129, 1.0, v139
	v_fma_f32 v129, -v138, v129, 1.0
	v_mul_f32_e32 v128, v128, v129
	v_max_f32_e32 v128, 0, v128
	v_mul_f32_e32 v129, 0x4f800000, v128
	v_cmp_gt_f32_e64 s[12:13], s82, v128
	v_div_fmas_f32 v138, v186, v173, v185
	v_div_fixup_f32 v124, v138, v124, 1.0
	v_cndmask_b32_e64 v128, v128, v129, s[12:13]
	v_sqrt_f32_e32 v129, v128
	v_add_f32_e32 v125, v125, v93
	v_mul_f32_e32 v125, 0xbfb8aa3b, v125
	v_exp_f32_e32 v125, v125
	v_add_u32_e32 v138, -1, v129
	v_add_u32_e32 v139, 1, v129
	v_fma_f32 v157, -v138, v129, v128
	v_fma_f32 v159, -v139, v129, v128
	v_cmp_ge_f32_e32 vcc, 0, v157
	v_add_f32_e32 v125, 1.0, v125
	v_add_f32_e32 v130, v130, v98
	v_cndmask_b32_e32 v129, v129, v138, vcc
	v_cmp_lt_f32_e32 vcc, 0, v159
	v_mul_f32_e32 v130, 0xbfb8aa3b, v130
	v_exp_f32_e32 v130, v130
	v_cndmask_b32_e32 v129, v129, v139, vcc
	v_mul_f32_e32 v138, 0x37800000, v129
	v_cndmask_b32_e64 v129, v129, v138, s[12:13]
	v_cmp_class_f32_e32 vcc, v128, v182
	s_waitcnt vmcnt(0) lgkmcnt(0)
; DI unsigned pk2(float a, float b) { f32x2 v = {a, b}; bf16v2_t r = __builtin_convertvector(v, bf16v2_t); return __builtin_bit_cast(unsigned, r); }
; DI float sigm(float x) { return 1.f / (1.f + __expf(-x)); }
;     DI void operator()(const Acc& acc, const Unit& u, int wr, int wc, int fr, int fq, const float (&pre)[8]) const {
;     ...
;         for (int n = 0; n < 2; ++n) {
;             const f32x4 br = *(const f32x4*)(brg + f0 + 4 * n), bi = *(const f32x4*)(big + f0 + 4 * n), sp = *(const f32x4*)(sp8t + f0 + 4 * n);
; #pragma unroll
;             for (int ai = 0; ai < 2; ++ai)
; #pragma unroll
;                 for (int m = 0; m < 4; ++m) { const size_t o = (size_t)(row0 + ai * HALF + m * 16) * DM + f0 + 4 * n;
;                     const u32x2 xw = *(const u32x2*)(xc + o);
;                     const float xv[4] = {__uint_as_float(xw.x << 16), __uint_as_float(xw.x & 0xffff0000u), __uint_as_float(xw.y << 16), __uint_as_float(xw.y & 0xffff0000u)};
;                     u32x4 w;
; #pragma unroll
;                     for (int e = 0; e < 4; ++e) { const float r = sigm(acc[ai][0][m][n][e] + br[e]), ig = sigm(acc[ai][1][m][n][e] + bi[e]);
;                         const float la = -sp[e] * r, uu = -2.f * la;
;                         const float om = uu * (1.f - uu * 0.5f * (1.f - uu * (1.f / 3.f) * (1.f - uu * 0.25f * (1.f - uu * 0.2f * (1.f - uu * (1.f / 6.f))))));
;                         w[e] = pk2(la, sqrtf(fmaxf(om, 0.f)) * ig * xv[e]); }
;                     *(u32x4*)(ax + o) = w; __builtin_amdgcn_sched_barrier(0); }
	v_and_b32_e32 v138, 0xffff0000, v136
	v_lshlrev_b32_e32 v139, 16, v137
	v_cndmask_b32_e32 v128, v129, v128, vcc
	v_mul_f32_e32 v124, v124, v128
	v_lshlrev_b32_e32 v128, 16, v136
	v_mul_f32_e32 v124, v124, v128
	v_rcp_f32_e32 v128, v171
	v_and_b32_e32 v173, 0xffff0000, v137
	v_cvt_pk_bf16_f32 v124, v184, v124
	v_mul_f32_e64 v184, v128, -v89
	v_mul_f32_e32 v128, -2.0, v184
	v_mul_f32_e32 v129, 0x3e4ccccd, v128
	v_fma_f32 v157, v128, s81, 1.0
	v_pk_mul_f32 v[136:137], v[128:129], v[156:157]
	v_mul_f32_e32 v185, 0x3eaaaaab, v128
	v_sub_f32_e32 v129, 1.0, v137
	v_fma_f32 v159, -v136, v129, 1.0
	v_mov_b32_e32 v129, v185
	v_pk_mul_f32 v[136:137], v[128:129], v[158:159]
	v_add_f32_e32 v126, v126, v94
	v_sub_f32_e32 v129, 1.0, v137
	v_fma_f32 v129, -v136, v129, 1.0
	v_mul_f32_e32 v128, v128, v129
	v_max_f32_e32 v128, 0, v128
	v_mul_f32_e32 v129, 0x4f800000, v128
	v_cmp_gt_f32_e64 s[10:11], s82, v128
	v_rcp_f32_e32 v125, v125
	s_nop 0
	v_cndmask_b32_e64 v128, v128, v129, s[10:11]
	v_sqrt_f32_e32 v129, v128
	v_mul_f32_e32 v126, 0xbfb8aa3b, v126
	v_exp_f32_e32 v126, v126
	v_add_f32_e32 v131, v131, v99
	v_add_u32_e32 v136, -1, v129
	v_fma_f32 v137, -v136, v129, v128
	v_cmp_ge_f32_e32 vcc, 0, v137
	v_add_u32_e32 v137, 1, v129
	v_add_f32_e32 v126, 1.0, v126
	v_cndmask_b32_e32 v136, v129, v136, vcc
	v_fma_f32 v129, -v137, v129, v128
	v_cmp_lt_f32_e32 vcc, 0, v129
	v_mul_f32_e32 v131, 0xbfb8aa3b, v131
	v_exp_f32_e32 v131, v131
	v_cndmask_b32_e32 v129, v136, v137, vcc
	v_mul_f32_e32 v136, 0x37800000, v129
	v_cndmask_b32_e64 v129, v129, v136, s[10:11]
	v_cmp_class_f32_e32 vcc, v128, v182
	v_add_f32_e32 v127, v127, v95
	v_mul_f32_e32 v127, 0xbfb8aa3b, v127
	v_cndmask_b32_e32 v128, v129, v128, vcc
	v_add_f32_e32 v129, 1.0, v130
	v_mul_f32_e32 v125, v125, v128
	v_mul_f32_e32 v125, v125, v138
	v_exp_f32_e32 v127, v127
	v_rcp_f32_e32 v128, v129
	s_nop 0
	v_mul_f32_e64 v172, v128, -v90
	v_mul_f32_e32 v128, -2.0, v172
	v_mul_f32_e32 v129, 0x3e4ccccd, v128
	v_fma_f32 v157, v128, s81, 1.0
	v_pk_mul_f32 v[136:137], v[128:129], v[156:157]
	v_mul_f32_e32 v183, 0x3eaaaaab, v128
	v_sub_f32_e32 v129, 1.0, v137
	v_fma_f32 v159, -v136, v129, 1.0
	v_mov_b32_e32 v129, v183
	v_pk_mul_f32 v[136:137], v[128:129], v[158:159]
	v_sub_f32_e32 v129, 1.0, v137
	v_fma_f32 v129, -v136, v129, 1.0
	v_mul_f32_e32 v128, v128, v129
	v_max_f32_e32 v128, 0, v128
	v_mul_f32_e32 v129, 0x4f800000, v128
	v_cmp_gt_f32_e64 s[10:11], s82, v128
	v_rcp_f32_e32 v126, v126
	v_add_f32_e32 v127, 1.0, v127
	v_cndmask_b32_e64 v128, v128, v129, s[10:11]
	v_sqrt_f32_e32 v129, v128
	v_cvt_pk_bf16_f32 v125, v184, v125
	v_add_u32_e32 v130, -1, v129
	v_fma_f32 v136, -v130, v129, v128
	v_cmp_ge_f32_e32 vcc, 0, v136
	v_add_u32_e32 v136, 1, v129
	s_nop 0
	v_cndmask_b32_e32 v130, v129, v130, vcc
	v_fma_f32 v129, -v136, v129, v128
	v_cmp_lt_f32_e32 vcc, 0, v129
	s_nop 1
	v_cndmask_b32_e32 v129, v130, v136, vcc
	v_mul_f32_e32 v130, 0x37800000, v129
	v_cndmask_b32_e64 v129, v129, v130, s[10:11]
	v_cmp_class_f32_e32 vcc, v128, v182
	s_nop 1
	v_cndmask_b32_e32 v128, v129, v128, vcc
	v_add_f32_e32 v129, 1.0, v131
	v_mul_f32_e32 v126, v126, v128
	v_mul_f32_e32 v126, v126, v139
	v_cvt_pk_bf16_f32 v126, v172, v126
	v_rcp_f32_e32 v128, v129
	s_nop 0
	v_mul_f32_e64 v139, v128, -v91
	v_mul_f32_e32 v128, -2.0, v139
	v_mul_f32_e32 v129, 0x3e4ccccd, v128
	v_fma_f32 v157, v128, s81, 1.0
	v_pk_mul_f32 v[130:131], v[128:129], v[156:157]
	v_mul_f32_e32 v171, 0x3eaaaaab, v128
	v_sub_f32_e32 v129, 1.0, v131
	v_fma_f32 v159, -v130, v129, 1.0
	v_mov_b32_e32 v129, v171
	v_pk_mul_f32 v[130:131], v[128:129], v[158:159]
	s_nop 0
	v_sub_f32_e32 v129, 1.0, v131
	v_fma_f32 v129, -v130, v129, 1.0
	v_mul_f32_e32 v128, v128, v129
	v_max_f32_e32 v128, 0, v128
	v_mul_f32_e32 v129, 0x4f800000, v128
	v_cmp_gt_f32_e64 s[10:11], s82, v128
	v_rcp_f32_e32 v127, v127
	s_nop 0
	v_cndmask_b32_e64 v128, v128, v129, s[10:11]
	v_sqrt_f32_e32 v129, v128
	s_nop 0
	v_add_u32_e32 v130, -1, v129
	v_fma_f32 v131, -v130, v129, v128
	v_cmp_ge_f32_e32 vcc, 0, v131
	v_add_u32_e32 v131, 1, v129
	s_nop 0
	v_cndmask_b32_e32 v130, v129, v130, vcc
	v_fma_f32 v129, -v131, v129, v128
	v_cmp_lt_f32_e32 vcc, 0, v129
	s_nop 1
	v_cndmask_b32_e32 v129, v130, v131, vcc
	v_mul_f32_e32 v130, 0x37800000, v129
	v_cndmask_b32_e64 v129, v129, v130, s[10:11]
	v_cmp_class_f32_e32 vcc, v128, v182
	s_nop 1
	v_cndmask_b32_e32 v128, v129, v128, vcc
	v_mul_f32_e32 v127, v127, v128
	v_mul_f32_e32 v127, v127, v173
	v_cvt_pk_bf16_f32 v127, v139, v127
	v_lshl_add_u64 v[128:129], v[134:135], 2, s[36:37]
	flat_store_dwordx4 v[128:129], v[124:127]
	s_nop 1
	v_or_b32_e32 v124, 32, v170
	v_ashrrev_i32_e32 v125, 31, v124
	v_lshlrev_b64 v[124:125], 11, v[124:125]
	v_lshl_add_u64 v[126:127], v[124:125], 0, v[160:161]
	v_lshl_add_u64 v[128:129], v[126:127], 1, s[16:17]
	flat_load_dwordx2 v[128:129], v[128:129]
	v_add_f32_e32 v120, v120, v96
	v_add_f32_e32 v121, v121, v97
	v_mul_f32_e32 v120, 0xbfb8aa3b, v120
	v_add_f32_e32 v116, v116, v92
	v_mul_f32_e32 v121, 0xbfb8aa3b, v121
	v_exp_f32_e32 v120, v120
	v_mul_f32_e32 v116, 0xbfb8aa3b, v116
	v_exp_f32_e32 v121, v121
	v_exp_f32_e32 v116, v116
	v_add_f32_e32 v120, 1.0, v120
	v_add_f32_e32 v134, 1.0, v121
	v_add_f32_e32 v116, 1.0, v116
	v_div_scale_f32 v131, s[10:11], v116, v116, 1.0
	v_rcp_f32_e32 v137, v131
	s_nop 0
	v_fma_f32 v159, -v131, v137, 1.0
	v_fmac_f32_e32 v137, v159, v137
	v_div_scale_f32 v139, s[10:11], 1.0, v116, 1.0
	v_rcp_f32_e32 v120, v120
	v_mul_f32_e32 v171, v139, v137
	v_mul_f32_e64 v136, v120, -v88
	v_fma_f32 v172, -v131, v171, v139
	v_mul_f32_e32 v120, -2.0, v136
	v_fmac_f32_e32 v171, v172, v137
	v_mul_f32_e32 v121, 0x3e4ccccd, v120
	v_fma_f32 v157, v120, s81, 1.0
	v_fma_f32 v139, -v131, v171, v139
	v_pk_mul_f32 v[130:131], v[120:121], v[156:157]
	v_mul_f32_e32 v159, 0x3eaaaaab, v120
	v_sub_f32_e32 v131, 1.0, v131
	v_mov_b32_e32 v121, v159
	v_fma_f32 v159, -v130, v131, 1.0
	v_pk_mul_f32 v[130:131], v[120:121], v[158:159]
	s_mov_b64 vcc, s[10:11]
	v_sub_f32_e32 v121, 1.0, v131
	v_fma_f32 v121, -v130, v121, 1.0
	v_mul_f32_e32 v120, v120, v121
	v_max_f32_e32 v120, 0, v120
	v_mul_f32_e32 v121, 0x4f800000, v120
	v_cmp_gt_f32_e64 s[12:13], s82, v120
	v_div_fmas_f32 v130, v139, v137, v171
	v_div_fixup_f32 v116, v130, v116, 1.0
	v_cndmask_b32_e64 v120, v120, v121, s[12:13]
	v_sqrt_f32_e32 v121, v120
	v_add_f32_e32 v117, v117, v93
	v_mul_f32_e32 v117, 0xbfb8aa3b, v117
	v_exp_f32_e32 v117, v117
	v_add_u32_e32 v130, -1, v121
	v_add_u32_e32 v131, 1, v121
	v_fma_f32 v137, -v130, v121, v120
	v_fma_f32 v139, -v131, v121, v120
	v_cmp_ge_f32_e32 vcc, 0, v137
	v_add_f32_e32 v117, 1.0, v117
	v_add_f32_e32 v122, v122, v98
	v_cndmask_b32_e32 v121, v121, v130, vcc
	v_cmp_lt_f32_e32 vcc, 0, v139
	v_mul_f32_e32 v122, 0xbfb8aa3b, v122
	v_exp_f32_e32 v122, v122
	v_cndmask_b32_e32 v121, v121, v131, vcc
	v_mul_f32_e32 v130, 0x37800000, v121
	v_cndmask_b32_e64 v121, v121, v130, s[12:13]
	v_cmp_class_f32_e32 vcc, v120, v182
	s_waitcnt vmcnt(0) lgkmcnt(0)
; DI unsigned pk2(float a, float b) { f32x2 v = {a, b}; bf16v2_t r = __builtin_convertvector(v, bf16v2_t); return __builtin_bit_cast(unsigned, r); }
; DI float sigm(float x) { return 1.f / (1.f + __expf(-x)); }
;     DI void operator()(const Acc& acc, const Unit& u, int wr, int wc, int fr, int fq, const float (&pre)[8]) const {
;     ...
;         for (int n = 0; n < 2; ++n) {
;             const f32x4 br = *(const f32x4*)(brg + f0 + 4 * n), bi = *(const f32x4*)(big + f0 + 4 * n), sp = *(const f32x4*)(sp8t + f0 + 4 * n);
; #pragma unroll
;             for (int ai = 0; ai < 2; ++ai)
; #pragma unroll
;                 for (int m = 0; m < 4; ++m) { const size_t o = (size_t)(row0 + ai * HALF + m * 16) * DM + f0 + 4 * n;
;                     const u32x2 xw = *(const u32x2*)(xc + o);
;                     const float xv[4] = {__uint_as_float(xw.x << 16), __uint_as_float(xw.x & 0xffff0000u), __uint_as_float(xw.y << 16), __uint_as_float(xw.y & 0xffff0000u)};
;                     u32x4 w;
; #pragma unroll
;                     for (int e = 0; e < 4; ++e) { const float r = sigm(acc[ai][0][m][n][e] + br[e]), ig = sigm(acc[ai][1][m][n][e] + bi[e]);
;                         const float la = -sp[e] * r, uu = -2.f * la;
;                         const float om = uu * (1.f - uu * 0.5f * (1.f - uu * (1.f / 3.f) * (1.f - uu * 0.25f * (1.f - uu * 0.2f * (1.f - uu * (1.f / 6.f))))));
;                         w[e] = pk2(la, sqrtf(fmaxf(om, 0.f)) * ig * xv[e]); }
;                     *(u32x4*)(ax + o) = w; __builtin_amdgcn_sched_barrier(0); }
	v_and_b32_e32 v130, 0xffff0000, v128
	v_lshlrev_b32_e32 v131, 16, v129
	v_cndmask_b32_e32 v120, v121, v120, vcc
	v_mul_f32_e32 v116, v116, v120
	v_lshlrev_b32_e32 v120, 16, v128
	v_mul_f32_e32 v116, v116, v120
	v_rcp_f32_e32 v120, v134
	v_and_b32_e32 v137, 0xffff0000, v129
	v_mul_f32_e64 v138, v120, -v89
	v_mul_f32_e32 v120, -2.0, v138
	v_cvt_pk_bf16_f32 v116, v136, v116
	v_mul_f32_e32 v121, 0x3e4ccccd, v120
	v_fma_f32 v157, v120, s81, 1.0
	v_pk_mul_f32 v[128:129], v[120:121], v[156:157]
	v_mul_f32_e32 v139, 0x3eaaaaab, v120
	v_sub_f32_e32 v121, 1.0, v129
	v_fma_f32 v159, -v128, v121, 1.0
	v_mov_b32_e32 v121, v139
	v_pk_mul_f32 v[128:129], v[120:121], v[158:159]
	v_add_f32_e32 v118, v118, v94
	v_sub_f32_e32 v121, 1.0, v129
	v_fma_f32 v121, -v128, v121, 1.0
	v_mul_f32_e32 v120, v120, v121
	v_max_f32_e32 v120, 0, v120
	v_mul_f32_e32 v121, 0x4f800000, v120
	v_cmp_gt_f32_e64 s[10:11], s82, v120
	v_rcp_f32_e32 v117, v117
	s_nop 0
	v_cndmask_b32_e64 v120, v120, v121, s[10:11]
	v_sqrt_f32_e32 v121, v120
	v_mul_f32_e32 v118, 0xbfb8aa3b, v118
	v_exp_f32_e32 v118, v118
	v_add_f32_e32 v123, v123, v99
	v_add_u32_e32 v128, -1, v121
	v_fma_f32 v129, -v128, v121, v120
	v_cmp_ge_f32_e32 vcc, 0, v129
	v_add_u32_e32 v129, 1, v121
	v_add_f32_e32 v118, 1.0, v118
	v_cndmask_b32_e32 v128, v121, v128, vcc
	v_fma_f32 v121, -v129, v121, v120
	v_cmp_lt_f32_e32 vcc, 0, v121
	v_mul_f32_e32 v123, 0xbfb8aa3b, v123
	v_exp_f32_e32 v123, v123
	v_cndmask_b32_e32 v121, v128, v129, vcc
	v_mul_f32_e32 v128, 0x37800000, v121
	v_cndmask_b32_e64 v121, v121, v128, s[10:11]
	v_cmp_class_f32_e32 vcc, v120, v182
	v_add_f32_e32 v119, v119, v95
	v_mul_f32_e32 v119, 0xbfb8aa3b, v119
	v_cndmask_b32_e32 v120, v121, v120, vcc
	v_add_f32_e32 v121, 1.0, v122
	v_mul_f32_e32 v117, v117, v120
	v_mul_f32_e32 v117, v117, v130
	v_exp_f32_e32 v119, v119
	v_rcp_f32_e32 v120, v121
	s_nop 0
	v_mul_f32_e64 v135, v120, -v90
	v_mul_f32_e32 v120, -2.0, v135
	v_mul_f32_e32 v121, 0x3e4ccccd, v120
	v_fma_f32 v157, v120, s81, 1.0
	v_pk_mul_f32 v[128:129], v[120:121], v[156:157]
	v_mul_f32_e32 v136, 0x3eaaaaab, v120
	v_sub_f32_e32 v121, 1.0, v129
	v_fma_f32 v159, -v128, v121, 1.0
	v_mov_b32_e32 v121, v136
	v_pk_mul_f32 v[128:129], v[120:121], v[158:159]
	v_sub_f32_e32 v121, 1.0, v129
	v_fma_f32 v121, -v128, v121, 1.0
	v_mul_f32_e32 v120, v120, v121
	v_max_f32_e32 v120, 0, v120
	v_mul_f32_e32 v121, 0x4f800000, v120
	v_cmp_gt_f32_e64 s[10:11], s82, v120
	v_rcp_f32_e32 v118, v118
	v_add_f32_e32 v119, 1.0, v119
	v_cndmask_b32_e64 v120, v120, v121, s[10:11]
	v_sqrt_f32_e32 v121, v120
	v_cvt_pk_bf16_f32 v117, v138, v117
	v_add_u32_e32 v122, -1, v121
	v_fma_f32 v128, -v122, v121, v120
	v_cmp_ge_f32_e32 vcc, 0, v128
	v_add_u32_e32 v128, 1, v121
	s_nop 0
	v_cndmask_b32_e32 v122, v121, v122, vcc
	v_fma_f32 v121, -v128, v121, v120
	v_cmp_lt_f32_e32 vcc, 0, v121
	s_nop 1
	v_cndmask_b32_e32 v121, v122, v128, vcc
	v_mul_f32_e32 v122, 0x37800000, v121
	v_cndmask_b32_e64 v121, v121, v122, s[10:11]
	v_cmp_class_f32_e32 vcc, v120, v182
	s_nop 1
	v_cndmask_b32_e32 v120, v121, v120, vcc
	v_add_f32_e32 v121, 1.0, v123
	v_mul_f32_e32 v118, v118, v120
	v_mul_f32_e32 v118, v118, v131
	v_cvt_pk_bf16_f32 v118, v135, v118
	v_rcp_f32_e32 v120, v121
	s_nop 0
	v_mul_f32_e64 v131, v120, -v91
	v_mul_f32_e32 v120, -2.0, v131
	v_mul_f32_e32 v121, 0x3e4ccccd, v120
	v_fma_f32 v157, v120, s81, 1.0
	v_pk_mul_f32 v[122:123], v[120:121], v[156:157]
	v_mul_f32_e32 v134, 0x3eaaaaab, v120
	v_sub_f32_e32 v121, 1.0, v123
	v_fma_f32 v159, -v122, v121, 1.0
	v_mov_b32_e32 v121, v134
	v_pk_mul_f32 v[122:123], v[120:121], v[158:159]
	s_nop 0
	v_sub_f32_e32 v121, 1.0, v123
	v_fma_f32 v121, -v122, v121, 1.0
	v_mul_f32_e32 v120, v120, v121
	v_max_f32_e32 v120, 0, v120
	v_mul_f32_e32 v121, 0x4f800000, v120
	v_cmp_gt_f32_e64 s[10:11], s82, v120
	v_rcp_f32_e32 v119, v119
	s_nop 0
	v_cndmask_b32_e64 v120, v120, v121, s[10:11]
	v_sqrt_f32_e32 v121, v120
	s_nop 0
	v_add_u32_e32 v122, -1, v121
	v_fma_f32 v123, -v122, v121, v120
	v_cmp_ge_f32_e32 vcc, 0, v123
	v_add_u32_e32 v123, 1, v121
	s_nop 0
	v_cndmask_b32_e32 v122, v121, v122, vcc
	v_fma_f32 v121, -v123, v121, v120
	v_cmp_lt_f32_e32 vcc, 0, v121
	s_nop 1
	v_cndmask_b32_e32 v121, v122, v123, vcc
	v_mul_f32_e32 v122, 0x37800000, v121
	v_cndmask_b32_e64 v121, v121, v122, s[10:11]
	v_cmp_class_f32_e32 vcc, v120, v182
	s_nop 1
	v_cndmask_b32_e32 v120, v121, v120, vcc
	v_mul_f32_e32 v119, v119, v120
	v_mul_f32_e32 v119, v119, v137
	v_cvt_pk_bf16_f32 v119, v131, v119
	v_lshl_add_u64 v[120:121], v[126:127], 2, s[36:37]
	flat_store_dwordx4 v[120:121], v[116:119]
	s_nop 1
	v_or_b32_e32 v116, 48, v170
	v_ashrrev_i32_e32 v117, 31, v116
	v_lshlrev_b64 v[116:117], 11, v[116:117]
	v_lshl_add_u64 v[118:119], v[116:117], 0, v[160:161]
	v_lshl_add_u64 v[120:121], v[118:119], 1, s[16:17]
	flat_load_dwordx2 v[120:121], v[120:121]
	v_add_f32_e32 v112, v112, v96
	v_add_f32_e32 v113, v113, v97
	v_mul_f32_e32 v112, 0xbfb8aa3b, v112
	v_mul_f32_e32 v113, 0xbfb8aa3b, v113
	v_exp_f32_e32 v112, v112
	v_exp_f32_e32 v113, v113
	v_add_f32_e32 v108, v108, v92
	v_mul_f32_e32 v108, 0xbfb8aa3b, v108
	v_add_f32_e32 v112, 1.0, v112
	v_add_f32_e32 v126, 1.0, v113
	v_exp_f32_e32 v108, v108
	s_nop 0
	v_add_f32_e32 v108, 1.0, v108
	v_div_scale_f32 v123, s[10:11], v108, v108, 1.0
	v_rcp_f32_e32 v129, v123
	s_nop 0
	v_fma_f32 v135, -v123, v129, 1.0
	v_div_scale_f32 v131, s[10:11], 1.0, v108, 1.0
	v_fmac_f32_e32 v129, v135, v129
	v_rcp_f32_e32 v112, v112
	v_mul_f32_e32 v135, v131, v129
	v_mul_f32_e64 v128, v112, -v88
	v_fma_f32 v137, -v123, v135, v131
	v_mul_f32_e32 v112, -2.0, v128
	v_fmac_f32_e32 v135, v137, v129
	v_mul_f32_e32 v113, 0x3e4ccccd, v112
	v_fma_f32 v157, v112, s81, 1.0
	v_fma_f32 v131, -v123, v135, v131
	v_pk_mul_f32 v[122:123], v[112:113], v[156:157]
	v_mul_f32_e32 v134, 0x3eaaaaab, v112
	v_sub_f32_e32 v123, 1.0, v123
	v_mov_b32_e32 v113, v134
	v_fma_f32 v159, -v122, v123, 1.0
	v_pk_mul_f32 v[122:123], v[112:113], v[158:159]
	s_mov_b64 vcc, s[10:11]
	v_sub_f32_e32 v113, 1.0, v123
	v_fma_f32 v113, -v122, v113, 1.0
	v_mul_f32_e32 v112, v112, v113
	v_max_f32_e32 v112, 0, v112
	v_mul_f32_e32 v113, 0x4f800000, v112
	v_cmp_gt_f32_e64 s[12:13], s82, v112
	v_div_fmas_f32 v122, v131, v129, v135
	v_div_fixup_f32 v108, v122, v108, 1.0
	v_cndmask_b32_e64 v112, v112, v113, s[12:13]
	v_sqrt_f32_e32 v113, v112
	v_add_f32_e32 v109, v109, v93
	v_mul_f32_e32 v109, 0xbfb8aa3b, v109
	v_exp_f32_e32 v109, v109
	v_add_u32_e32 v122, -1, v113
	v_add_u32_e32 v123, 1, v113
	v_fma_f32 v129, -v122, v113, v112
	v_fma_f32 v131, -v123, v113, v112
	v_cmp_ge_f32_e32 vcc, 0, v129
	v_add_f32_e32 v109, 1.0, v109
	v_add_f32_e32 v114, v114, v98
	v_cndmask_b32_e32 v113, v113, v122, vcc
	v_cmp_lt_f32_e32 vcc, 0, v131
	v_mul_f32_e32 v114, 0xbfb8aa3b, v114
	v_exp_f32_e32 v114, v114
	v_cndmask_b32_e32 v113, v113, v123, vcc
	v_mul_f32_e32 v122, 0x37800000, v113
	v_cndmask_b32_e64 v113, v113, v122, s[12:13]
	v_cmp_class_f32_e32 vcc, v112, v182
	s_waitcnt vmcnt(0) lgkmcnt(0)
; DI unsigned pk2(float a, float b) { f32x2 v = {a, b}; bf16v2_t r = __builtin_convertvector(v, bf16v2_t); return __builtin_bit_cast(unsigned, r); }
; DI float sigm(float x) { return 1.f / (1.f + __expf(-x)); }
;     DI void operator()(const Acc& acc, const Unit& u, int wr, int wc, int fr, int fq, const float (&pre)[8]) const {
;     ...
;         for (int n = 0; n < 2; ++n) {
;             const f32x4 br = *(const f32x4*)(brg + f0 + 4 * n), bi = *(const f32x4*)(big + f0 + 4 * n), sp = *(const f32x4*)(sp8t + f0 + 4 * n);
; #pragma unroll
;             for (int ai = 0; ai < 2; ++ai)
; #pragma unroll
;                 for (int m = 0; m < 4; ++m) { const size_t o = (size_t)(row0 + ai * HALF + m * 16) * DM + f0 + 4 * n;
;                     const u32x2 xw = *(const u32x2*)(xc + o);
;                     const float xv[4] = {__uint_as_float(xw.x << 16), __uint_as_float(xw.x & 0xffff0000u), __uint_as_float(xw.y << 16), __uint_as_float(xw.y & 0xffff0000u)};
;                     u32x4 w;
; #pragma unroll
;                     for (int e = 0; e < 4; ++e) { const float r = sigm(acc[ai][0][m][n][e] + br[e]), ig = sigm(acc[ai][1][m][n][e] + bi[e]);
;                         const float la = -sp[e] * r, uu = -2.f * la;
;                         const float om = uu * (1.f - uu * 0.5f * (1.f - uu * (1.f / 3.f) * (1.f - uu * 0.25f * (1.f - uu * 0.2f * (1.f - uu * (1.f / 6.f))))));
;                         w[e] = pk2(la, sqrtf(fmaxf(om, 0.f)) * ig * xv[e]); }
;                     *(u32x4*)(ax + o) = w; __builtin_amdgcn_sched_barrier(0); }
	v_and_b32_e32 v122, 0xffff0000, v120
	v_lshlrev_b32_e32 v123, 16, v121
	v_cndmask_b32_e32 v112, v113, v112, vcc
	v_mul_f32_e32 v108, v108, v112
	v_lshlrev_b32_e32 v112, 16, v120
	v_mul_f32_e32 v108, v108, v112
	v_rcp_f32_e32 v112, v126
	v_and_b32_e32 v129, 0xffff0000, v121
	v_mul_f32_e64 v130, v112, -v89
	v_mul_f32_e32 v112, -2.0, v130
	v_cvt_pk_bf16_f32 v108, v128, v108
	v_mul_f32_e32 v113, 0x3e4ccccd, v112
	v_fma_f32 v157, v112, s81, 1.0
	v_pk_mul_f32 v[120:121], v[112:113], v[156:157]
	v_mul_f32_e32 v131, 0x3eaaaaab, v112
	v_sub_f32_e32 v113, 1.0, v121
	v_fma_f32 v159, -v120, v113, 1.0
	v_mov_b32_e32 v113, v131
	v_pk_mul_f32 v[120:121], v[112:113], v[158:159]
	v_add_f32_e32 v110, v110, v94
	v_sub_f32_e32 v113, 1.0, v121
	v_fma_f32 v113, -v120, v113, 1.0
	v_mul_f32_e32 v112, v112, v113
	v_max_f32_e32 v112, 0, v112
	v_mul_f32_e32 v113, 0x4f800000, v112
	v_cmp_gt_f32_e64 s[10:11], s82, v112
	v_rcp_f32_e32 v109, v109
	s_nop 0
	v_cndmask_b32_e64 v112, v112, v113, s[10:11]
	v_sqrt_f32_e32 v113, v112
	v_mul_f32_e32 v110, 0xbfb8aa3b, v110
	v_exp_f32_e32 v110, v110
	v_add_f32_e32 v115, v115, v99
	v_add_u32_e32 v120, -1, v113
	v_fma_f32 v121, -v120, v113, v112
	v_cmp_ge_f32_e32 vcc, 0, v121
	v_add_u32_e32 v121, 1, v113
	v_add_f32_e32 v110, 1.0, v110
	v_cndmask_b32_e32 v120, v113, v120, vcc
	v_fma_f32 v113, -v121, v113, v112
	v_cmp_lt_f32_e32 vcc, 0, v113
	v_mul_f32_e32 v115, 0xbfb8aa3b, v115
	v_exp_f32_e32 v115, v115
	v_cndmask_b32_e32 v113, v120, v121, vcc
	v_mul_f32_e32 v120, 0x37800000, v113
	v_cndmask_b32_e64 v113, v113, v120, s[10:11]
	v_cmp_class_f32_e32 vcc, v112, v182
	v_add_f32_e32 v111, v111, v95
	v_mul_f32_e32 v111, 0xbfb8aa3b, v111
	v_cndmask_b32_e32 v112, v113, v112, vcc
	v_add_f32_e32 v113, 1.0, v114
	v_mul_f32_e32 v109, v109, v112
	v_mul_f32_e32 v109, v109, v122
	v_exp_f32_e32 v111, v111
	v_rcp_f32_e32 v112, v113
	s_nop 0
	v_mul_f32_e64 v127, v112, -v90
	v_mul_f32_e32 v112, -2.0, v127
	v_mul_f32_e32 v113, 0x3e4ccccd, v112
	v_fma_f32 v157, v112, s81, 1.0
	v_pk_mul_f32 v[120:121], v[112:113], v[156:157]
	v_mul_f32_e32 v128, 0x3eaaaaab, v112
	v_sub_f32_e32 v113, 1.0, v121
	v_fma_f32 v159, -v120, v113, 1.0
	v_mov_b32_e32 v113, v128
	v_pk_mul_f32 v[120:121], v[112:113], v[158:159]
	v_sub_f32_e32 v113, 1.0, v121
	v_fma_f32 v113, -v120, v113, 1.0
	v_mul_f32_e32 v112, v112, v113
	v_max_f32_e32 v112, 0, v112
	v_mul_f32_e32 v113, 0x4f800000, v112
	v_cmp_gt_f32_e64 s[10:11], s82, v112
	v_rcp_f32_e32 v110, v110
	v_add_f32_e32 v111, 1.0, v111
	v_cndmask_b32_e64 v112, v112, v113, s[10:11]
	v_sqrt_f32_e32 v113, v112
	v_cvt_pk_bf16_f32 v109, v130, v109
	v_add_u32_e32 v114, -1, v113
	v_fma_f32 v120, -v114, v113, v112
	v_cmp_ge_f32_e32 vcc, 0, v120
	v_add_u32_e32 v120, 1, v113
	s_nop 0
	v_cndmask_b32_e32 v114, v113, v114, vcc
	v_fma_f32 v113, -v120, v113, v112
	v_cmp_lt_f32_e32 vcc, 0, v113
	s_nop 1
	v_cndmask_b32_e32 v113, v114, v120, vcc
	v_mul_f32_e32 v114, 0x37800000, v113
	v_cndmask_b32_e64 v113, v113, v114, s[10:11]
	v_cmp_class_f32_e32 vcc, v112, v182
	s_nop 1
	v_cndmask_b32_e32 v112, v113, v112, vcc
	v_add_f32_e32 v113, 1.0, v115
	v_mul_f32_e32 v110, v110, v112
	v_mul_f32_e32 v110, v110, v123
	v_cvt_pk_bf16_f32 v110, v127, v110
	v_rcp_f32_e32 v112, v113
	s_nop 0
	v_mul_f32_e64 v123, v112, -v91
	v_mul_f32_e32 v112, -2.0, v123
	v_mul_f32_e32 v113, 0x3e4ccccd, v112
	v_fma_f32 v157, v112, s81, 1.0
	v_pk_mul_f32 v[114:115], v[112:113], v[156:157]
	v_mul_f32_e32 v126, 0x3eaaaaab, v112
	v_sub_f32_e32 v113, 1.0, v115
	v_fma_f32 v159, -v114, v113, 1.0
	v_mov_b32_e32 v113, v126
	v_pk_mul_f32 v[114:115], v[112:113], v[158:159]
	s_nop 0
	v_sub_f32_e32 v113, 1.0, v115
	v_fma_f32 v113, -v114, v113, 1.0
	v_mul_f32_e32 v112, v112, v113
	v_max_f32_e32 v112, 0, v112
	v_mul_f32_e32 v113, 0x4f800000, v112
	v_cmp_gt_f32_e64 s[10:11], s82, v112
	v_rcp_f32_e32 v111, v111
	s_nop 0
	v_cndmask_b32_e64 v112, v112, v113, s[10:11]
	v_sqrt_f32_e32 v113, v112
	s_nop 0
	v_add_u32_e32 v114, -1, v113
	v_fma_f32 v115, -v114, v113, v112
	v_cmp_ge_f32_e32 vcc, 0, v115
	v_add_u32_e32 v115, 1, v113
	s_nop 0
	v_cndmask_b32_e32 v114, v113, v114, vcc
	v_fma_f32 v113, -v115, v113, v112
	v_cmp_lt_f32_e32 vcc, 0, v113
	s_nop 1
	v_cndmask_b32_e32 v113, v114, v115, vcc
	v_mul_f32_e32 v114, 0x37800000, v113
	v_cndmask_b32_e64 v113, v113, v114, s[10:11]
	v_cmp_class_f32_e32 vcc, v112, v182
	s_nop 1
	v_cndmask_b32_e32 v112, v113, v112, vcc
	v_mul_f32_e32 v111, v111, v112
	v_mul_f32_e32 v111, v111, v129
	v_cvt_pk_bf16_f32 v111, v123, v111
	v_lshl_add_u64 v[112:113], v[118:119], 2, s[36:37]
	flat_store_dwordx4 v[112:113], v[108:111]
	s_nop 1
	v_lshl_add_u64 v[108:109], v[166:167], 0, s[42:43]
	v_lshl_add_u64 v[110:111], v[108:109], 0, v[160:161]
	v_lshl_add_u64 v[112:113], v[110:111], 1, s[16:17]
	flat_load_dwordx2 v[112:113], v[112:113]
	v_add_f32_e32 v104, v104, v96
	v_add_f32_e32 v105, v105, v97
	v_mul_f32_e32 v104, 0xbfb8aa3b, v104
	v_mul_f32_e32 v105, 0xbfb8aa3b, v105
	v_exp_f32_e32 v104, v104
	v_exp_f32_e32 v105, v105
	v_add_f32_e32 v100, v100, v92
	v_mul_f32_e32 v100, 0xbfb8aa3b, v100
	v_add_f32_e32 v104, 1.0, v104
	v_add_f32_e32 v118, 1.0, v105
	v_exp_f32_e32 v100, v100
	s_nop 0
	v_add_f32_e32 v100, 1.0, v100
	v_div_scale_f32 v115, s[10:11], v100, v100, 1.0
	v_rcp_f32_e32 v121, v115
	s_nop 0
	v_fma_f32 v127, -v115, v121, 1.0
	v_div_scale_f32 v123, s[10:11], 1.0, v100, 1.0
	v_fmac_f32_e32 v121, v127, v121
	v_rcp_f32_e32 v104, v104
	v_mul_f32_e32 v127, v123, v121
	v_mul_f32_e64 v120, v104, -v88
	v_fma_f32 v129, -v115, v127, v123
	v_mul_f32_e32 v104, -2.0, v120
	v_fmac_f32_e32 v127, v129, v121
	v_mul_f32_e32 v105, 0x3e4ccccd, v104
	v_fma_f32 v157, v104, s81, 1.0
	v_fma_f32 v123, -v115, v127, v123
	v_pk_mul_f32 v[114:115], v[104:105], v[156:157]
	v_mul_f32_e32 v126, 0x3eaaaaab, v104
	v_sub_f32_e32 v115, 1.0, v115
	v_mov_b32_e32 v105, v126
	v_fma_f32 v159, -v114, v115, 1.0
	v_pk_mul_f32 v[114:115], v[104:105], v[158:159]
	s_mov_b64 vcc, s[10:11]
	v_sub_f32_e32 v105, 1.0, v115
	v_fma_f32 v105, -v114, v105, 1.0
	v_mul_f32_e32 v104, v104, v105
	v_max_f32_e32 v104, 0, v104
	v_mul_f32_e32 v105, 0x4f800000, v104
	v_cmp_gt_f32_e64 s[12:13], s82, v104
	v_div_fmas_f32 v114, v123, v121, v127
	v_div_fixup_f32 v100, v114, v100, 1.0
	v_cndmask_b32_e64 v104, v104, v105, s[12:13]
	v_sqrt_f32_e32 v105, v104
	v_add_f32_e32 v101, v101, v93
	v_mul_f32_e32 v101, 0xbfb8aa3b, v101
	v_exp_f32_e32 v101, v101
	v_add_u32_e32 v114, -1, v105
	v_add_u32_e32 v115, 1, v105
	v_fma_f32 v121, -v114, v105, v104
	v_fma_f32 v123, -v115, v105, v104
	v_cmp_ge_f32_e32 vcc, 0, v121
	v_add_f32_e32 v101, 1.0, v101
	v_add_f32_e32 v106, v106, v98
	v_cndmask_b32_e32 v105, v105, v114, vcc
	v_cmp_lt_f32_e32 vcc, 0, v123
	v_mul_f32_e32 v106, 0xbfb8aa3b, v106
	v_exp_f32_e32 v106, v106
	v_cndmask_b32_e32 v105, v105, v115, vcc
	v_mul_f32_e32 v114, 0x37800000, v105
	v_cndmask_b32_e64 v105, v105, v114, s[12:13]
	v_cmp_class_f32_e32 vcc, v104, v182
	s_waitcnt vmcnt(0) lgkmcnt(0)
; DI unsigned pk2(float a, float b) { f32x2 v = {a, b}; bf16v2_t r = __builtin_convertvector(v, bf16v2_t); return __builtin_bit_cast(unsigned, r); }
; DI float sigm(float x) { return 1.f / (1.f + __expf(-x)); }
;     DI void operator()(const Acc& acc, const Unit& u, int wr, int wc, int fr, int fq, const float (&pre)[8]) const {
;     ...
;         for (int n = 0; n < 2; ++n) {
;             const f32x4 br = *(const f32x4*)(brg + f0 + 4 * n), bi = *(const f32x4*)(big + f0 + 4 * n), sp = *(const f32x4*)(sp8t + f0 + 4 * n);
; #pragma unroll
;             for (int ai = 0; ai < 2; ++ai)
; #pragma unroll
;                 for (int m = 0; m < 4; ++m) { const size_t o = (size_t)(row0 + ai * HALF + m * 16) * DM + f0 + 4 * n;
;                     const u32x2 xw = *(const u32x2*)(xc + o);
;                     const float xv[4] = {__uint_as_float(xw.x << 16), __uint_as_float(xw.x & 0xffff0000u), __uint_as_float(xw.y << 16), __uint_as_float(xw.y & 0xffff0000u)};
;                     u32x4 w;
; #pragma unroll
;                     for (int e = 0; e < 4; ++e) { const float r = sigm(acc[ai][0][m][n][e] + br[e]), ig = sigm(acc[ai][1][m][n][e] + bi[e]);
;                         const float la = -sp[e] * r, uu = -2.f * la;
;                         const float om = uu * (1.f - uu * 0.5f * (1.f - uu * (1.f / 3.f) * (1.f - uu * 0.25f * (1.f - uu * 0.2f * (1.f - uu * (1.f / 6.f))))));
;                         w[e] = pk2(la, sqrtf(fmaxf(om, 0.f)) * ig * xv[e]); }
;                     *(u32x4*)(ax + o) = w; __builtin_amdgcn_sched_barrier(0); }
	v_and_b32_e32 v114, 0xffff0000, v112
	v_lshlrev_b32_e32 v115, 16, v113
	v_cndmask_b32_e32 v104, v105, v104, vcc
	v_mul_f32_e32 v100, v100, v104
	v_lshlrev_b32_e32 v104, 16, v112
	v_mul_f32_e32 v100, v100, v104
	v_rcp_f32_e32 v104, v118
	v_and_b32_e32 v121, 0xffff0000, v113
	v_mul_f32_e64 v122, v104, -v89
	v_mul_f32_e32 v104, -2.0, v122
	v_cvt_pk_bf16_f32 v100, v120, v100
	v_mul_f32_e32 v105, 0x3e4ccccd, v104
	v_fma_f32 v157, v104, s81, 1.0
	v_pk_mul_f32 v[112:113], v[104:105], v[156:157]
	v_mul_f32_e32 v123, 0x3eaaaaab, v104
	v_sub_f32_e32 v105, 1.0, v113
	v_fma_f32 v159, -v112, v105, 1.0
	v_mov_b32_e32 v105, v123
	v_pk_mul_f32 v[112:113], v[104:105], v[158:159]
	v_add_f32_e32 v102, v102, v94
	v_sub_f32_e32 v105, 1.0, v113
	v_fma_f32 v105, -v112, v105, 1.0
	v_mul_f32_e32 v104, v104, v105
	v_max_f32_e32 v104, 0, v104
	v_mul_f32_e32 v105, 0x4f800000, v104
	v_cmp_gt_f32_e64 s[10:11], s82, v104
	v_rcp_f32_e32 v101, v101
	s_nop 0
	v_cndmask_b32_e64 v104, v104, v105, s[10:11]
	v_sqrt_f32_e32 v105, v104
	v_mul_f32_e32 v102, 0xbfb8aa3b, v102
	v_exp_f32_e32 v102, v102
	v_add_f32_e32 v107, v107, v99
	v_add_u32_e32 v112, -1, v105
	v_fma_f32 v113, -v112, v105, v104
	v_cmp_ge_f32_e32 vcc, 0, v113
	v_add_u32_e32 v113, 1, v105
	v_add_f32_e32 v102, 1.0, v102
	v_cndmask_b32_e32 v112, v105, v112, vcc
	v_fma_f32 v105, -v113, v105, v104
	v_cmp_lt_f32_e32 vcc, 0, v105
	v_mul_f32_e32 v107, 0xbfb8aa3b, v107
	v_exp_f32_e32 v107, v107
	v_cndmask_b32_e32 v105, v112, v113, vcc
	v_mul_f32_e32 v112, 0x37800000, v105
	v_cndmask_b32_e64 v105, v105, v112, s[10:11]
	v_cmp_class_f32_e32 vcc, v104, v182
	v_add_f32_e32 v103, v103, v95
	v_mul_f32_e32 v103, 0xbfb8aa3b, v103
	v_cndmask_b32_e32 v104, v105, v104, vcc
	v_add_f32_e32 v105, 1.0, v106
	v_mul_f32_e32 v101, v101, v104
	v_mul_f32_e32 v101, v101, v114
	v_exp_f32_e32 v103, v103
	v_rcp_f32_e32 v104, v105
	s_nop 0
	v_mul_f32_e64 v119, v104, -v90
	v_mul_f32_e32 v104, -2.0, v119
	v_mul_f32_e32 v105, 0x3e4ccccd, v104
	v_fma_f32 v157, v104, s81, 1.0
	v_pk_mul_f32 v[112:113], v[104:105], v[156:157]
	v_mul_f32_e32 v120, 0x3eaaaaab, v104
	v_sub_f32_e32 v105, 1.0, v113
	v_fma_f32 v159, -v112, v105, 1.0
	v_mov_b32_e32 v105, v120
	v_pk_mul_f32 v[112:113], v[104:105], v[158:159]
	v_sub_f32_e32 v105, 1.0, v113
	v_fma_f32 v105, -v112, v105, 1.0
	v_mul_f32_e32 v104, v104, v105
	v_max_f32_e32 v104, 0, v104
	v_mul_f32_e32 v105, 0x4f800000, v104
	v_cmp_gt_f32_e64 s[10:11], s82, v104
	v_rcp_f32_e32 v102, v102
	v_add_f32_e32 v103, 1.0, v103
	v_cndmask_b32_e64 v104, v104, v105, s[10:11]
	v_sqrt_f32_e32 v105, v104
	v_cvt_pk_bf16_f32 v101, v122, v101
	v_add_u32_e32 v106, -1, v105
	v_fma_f32 v112, -v106, v105, v104
	v_cmp_ge_f32_e32 vcc, 0, v112
	v_add_u32_e32 v112, 1, v105
	s_nop 0
	v_cndmask_b32_e32 v106, v105, v106, vcc
	v_fma_f32 v105, -v112, v105, v104
	v_cmp_lt_f32_e32 vcc, 0, v105
	s_nop 1
	v_cndmask_b32_e32 v105, v106, v112, vcc
	v_mul_f32_e32 v106, 0x37800000, v105
	v_cndmask_b32_e64 v105, v105, v106, s[10:11]
	v_cmp_class_f32_e32 vcc, v104, v182
	s_nop 1
	v_cndmask_b32_e32 v104, v105, v104, vcc
	v_add_f32_e32 v105, 1.0, v107
	v_mul_f32_e32 v102, v102, v104
	v_mul_f32_e32 v102, v102, v115
	v_cvt_pk_bf16_f32 v102, v119, v102
	v_rcp_f32_e32 v104, v105
	s_nop 0
	v_mul_f32_e64 v115, v104, -v91
	v_mul_f32_e32 v104, -2.0, v115
	v_mul_f32_e32 v105, 0x3e4ccccd, v104
	v_fma_f32 v157, v104, s81, 1.0
	v_pk_mul_f32 v[106:107], v[104:105], v[156:157]
	v_mul_f32_e32 v118, 0x3eaaaaab, v104
	v_sub_f32_e32 v105, 1.0, v107
	v_fma_f32 v159, -v106, v105, 1.0
	v_mov_b32_e32 v105, v118
	v_pk_mul_f32 v[106:107], v[104:105], v[158:159]
	s_nop 0
	v_sub_f32_e32 v105, 1.0, v107
	v_fma_f32 v105, -v106, v105, 1.0
	v_mul_f32_e32 v104, v104, v105
	v_max_f32_e32 v104, 0, v104
	v_mul_f32_e32 v105, 0x4f800000, v104
	v_cmp_gt_f32_e64 s[10:11], s82, v104
	v_rcp_f32_e32 v103, v103
	s_nop 0
	v_cndmask_b32_e64 v104, v104, v105, s[10:11]
	v_sqrt_f32_e32 v105, v104
	s_nop 0
	v_add_u32_e32 v106, -1, v105
	v_fma_f32 v107, -v106, v105, v104
	v_cmp_ge_f32_e32 vcc, 0, v107
	v_add_u32_e32 v107, 1, v105
	s_nop 0
	v_cndmask_b32_e32 v106, v105, v106, vcc
	v_fma_f32 v105, -v107, v105, v104
	v_cmp_lt_f32_e32 vcc, 0, v105
	s_nop 1
	v_cndmask_b32_e32 v105, v106, v107, vcc
	v_mul_f32_e32 v106, 0x37800000, v105
	v_cndmask_b32_e64 v105, v105, v106, s[10:11]
	v_cmp_class_f32_e32 vcc, v104, v182
	s_nop 1
	v_cndmask_b32_e32 v104, v105, v104, vcc
	v_mul_f32_e32 v103, v103, v104
	v_mul_f32_e32 v103, v103, v121
	v_cvt_pk_bf16_f32 v103, v115, v103
	v_lshl_add_u64 v[104:105], v[110:111], 2, s[36:37]
	flat_store_dwordx4 v[104:105], v[100:103]
	s_nop 1
	v_lshl_add_u64 v[100:101], v[166:167], 0, s[44:45]
	v_lshl_add_u64 v[102:103], v[100:101], 0, v[160:161]
	v_lshl_add_u64 v[104:105], v[102:103], 1, s[16:17]
	flat_load_dwordx2 v[104:105], v[104:105]
	v_add_f32_e32 v84, v84, v96
	v_add_f32_e32 v85, v85, v97
	v_mul_f32_e32 v84, 0xbfb8aa3b, v84
	v_mul_f32_e32 v85, 0xbfb8aa3b, v85
	v_exp_f32_e32 v84, v84
	v_exp_f32_e32 v85, v85
	v_add_f32_e32 v80, v80, v92
	v_mul_f32_e32 v80, 0xbfb8aa3b, v80
	v_add_f32_e32 v84, 1.0, v84
	v_add_f32_e32 v110, 1.0, v85
	v_exp_f32_e32 v80, v80
	s_nop 0
	v_add_f32_e32 v80, 1.0, v80
	v_div_scale_f32 v107, s[10:11], v80, v80, 1.0
	v_rcp_f32_e32 v113, v107
	s_nop 0
	v_fma_f32 v119, -v107, v113, 1.0
	v_div_scale_f32 v115, s[10:11], 1.0, v80, 1.0
	v_fmac_f32_e32 v113, v119, v113
	v_rcp_f32_e32 v84, v84
	v_mul_f32_e32 v119, v115, v113
	v_mul_f32_e64 v112, v84, -v88
	v_fma_f32 v121, -v107, v119, v115
	v_mul_f32_e32 v84, -2.0, v112
	v_fmac_f32_e32 v119, v121, v113
	v_mul_f32_e32 v85, 0x3e4ccccd, v84
	v_fma_f32 v157, v84, s81, 1.0
	v_fma_f32 v115, -v107, v119, v115
	v_pk_mul_f32 v[106:107], v[84:85], v[156:157]
	v_mul_f32_e32 v118, 0x3eaaaaab, v84
	v_sub_f32_e32 v107, 1.0, v107
	v_mov_b32_e32 v85, v118
	v_fma_f32 v159, -v106, v107, 1.0
	v_pk_mul_f32 v[106:107], v[84:85], v[158:159]
	s_mov_b64 vcc, s[10:11]
	v_sub_f32_e32 v85, 1.0, v107
	v_fma_f32 v85, -v106, v85, 1.0
	v_mul_f32_e32 v84, v84, v85
	v_max_f32_e32 v84, 0, v84
	v_mul_f32_e32 v85, 0x4f800000, v84
	v_cmp_gt_f32_e64 s[12:13], s82, v84
	v_div_fmas_f32 v106, v115, v113, v119
	v_div_fixup_f32 v80, v106, v80, 1.0
	v_cndmask_b32_e64 v84, v84, v85, s[12:13]
	v_sqrt_f32_e32 v85, v84
	v_add_f32_e32 v81, v81, v93
	v_mul_f32_e32 v81, 0xbfb8aa3b, v81
	v_exp_f32_e32 v81, v81
	v_add_u32_e32 v106, -1, v85
	v_add_u32_e32 v107, 1, v85
	v_fma_f32 v113, -v106, v85, v84
	v_fma_f32 v115, -v107, v85, v84
	v_cmp_ge_f32_e32 vcc, 0, v113
	v_add_f32_e32 v81, 1.0, v81
	v_add_f32_e32 v86, v86, v98
	v_cndmask_b32_e32 v85, v85, v106, vcc
	v_cmp_lt_f32_e32 vcc, 0, v115
	v_mul_f32_e32 v86, 0xbfb8aa3b, v86
	v_exp_f32_e32 v86, v86
	v_cndmask_b32_e32 v85, v85, v107, vcc
	v_mul_f32_e32 v106, 0x37800000, v85
	v_cndmask_b32_e64 v85, v85, v106, s[12:13]
	v_cmp_class_f32_e32 vcc, v84, v182
	s_waitcnt vmcnt(0) lgkmcnt(0)
; DI unsigned pk2(float a, float b) { f32x2 v = {a, b}; bf16v2_t r = __builtin_convertvector(v, bf16v2_t); return __builtin_bit_cast(unsigned, r); }
; DI float sigm(float x) { return 1.f / (1.f + __expf(-x)); }
;     DI void operator()(const Acc& acc, const Unit& u, int wr, int wc, int fr, int fq, const float (&pre)[8]) const {
;     ...
;         for (int n = 0; n < 2; ++n) {
;             const f32x4 br = *(const f32x4*)(brg + f0 + 4 * n), bi = *(const f32x4*)(big + f0 + 4 * n), sp = *(const f32x4*)(sp8t + f0 + 4 * n);
; #pragma unroll
;             for (int ai = 0; ai < 2; ++ai)
; #pragma unroll
;                 for (int m = 0; m < 4; ++m) { const size_t o = (size_t)(row0 + ai * HALF + m * 16) * DM + f0 + 4 * n;
;                     const u32x2 xw = *(const u32x2*)(xc + o);
;                     const float xv[4] = {__uint_as_float(xw.x << 16), __uint_as_float(xw.x & 0xffff0000u), __uint_as_float(xw.y << 16), __uint_as_float(xw.y & 0xffff0000u)};
;                     u32x4 w;
; #pragma unroll
;                     for (int e = 0; e < 4; ++e) { const float r = sigm(acc[ai][0][m][n][e] + br[e]), ig = sigm(acc[ai][1][m][n][e] + bi[e]);
;                         const float la = -sp[e] * r, uu = -2.f * la;
;                         const float om = uu * (1.f - uu * 0.5f * (1.f - uu * (1.f / 3.f) * (1.f - uu * 0.25f * (1.f - uu * 0.2f * (1.f - uu * (1.f / 6.f))))));
;                         w[e] = pk2(la, sqrtf(fmaxf(om, 0.f)) * ig * xv[e]); }
;                     *(u32x4*)(ax + o) = w; __builtin_amdgcn_sched_barrier(0); }
	v_and_b32_e32 v106, 0xffff0000, v104
	v_lshlrev_b32_e32 v107, 16, v105
	v_cndmask_b32_e32 v84, v85, v84, vcc
	v_mul_f32_e32 v80, v80, v84
	v_lshlrev_b32_e32 v84, 16, v104
	v_mul_f32_e32 v80, v80, v84
	v_rcp_f32_e32 v84, v110
	v_and_b32_e32 v113, 0xffff0000, v105
	v_mul_f32_e64 v114, v84, -v89
	v_mul_f32_e32 v84, -2.0, v114
	v_cvt_pk_bf16_f32 v80, v112, v80
	v_mul_f32_e32 v85, 0x3e4ccccd, v84
	v_fma_f32 v157, v84, s81, 1.0
	v_pk_mul_f32 v[104:105], v[84:85], v[156:157]
	v_mul_f32_e32 v115, 0x3eaaaaab, v84
	v_sub_f32_e32 v85, 1.0, v105
	v_fma_f32 v159, -v104, v85, 1.0
	v_mov_b32_e32 v85, v115
	v_pk_mul_f32 v[104:105], v[84:85], v[158:159]
	v_add_f32_e32 v82, v82, v94
	v_sub_f32_e32 v85, 1.0, v105
	v_fma_f32 v85, -v104, v85, 1.0
	v_mul_f32_e32 v84, v84, v85
	v_max_f32_e32 v84, 0, v84
	v_mul_f32_e32 v85, 0x4f800000, v84
	v_cmp_gt_f32_e64 s[10:11], s82, v84
	v_rcp_f32_e32 v81, v81
	s_nop 0
	v_cndmask_b32_e64 v84, v84, v85, s[10:11]
	v_sqrt_f32_e32 v85, v84
	v_mul_f32_e32 v82, 0xbfb8aa3b, v82
	v_exp_f32_e32 v82, v82
	v_add_f32_e32 v87, v87, v99
	v_add_u32_e32 v104, -1, v85
	v_fma_f32 v105, -v104, v85, v84
	v_cmp_ge_f32_e32 vcc, 0, v105
	v_add_u32_e32 v105, 1, v85
	v_add_f32_e32 v82, 1.0, v82
	v_cndmask_b32_e32 v104, v85, v104, vcc
	v_fma_f32 v85, -v105, v85, v84
	v_cmp_lt_f32_e32 vcc, 0, v85
	v_mul_f32_e32 v87, 0xbfb8aa3b, v87
	v_exp_f32_e32 v87, v87
	v_cndmask_b32_e32 v85, v104, v105, vcc
	v_mul_f32_e32 v104, 0x37800000, v85
	v_cndmask_b32_e64 v85, v85, v104, s[10:11]
	v_cmp_class_f32_e32 vcc, v84, v182
	v_add_f32_e32 v83, v83, v95
	v_mul_f32_e32 v83, 0xbfb8aa3b, v83
	v_cndmask_b32_e32 v84, v85, v84, vcc
	v_add_f32_e32 v85, 1.0, v86
	v_mul_f32_e32 v81, v81, v84
	v_mul_f32_e32 v81, v81, v106
	v_exp_f32_e32 v83, v83
	v_rcp_f32_e32 v84, v85
	s_nop 0
	v_mul_f32_e64 v111, v84, -v90
	v_mul_f32_e32 v84, -2.0, v111
	v_mul_f32_e32 v85, 0x3e4ccccd, v84
	v_fma_f32 v157, v84, s81, 1.0
	v_pk_mul_f32 v[104:105], v[84:85], v[156:157]
	v_mul_f32_e32 v112, 0x3eaaaaab, v84
	v_sub_f32_e32 v85, 1.0, v105
	v_fma_f32 v159, -v104, v85, 1.0
	v_mov_b32_e32 v85, v112
	v_pk_mul_f32 v[104:105], v[84:85], v[158:159]
	v_sub_f32_e32 v85, 1.0, v105
	v_fma_f32 v85, -v104, v85, 1.0
	v_mul_f32_e32 v84, v84, v85
	v_max_f32_e32 v84, 0, v84
	v_mul_f32_e32 v85, 0x4f800000, v84
	v_cmp_gt_f32_e64 s[10:11], s82, v84
	v_rcp_f32_e32 v82, v82
	v_add_f32_e32 v83, 1.0, v83
	v_cndmask_b32_e64 v84, v84, v85, s[10:11]
	v_sqrt_f32_e32 v85, v84
	v_cvt_pk_bf16_f32 v81, v114, v81
	v_add_u32_e32 v86, -1, v85
	v_fma_f32 v104, -v86, v85, v84
	v_cmp_ge_f32_e32 vcc, 0, v104
	v_add_u32_e32 v104, 1, v85
	s_nop 0
	v_cndmask_b32_e32 v86, v85, v86, vcc
	v_fma_f32 v85, -v104, v85, v84
	v_cmp_lt_f32_e32 vcc, 0, v85
	s_nop 1
	v_cndmask_b32_e32 v85, v86, v104, vcc
	v_mul_f32_e32 v86, 0x37800000, v85
	v_cndmask_b32_e64 v85, v85, v86, s[10:11]
	v_cmp_class_f32_e32 vcc, v84, v182
	s_nop 1
	v_cndmask_b32_e32 v84, v85, v84, vcc
	v_add_f32_e32 v85, 1.0, v87
	v_mul_f32_e32 v82, v82, v84
	v_mul_f32_e32 v82, v82, v107
	v_cvt_pk_bf16_f32 v82, v111, v82
	v_rcp_f32_e32 v84, v85
	s_nop 0
	v_mul_f32_e64 v107, v84, -v91
	v_mul_f32_e32 v84, -2.0, v107
	v_mul_f32_e32 v85, 0x3e4ccccd, v84
	v_fma_f32 v157, v84, s81, 1.0
	v_pk_mul_f32 v[86:87], v[84:85], v[156:157]
	v_mul_f32_e32 v110, 0x3eaaaaab, v84
	v_sub_f32_e32 v85, 1.0, v87
	v_fma_f32 v159, -v86, v85, 1.0
	v_mov_b32_e32 v85, v110
	v_pk_mul_f32 v[86:87], v[84:85], v[158:159]
	s_nop 0
	v_sub_f32_e32 v85, 1.0, v87
	v_fma_f32 v85, -v86, v85, 1.0
	v_mul_f32_e32 v84, v84, v85
	v_max_f32_e32 v84, 0, v84
	v_mul_f32_e32 v85, 0x4f800000, v84
	v_cmp_gt_f32_e64 s[10:11], s82, v84
	v_rcp_f32_e32 v83, v83
	s_nop 0
	v_cndmask_b32_e64 v84, v84, v85, s[10:11]
	v_sqrt_f32_e32 v85, v84
	s_nop 0
	v_add_u32_e32 v86, -1, v85
	v_fma_f32 v87, -v86, v85, v84
	v_cmp_ge_f32_e32 vcc, 0, v87
	v_add_u32_e32 v87, 1, v85
	s_nop 0
	v_cndmask_b32_e32 v86, v85, v86, vcc
	v_fma_f32 v85, -v87, v85, v84
	v_cmp_lt_f32_e32 vcc, 0, v85
	s_nop 1
	v_cndmask_b32_e32 v85, v86, v87, vcc
	v_mul_f32_e32 v86, 0x37800000, v85
	v_cndmask_b32_e64 v85, v85, v86, s[10:11]
	v_cmp_class_f32_e32 vcc, v84, v182
	s_nop 1
	v_cndmask_b32_e32 v84, v85, v84, vcc
	v_mul_f32_e32 v83, v83, v84
	v_mul_f32_e32 v83, v83, v113
	v_cvt_pk_bf16_f32 v83, v107, v83
	v_lshl_add_u64 v[84:85], v[102:103], 2, s[36:37]
	flat_store_dwordx4 v[84:85], v[80:83]
	s_nop 1
	v_lshl_add_u64 v[80:81], v[166:167], 0, s[46:47]
	v_lshl_add_u64 v[82:83], v[80:81], 0, v[160:161]
	v_lshl_add_u64 v[84:85], v[82:83], 1, s[16:17]
	flat_load_dwordx2 v[84:85], v[84:85]
	v_add_f32_e32 v76, v76, v96
	v_add_f32_e32 v77, v77, v97
	v_mul_f32_e32 v76, 0xbfb8aa3b, v76
	v_mul_f32_e32 v77, 0xbfb8aa3b, v77
	v_exp_f32_e32 v76, v76
	v_exp_f32_e32 v77, v77
	v_add_f32_e32 v72, v72, v92
	v_mul_f32_e32 v72, 0xbfb8aa3b, v72
	v_add_f32_e32 v76, 1.0, v76
	v_add_f32_e32 v102, 1.0, v77
	v_exp_f32_e32 v72, v72
	s_nop 0
	v_add_f32_e32 v72, 1.0, v72
	v_div_scale_f32 v87, s[10:11], v72, v72, 1.0
	v_rcp_f32_e32 v105, v87
	s_nop 0
	v_fma_f32 v111, -v87, v105, 1.0
	v_div_scale_f32 v107, s[10:11], 1.0, v72, 1.0
	v_fmac_f32_e32 v105, v111, v105
	v_rcp_f32_e32 v76, v76
	v_mul_f32_e32 v111, v107, v105
	v_mul_f32_e64 v104, v76, -v88
	v_fma_f32 v113, -v87, v111, v107
	v_mul_f32_e32 v76, -2.0, v104
	v_fmac_f32_e32 v111, v113, v105
	v_mul_f32_e32 v77, 0x3e4ccccd, v76
	v_fma_f32 v157, v76, s81, 1.0
	v_fma_f32 v107, -v87, v111, v107
	v_pk_mul_f32 v[86:87], v[76:77], v[156:157]
	v_mul_f32_e32 v110, 0x3eaaaaab, v76
	v_sub_f32_e32 v87, 1.0, v87
	v_mov_b32_e32 v77, v110
	v_fma_f32 v159, -v86, v87, 1.0
	v_pk_mul_f32 v[86:87], v[76:77], v[158:159]
	s_mov_b64 vcc, s[10:11]
	v_sub_f32_e32 v77, 1.0, v87
	v_fma_f32 v77, -v86, v77, 1.0
	v_mul_f32_e32 v76, v76, v77
	v_max_f32_e32 v76, 0, v76
	v_mul_f32_e32 v77, 0x4f800000, v76
	v_cmp_gt_f32_e64 s[12:13], s82, v76
	v_div_fmas_f32 v86, v107, v105, v111
	v_div_fixup_f32 v72, v86, v72, 1.0
	v_cndmask_b32_e64 v76, v76, v77, s[12:13]
	v_sqrt_f32_e32 v77, v76
	v_add_f32_e32 v73, v73, v93
	v_mul_f32_e32 v73, 0xbfb8aa3b, v73
	v_exp_f32_e32 v73, v73
	v_add_u32_e32 v86, -1, v77
	v_add_u32_e32 v87, 1, v77
	v_fma_f32 v105, -v86, v77, v76
	v_fma_f32 v107, -v87, v77, v76
	v_cmp_ge_f32_e32 vcc, 0, v105
	v_add_f32_e32 v73, 1.0, v73
	v_add_f32_e32 v78, v78, v98
	v_cndmask_b32_e32 v77, v77, v86, vcc
	v_cmp_lt_f32_e32 vcc, 0, v107
	v_mul_f32_e32 v78, 0xbfb8aa3b, v78
	v_exp_f32_e32 v78, v78
	v_cndmask_b32_e32 v77, v77, v87, vcc
	v_mul_f32_e32 v86, 0x37800000, v77
	v_cndmask_b32_e64 v77, v77, v86, s[12:13]
	v_cmp_class_f32_e32 vcc, v76, v182
	s_waitcnt vmcnt(0) lgkmcnt(0)
; DI unsigned pk2(float a, float b) { f32x2 v = {a, b}; bf16v2_t r = __builtin_convertvector(v, bf16v2_t); return __builtin_bit_cast(unsigned, r); }
; DI float sigm(float x) { return 1.f / (1.f + __expf(-x)); }
;     DI void operator()(const Acc& acc, const Unit& u, int wr, int wc, int fr, int fq, const float (&pre)[8]) const {
;     ...
;                 for (int m = 0; m < 4; ++m) { const size_t o = (size_t)(row0 + ai * HALF + m * 16) * DM + f0 + 4 * n;
;                     const u32x2 xw = *(const u32x2*)(xc + o);
;                     const float xv[4] = {__uint_as_float(xw.x << 16), __uint_as_float(xw.x & 0xffff0000u), __uint_as_float(xw.y << 16), __uint_as_float(xw.y & 0xffff0000u)};
;                     u32x4 w;
; #pragma unroll
;                     for (int e = 0; e < 4; ++e) { const float r = sigm(acc[ai][0][m][n][e] + br[e]), ig = sigm(acc[ai][1][m][n][e] + bi[e]);
;                         const float la = -sp[e] * r, uu = -2.f * la;
;                         const float om = uu * (1.f - uu * 0.5f * (1.f - uu * (1.f / 3.f) * (1.f - uu * 0.25f * (1.f - uu * 0.2f * (1.f - uu * (1.f / 6.f))))));
;                         w[e] = pk2(la, sqrtf(fmaxf(om, 0.f)) * ig * xv[e]); }
;                     *(u32x4*)(ax + o) = w; __builtin_amdgcn_sched_barrier(0); }
	v_and_b32_e32 v86, 0xffff0000, v84
	v_lshlrev_b32_e32 v87, 16, v85
	v_cndmask_b32_e32 v76, v77, v76, vcc
	v_mul_f32_e32 v72, v72, v76
	v_lshlrev_b32_e32 v76, 16, v84
	v_mul_f32_e32 v72, v72, v76
	v_rcp_f32_e32 v76, v102
	v_and_b32_e32 v105, 0xffff0000, v85
	v_mul_f32_e64 v106, v76, -v89
	v_mul_f32_e32 v76, -2.0, v106
	v_cvt_pk_bf16_f32 v72, v104, v72
	v_mul_f32_e32 v77, 0x3e4ccccd, v76
	v_fma_f32 v157, v76, s81, 1.0
	v_pk_mul_f32 v[84:85], v[76:77], v[156:157]
	v_mul_f32_e32 v107, 0x3eaaaaab, v76
	v_sub_f32_e32 v77, 1.0, v85
	v_fma_f32 v159, -v84, v77, 1.0
	v_mov_b32_e32 v77, v107
	v_pk_mul_f32 v[84:85], v[76:77], v[158:159]
	v_add_f32_e32 v74, v74, v94
	v_sub_f32_e32 v77, 1.0, v85
	v_fma_f32 v77, -v84, v77, 1.0
	v_mul_f32_e32 v76, v76, v77
	v_max_f32_e32 v76, 0, v76
	v_mul_f32_e32 v77, 0x4f800000, v76
	v_cmp_gt_f32_e64 s[10:11], s82, v76
	v_rcp_f32_e32 v73, v73
	s_nop 0
	v_cndmask_b32_e64 v76, v76, v77, s[10:11]
	v_sqrt_f32_e32 v77, v76
	v_mul_f32_e32 v74, 0xbfb8aa3b, v74
	v_exp_f32_e32 v74, v74
	v_add_f32_e32 v79, v79, v99
	v_add_u32_e32 v84, -1, v77
	v_fma_f32 v85, -v84, v77, v76
	v_cmp_ge_f32_e32 vcc, 0, v85
	v_add_u32_e32 v85, 1, v77
	v_add_f32_e32 v74, 1.0, v74
	v_cndmask_b32_e32 v84, v77, v84, vcc
	v_fma_f32 v77, -v85, v77, v76
	v_cmp_lt_f32_e32 vcc, 0, v77
	v_mul_f32_e32 v79, 0xbfb8aa3b, v79
	v_exp_f32_e32 v79, v79
	v_cndmask_b32_e32 v77, v84, v85, vcc
	v_mul_f32_e32 v84, 0x37800000, v77
	v_cndmask_b32_e64 v77, v77, v84, s[10:11]
	v_cmp_class_f32_e32 vcc, v76, v182
	v_add_f32_e32 v75, v75, v95
	v_mul_f32_e32 v75, 0xbfb8aa3b, v75
	v_cndmask_b32_e32 v76, v77, v76, vcc
	v_add_f32_e32 v77, 1.0, v78
	v_mul_f32_e32 v73, v73, v76
	v_mul_f32_e32 v73, v73, v86
	v_exp_f32_e32 v75, v75
	v_rcp_f32_e32 v76, v77
	s_nop 0
	v_mul_f32_e64 v103, v76, -v90
	v_mul_f32_e32 v76, -2.0, v103
	v_mul_f32_e32 v77, 0x3e4ccccd, v76
	v_fma_f32 v157, v76, s81, 1.0
	v_pk_mul_f32 v[84:85], v[76:77], v[156:157]
	v_mul_f32_e32 v104, 0x3eaaaaab, v76
	v_sub_f32_e32 v77, 1.0, v85
	v_fma_f32 v159, -v84, v77, 1.0
	v_mov_b32_e32 v77, v104
	v_pk_mul_f32 v[84:85], v[76:77], v[158:159]
	v_sub_f32_e32 v77, 1.0, v85
	v_fma_f32 v77, -v84, v77, 1.0
	v_mul_f32_e32 v76, v76, v77
	v_max_f32_e32 v76, 0, v76
	v_mul_f32_e32 v77, 0x4f800000, v76
	v_cmp_gt_f32_e64 s[10:11], s82, v76
	v_rcp_f32_e32 v74, v74
	v_add_f32_e32 v75, 1.0, v75
	v_cndmask_b32_e64 v76, v76, v77, s[10:11]
	v_sqrt_f32_e32 v77, v76
	v_cvt_pk_bf16_f32 v73, v106, v73
	v_add_u32_e32 v78, -1, v77
	v_fma_f32 v84, -v78, v77, v76
	v_cmp_ge_f32_e32 vcc, 0, v84
	v_add_u32_e32 v84, 1, v77
	s_nop 0
	v_cndmask_b32_e32 v78, v77, v78, vcc
	v_fma_f32 v77, -v84, v77, v76
	v_cmp_lt_f32_e32 vcc, 0, v77
	s_nop 1
	v_cndmask_b32_e32 v77, v78, v84, vcc
	v_mul_f32_e32 v78, 0x37800000, v77
	v_cndmask_b32_e64 v77, v77, v78, s[10:11]
	v_cmp_class_f32_e32 vcc, v76, v182
	s_nop 1
	v_cndmask_b32_e32 v76, v77, v76, vcc
	v_add_f32_e32 v77, 1.0, v79
	v_mul_f32_e32 v74, v74, v76
	v_mul_f32_e32 v74, v74, v87
	v_cvt_pk_bf16_f32 v74, v103, v74
	v_rcp_f32_e32 v76, v77
	s_nop 0
	v_mul_f32_e64 v87, v76, -v91
	v_mul_f32_e32 v76, -2.0, v87
	v_mul_f32_e32 v77, 0x3e4ccccd, v76
	v_fma_f32 v157, v76, s81, 1.0
	v_pk_mul_f32 v[78:79], v[76:77], v[156:157]
	v_mul_f32_e32 v102, 0x3eaaaaab, v76
	v_sub_f32_e32 v77, 1.0, v79
	v_fma_f32 v159, -v78, v77, 1.0
	v_mov_b32_e32 v77, v102
	v_pk_mul_f32 v[78:79], v[76:77], v[158:159]
	s_nop 0
	v_sub_f32_e32 v77, 1.0, v79
	v_fma_f32 v77, -v78, v77, 1.0
	v_mul_f32_e32 v76, v76, v77
	v_max_f32_e32 v76, 0, v76
	v_mul_f32_e32 v77, 0x4f800000, v76
	v_cmp_gt_f32_e64 s[10:11], s82, v76
	v_rcp_f32_e32 v75, v75
	s_nop 0
	v_cndmask_b32_e64 v76, v76, v77, s[10:11]
	v_sqrt_f32_e32 v77, v76
	s_nop 0
	v_add_u32_e32 v78, -1, v77
	v_fma_f32 v79, -v78, v77, v76
	v_cmp_ge_f32_e32 vcc, 0, v79
	v_add_u32_e32 v79, 1, v77
	s_nop 0
	v_cndmask_b32_e32 v78, v77, v78, vcc
	v_fma_f32 v77, -v79, v77, v76
	v_cmp_lt_f32_e32 vcc, 0, v77
	s_nop 1
	v_cndmask_b32_e32 v77, v78, v79, vcc
	v_mul_f32_e32 v78, 0x37800000, v77
	v_cndmask_b32_e64 v77, v77, v78, s[10:11]
	v_cmp_class_f32_e32 vcc, v76, v182
	s_nop 1
	v_cndmask_b32_e32 v76, v77, v76, vcc
	v_mul_f32_e32 v75, v75, v76
	v_mul_f32_e32 v75, v75, v105
	v_cvt_pk_bf16_f32 v75, v87, v75
	v_lshl_add_u64 v[76:77], v[82:83], 2, s[36:37]
	flat_store_dwordx4 v[76:77], v[72:75]
	s_nop 1
	v_lshl_add_u64 v[76:77], v[166:167], 0, s[48:49]
	s_nop 0
	v_lshl_add_u64 v[72:73], v[76:77], 0, v[160:161]
	v_lshl_add_u64 v[74:75], v[72:73], 1, s[16:17]
	flat_load_dwordx2 v[74:75], v[74:75]
	v_add_f32_e32 v68, v68, v96
	v_add_f32_e32 v69, v69, v97
	v_mul_f32_e32 v68, 0xbfb8aa3b, v68
	v_mul_f32_e32 v69, 0xbfb8aa3b, v69
	v_exp_f32_e32 v68, v68
	v_exp_f32_e32 v69, v69
	v_add_f32_e32 v64, v64, v92
	v_mul_f32_e32 v64, 0xbfb8aa3b, v64
	v_add_f32_e32 v68, 1.0, v68
	v_add_f32_e32 v82, 1.0, v69
	v_exp_f32_e32 v64, v64
	s_nop 0
	v_add_f32_e32 v64, 1.0, v64
	v_div_scale_f32 v79, s[10:11], v64, v64, 1.0
	v_rcp_f32_e32 v85, v79
	s_nop 0
	v_fma_f32 v96, -v79, v85, 1.0
	v_div_scale_f32 v87, s[10:11], 1.0, v64, 1.0
	v_fmac_f32_e32 v85, v96, v85
	v_rcp_f32_e32 v68, v68
	v_mul_f32_e32 v96, v87, v85
	v_mul_f32_e64 v84, v68, -v88
	v_fma_f32 v102, -v79, v96, v87
	v_mul_f32_e32 v68, -2.0, v84
	v_fmac_f32_e32 v96, v102, v85
	v_mul_f32_e32 v69, 0x3e4ccccd, v68
	v_fma_f32 v157, v68, s81, 1.0
	v_fma_f32 v87, -v79, v96, v87
	v_pk_mul_f32 v[78:79], v[68:69], v[156:157]
	v_mul_f32_e32 v88, 0x3eaaaaab, v68
	v_sub_f32_e32 v79, 1.0, v79
	v_mov_b32_e32 v69, v88
	v_fma_f32 v159, -v78, v79, 1.0
	v_pk_mul_f32 v[78:79], v[68:69], v[158:159]
	s_mov_b64 vcc, s[10:11]
	v_sub_f32_e32 v69, 1.0, v79
	v_fma_f32 v69, -v78, v69, 1.0
	v_mul_f32_e32 v68, v68, v69
	v_max_f32_e32 v68, 0, v68
	v_mul_f32_e32 v69, 0x4f800000, v68
	v_cmp_gt_f32_e64 s[12:13], s82, v68
	v_div_fmas_f32 v78, v87, v85, v96
	v_div_fixup_f32 v64, v78, v64, 1.0
	v_cndmask_b32_e64 v68, v68, v69, s[12:13]
	v_sqrt_f32_e32 v69, v68
	v_add_f32_e32 v65, v65, v93
	v_mul_f32_e32 v65, 0xbfb8aa3b, v65
	v_exp_f32_e32 v65, v65
	v_add_u32_e32 v78, -1, v69
	v_add_u32_e32 v79, 1, v69
	v_fma_f32 v85, -v78, v69, v68
	v_fma_f32 v87, -v79, v69, v68
	v_cmp_ge_f32_e32 vcc, 0, v85
	v_add_f32_e32 v65, 1.0, v65
	v_add_f32_e32 v70, v70, v98
	v_cndmask_b32_e32 v69, v69, v78, vcc
	v_cmp_lt_f32_e32 vcc, 0, v87
	v_mul_f32_e32 v70, 0xbfb8aa3b, v70
	v_exp_f32_e32 v70, v70
	v_cndmask_b32_e32 v69, v69, v79, vcc
	v_mul_f32_e32 v78, 0x37800000, v69
	v_cndmask_b32_e64 v69, v69, v78, s[12:13]
	v_cmp_class_f32_e32 vcc, v68, v182
	s_waitcnt vmcnt(0) lgkmcnt(0)
; DI unsigned pk2(float a, float b) { f32x2 v = {a, b}; bf16v2_t r = __builtin_convertvector(v, bf16v2_t); return __builtin_bit_cast(unsigned, r); }
; DI float sigm(float x) { return 1.f / (1.f + __expf(-x)); }
;     DI void operator()(const Acc& acc, const Unit& u, int wr, int wc, int fr, int fq, const float (&pre)[8]) const {
;     ...
;             const f32x4 br = *(const f32x4*)(brg + f0 + 4 * n), bi = *(const f32x4*)(big + f0 + 4 * n), sp = *(const f32x4*)(sp8t + f0 + 4 * n);
; #pragma unroll
;             for (int ai = 0; ai < 2; ++ai)
; #pragma unroll
;                 for (int m = 0; m < 4; ++m) { const size_t o = (size_t)(row0 + ai * HALF + m * 16) * DM + f0 + 4 * n;
;                     const u32x2 xw = *(const u32x2*)(xc + o);
;                     const float xv[4] = {__uint_as_float(xw.x << 16), __uint_as_float(xw.x & 0xffff0000u), __uint_as_float(xw.y << 16), __uint_as_float(xw.y & 0xffff0000u)};
;                     u32x4 w;
; #pragma unroll
;                     for (int e = 0; e < 4; ++e) { const float r = sigm(acc[ai][0][m][n][e] + br[e]), ig = sigm(acc[ai][1][m][n][e] + bi[e]);
;                         const float la = -sp[e] * r, uu = -2.f * la;
;                         const float om = uu * (1.f - uu * 0.5f * (1.f - uu * (1.f / 3.f) * (1.f - uu * 0.25f * (1.f - uu * 0.2f * (1.f - uu * (1.f / 6.f))))));
;                         w[e] = pk2(la, sqrtf(fmaxf(om, 0.f)) * ig * xv[e]); }
;                     *(u32x4*)(ax + o) = w; __builtin_amdgcn_sched_barrier(0); }
	v_and_b32_e32 v78, 0xffff0000, v74
	v_lshlrev_b32_e32 v79, 16, v75
	v_cndmask_b32_e32 v68, v69, v68, vcc
	v_mul_f32_e32 v64, v64, v68
	v_lshlrev_b32_e32 v68, 16, v74
	v_mul_f32_e32 v64, v64, v68
	v_rcp_f32_e32 v68, v82
	v_and_b32_e32 v85, 0xffff0000, v75
	v_mul_f32_e64 v86, v68, -v89
	v_mul_f32_e32 v68, -2.0, v86
	v_cvt_pk_bf16_f32 v64, v84, v64
	v_mul_f32_e32 v69, 0x3e4ccccd, v68
	v_fma_f32 v157, v68, s81, 1.0
	v_pk_mul_f32 v[74:75], v[68:69], v[156:157]
	v_mul_f32_e32 v87, 0x3eaaaaab, v68
	v_sub_f32_e32 v69, 1.0, v75
	v_fma_f32 v159, -v74, v69, 1.0
	v_mov_b32_e32 v69, v87
	v_pk_mul_f32 v[74:75], v[68:69], v[158:159]
	v_add_f32_e32 v66, v66, v94
	v_sub_f32_e32 v69, 1.0, v75
	v_fma_f32 v69, -v74, v69, 1.0
	v_mul_f32_e32 v68, v68, v69
	v_max_f32_e32 v68, 0, v68
	v_mul_f32_e32 v69, 0x4f800000, v68
	v_cmp_gt_f32_e64 s[10:11], s82, v68
	v_rcp_f32_e32 v65, v65
	s_nop 0
	v_cndmask_b32_e64 v68, v68, v69, s[10:11]
	v_sqrt_f32_e32 v69, v68
	v_mul_f32_e32 v66, 0xbfb8aa3b, v66
	v_exp_f32_e32 v66, v66
	v_add_f32_e32 v71, v71, v99
	v_add_u32_e32 v74, -1, v69
	v_fma_f32 v75, -v74, v69, v68
	v_cmp_ge_f32_e32 vcc, 0, v75
	v_add_u32_e32 v75, 1, v69
	v_add_f32_e32 v66, 1.0, v66
	v_cndmask_b32_e32 v74, v69, v74, vcc
	v_fma_f32 v69, -v75, v69, v68
	v_cmp_lt_f32_e32 vcc, 0, v69
	v_mul_f32_e32 v71, 0xbfb8aa3b, v71
	v_exp_f32_e32 v71, v71
	v_cndmask_b32_e32 v69, v74, v75, vcc
	v_mul_f32_e32 v74, 0x37800000, v69
	v_cndmask_b32_e64 v69, v69, v74, s[10:11]
	v_cmp_class_f32_e32 vcc, v68, v182
	v_add_f32_e32 v67, v67, v95
	v_mul_f32_e32 v67, 0xbfb8aa3b, v67
	v_cndmask_b32_e32 v68, v69, v68, vcc
	v_add_f32_e32 v69, 1.0, v70
	v_mul_f32_e32 v65, v65, v68
	v_mul_f32_e32 v65, v65, v78
	v_exp_f32_e32 v67, v67
	v_rcp_f32_e32 v68, v69
	s_nop 0
	v_mul_f32_e64 v83, v68, -v90
	v_mul_f32_e32 v68, -2.0, v83
	v_mul_f32_e32 v69, 0x3e4ccccd, v68
	v_fma_f32 v157, v68, s81, 1.0
	v_pk_mul_f32 v[74:75], v[68:69], v[156:157]
	v_mul_f32_e32 v84, 0x3eaaaaab, v68
	v_sub_f32_e32 v69, 1.0, v75
	v_fma_f32 v159, -v74, v69, 1.0
	v_mov_b32_e32 v69, v84
	v_pk_mul_f32 v[74:75], v[68:69], v[158:159]
	v_sub_f32_e32 v69, 1.0, v75
	v_fma_f32 v69, -v74, v69, 1.0
	v_mul_f32_e32 v68, v68, v69
	v_max_f32_e32 v68, 0, v68
	v_mul_f32_e32 v69, 0x4f800000, v68
	v_cmp_gt_f32_e64 s[10:11], s82, v68
	v_rcp_f32_e32 v66, v66
	v_add_f32_e32 v67, 1.0, v67
	v_cndmask_b32_e64 v68, v68, v69, s[10:11]
	v_sqrt_f32_e32 v69, v68
	v_cvt_pk_bf16_f32 v65, v86, v65
	v_add_u32_e32 v70, -1, v69
	v_fma_f32 v74, -v70, v69, v68
	v_cmp_ge_f32_e32 vcc, 0, v74
	v_add_u32_e32 v74, 1, v69
	s_nop 0
	v_cndmask_b32_e32 v70, v69, v70, vcc
	v_fma_f32 v69, -v74, v69, v68
	v_cmp_lt_f32_e32 vcc, 0, v69
	s_nop 1
	v_cndmask_b32_e32 v69, v70, v74, vcc
	v_mul_f32_e32 v70, 0x37800000, v69
	v_cndmask_b32_e64 v69, v69, v70, s[10:11]
	v_cmp_class_f32_e32 vcc, v68, v182
	s_nop 1
	v_cndmask_b32_e32 v68, v69, v68, vcc
	v_add_f32_e32 v69, 1.0, v71
	v_mul_f32_e32 v66, v66, v68
	v_mul_f32_e32 v66, v66, v79
	v_cvt_pk_bf16_f32 v66, v83, v66
	v_rcp_f32_e32 v68, v69
	s_nop 0
	v_mul_f32_e64 v79, v68, -v91
	v_mul_f32_e32 v68, -2.0, v79
	v_mul_f32_e32 v69, 0x3e4ccccd, v68
	v_fma_f32 v157, v68, s81, 1.0
	v_pk_mul_f32 v[70:71], v[68:69], v[156:157]
	v_mul_f32_e32 v82, 0x3eaaaaab, v68
	v_sub_f32_e32 v69, 1.0, v71
	v_fma_f32 v159, -v70, v69, 1.0
	v_mov_b32_e32 v69, v82
	v_pk_mul_f32 v[70:71], v[68:69], v[158:159]
	s_nop 0
	v_sub_f32_e32 v69, 1.0, v71
	v_fma_f32 v69, -v70, v69, 1.0
	v_mul_f32_e32 v68, v68, v69
	v_max_f32_e32 v68, 0, v68
	v_mul_f32_e32 v69, 0x4f800000, v68
	v_cmp_gt_f32_e64 s[10:11], s82, v68
	v_rcp_f32_e32 v67, v67
	s_nop 0
	v_cndmask_b32_e64 v68, v68, v69, s[10:11]
	v_sqrt_f32_e32 v69, v68
	s_nop 0
	v_add_u32_e32 v70, -1, v69
	v_fma_f32 v71, -v70, v69, v68
	v_cmp_ge_f32_e32 vcc, 0, v71
	v_add_u32_e32 v71, 1, v69
	s_nop 0
	v_cndmask_b32_e32 v70, v69, v70, vcc
	v_fma_f32 v69, -v71, v69, v68
	v_cmp_lt_f32_e32 vcc, 0, v69
	s_nop 1
	v_cndmask_b32_e32 v69, v70, v71, vcc
	v_mul_f32_e32 v70, 0x37800000, v69
	v_cndmask_b32_e64 v69, v69, v70, s[10:11]
	v_cmp_class_f32_e32 vcc, v68, v182
	s_nop 1
	v_cndmask_b32_e32 v68, v69, v68, vcc
	v_mul_f32_e32 v67, v67, v68
	v_mul_f32_e32 v67, v67, v85
	v_cvt_pk_bf16_f32 v67, v79, v67
	v_lshl_add_u64 v[68:69], v[72:73], 2, s[36:37]
	flat_store_dwordx4 v[68:69], v[64:67]
	global_load_dwordx4 v[72:75], v[162:163], off offset:16
	s_nop 0
	global_load_dwordx4 v[68:71], v[164:165], off offset:16
	v_or_b32_e32 v160, 4, v160
	v_lshl_add_u64 v[78:79], v[166:167], 0, v[160:161]
	v_lshl_add_u64 v[64:65], v[78:79], 1, s[16:17]
	flat_load_dwordx2 v[82:83], v[64:65]
	s_nop 0
	flat_load_dwordx4 v[64:67], v[168:169] offset:16
	s_waitcnt vmcnt(0)
	v_add_f32_e32 v60, v60, v72
	v_add_f32_e32 v57, v57, v69
	v_mul_f32_e32 v60, 0xbfb8aa3b, v60
	v_add_f32_e32 v56, v56, v68
	v_mul_f32_e32 v57, 0xbfb8aa3b, v57
	v_exp_f32_e32 v60, v60
	v_add_f32_e32 v61, v61, v73
	v_mul_f32_e32 v56, 0xbfb8aa3b, v56
	v_exp_f32_e32 v57, v57
	v_mul_f32_e32 v61, 0xbfb8aa3b, v61
	v_exp_f32_e32 v56, v56
	v_exp_f32_e32 v61, v61
	v_add_f32_e32 v60, 1.0, v60
	v_add_f32_e32 v90, 1.0, v57
	v_add_f32_e32 v56, 1.0, v56
	s_waitcnt lgkmcnt(0)
; DI unsigned pk2(float a, float b) { f32x2 v = {a, b}; bf16v2_t r = __builtin_convertvector(v, bf16v2_t); return __builtin_bit_cast(unsigned, r); }
; DI float sigm(float x) { return 1.f / (1.f + __expf(-x)); }
;     DI void operator()(const Acc& acc, const Unit& u, int wr, int wc, int fr, int fq, const float (&pre)[8]) const {
;     ...
;                 for (int m = 0; m < 4; ++m) { const size_t o = (size_t)(row0 + ai * HALF + m * 16) * DM + f0 + 4 * n;
;                     const u32x2 xw = *(const u32x2*)(xc + o);
;                     const float xv[4] = {__uint_as_float(xw.x << 16), __uint_as_float(xw.x & 0xffff0000u), __uint_as_float(xw.y << 16), __uint_as_float(xw.y & 0xffff0000u)};
;                     u32x4 w;
; #pragma unroll
;                     for (int e = 0; e < 4; ++e) { const float r = sigm(acc[ai][0][m][n][e] + br[e]), ig = sigm(acc[ai][1][m][n][e] + bi[e]);
;                         const float la = -sp[e] * r, uu = -2.f * la;
;                         const float om = uu * (1.f - uu * 0.5f * (1.f - uu * (1.f / 3.f) * (1.f - uu * 0.25f * (1.f - uu * 0.2f * (1.f - uu * (1.f / 6.f))))));
;                         w[e] = pk2(la, sqrtf(fmaxf(om, 0.f)) * ig * xv[e]); }
;                     *(u32x4*)(ax + o) = w; __builtin_amdgcn_sched_barrier(0); }
	v_lshlrev_b32_e32 v88, 16, v83
	v_and_b32_e32 v89, 0xffff0000, v83
	v_add_f32_e32 v61, 1.0, v61
	v_div_scale_f32 v83, s[10:11], v56, v56, 1.0
	v_div_scale_f32 v85, s[10:11], v61, v61, 1.0
	v_div_scale_f32 v92, s[10:11], v90, v90, 1.0
	v_rcp_f32_e32 v95, v83
	v_rcp_f32_e32 v96, v85
	v_rcp_f32_e32 v97, v92
	v_lshlrev_b32_e32 v86, 16, v82
	v_and_b32_e32 v87, 0xffff0000, v82
	v_fma_f32 v99, -v83, v95, 1.0
	v_div_scale_f32 v84, s[12:13], 1.0, v56, 1.0
	v_fma_f32 v102, -v85, v96, 1.0
	v_fma_f32 v103, -v92, v97, 1.0
	v_fmac_f32_e32 v95, v99, v95
	v_div_scale_f32 v91, s[14:15], 1.0, v61, 1.0
	v_div_scale_f32 v93, s[10:11], 1.0, v90, 1.0
	v_fmac_f32_e32 v96, v102, v96
	v_fmac_f32_e32 v97, v103, v97
	v_mul_f32_e32 v99, v84, v95
	v_mul_f32_e32 v102, v91, v96
	v_mul_f32_e32 v103, v93, v97
	v_fma_f32 v105, -v83, v99, v84
	v_fma_f32 v106, -v85, v102, v91
	v_fma_f32 v107, -v92, v103, v93
	v_fmac_f32_e32 v99, v105, v95
	v_fmac_f32_e32 v102, v106, v96
	v_fmac_f32_e32 v103, v107, v97
	v_fma_f32 v82, -v83, v99, v84
	v_rcp_f32_e32 v57, v60
	s_mov_b64 vcc, s[12:13]
	v_fma_f32 v83, -v85, v102, v91
	v_fma_f32 v91, -v92, v103, v93
	v_div_fmas_f32 v60, v82, v95, v99
	v_mul_f32_e64 v93, v57, -v64
	s_mov_b64 vcc, s[14:15]
	v_div_fixup_f32 v92, v60, v56, 1.0
	v_div_fmas_f32 v57, v83, v96, v102
	v_mul_f32_e32 v56, -2.0, v93
	v_div_fixup_f32 v60, v57, v61, 1.0
	v_mul_f32_e32 v57, 0x3e4ccccd, v56
	v_fma_f32 v157, v56, s81, 1.0
	v_mul_f32_e32 v82, 0x3eaaaaab, v56
	v_mul_f32_e64 v94, v60, -v65
	v_pk_mul_f32 v[60:61], v[56:57], v[156:157]
	v_mov_b32_e32 v57, v82
	v_mul_f32_e32 v82, -2.0, v94
	v_sub_f32_e32 v61, 1.0, v61
	v_mul_f32_e32 v84, 0x3eaaaaab, v82
	v_mul_f32_e32 v83, 0x3e4ccccd, v82
	v_fma_f32 v157, v82, s81, 1.0
	v_fma_f32 v159, -v60, v61, 1.0
	v_pk_mul_f32 v[60:61], v[82:83], v[156:157]
	v_mov_b32_e32 v83, v84
	v_pk_mul_f32 v[84:85], v[56:57], v[158:159]
	v_sub_f32_e32 v57, 1.0, v61
	v_sub_f32_e32 v61, 1.0, v85
	v_fma_f32 v159, -v60, v57, 1.0
	v_fma_f32 v57, -v84, v61, 1.0
	v_mul_f32_e32 v56, v56, v57
	v_pk_mul_f32 v[60:61], v[82:83], v[158:159]
	v_max_f32_e32 v56, 0, v56
	v_sub_f32_e32 v57, 1.0, v61
	v_mul_f32_e32 v61, 0x4f800000, v56
	v_cmp_gt_f32_e32 vcc, s82, v56
	v_fma_f32 v57, -v60, v57, 1.0
	v_mul_f32_e32 v57, v82, v57
	v_cndmask_b32_e32 v56, v56, v61, vcc
	v_sqrt_f32_e32 v61, v56
	v_max_f32_e32 v57, 0, v57
	v_add_f32_e32 v62, v62, v74
	v_mul_f32_e32 v62, 0xbfb8aa3b, v62
	v_add_u32_e32 v60, -1, v61
	v_add_u32_e32 v82, 1, v61
	v_fma_f32 v83, -v60, v61, v56
	v_fma_f32 v84, -v82, v61, v56
	v_cmp_ge_f32_e64 s[12:13], 0, v83
	v_exp_f32_e32 v62, v62
	v_add_f32_e32 v58, v58, v70
	v_cndmask_b32_e64 v60, v61, v60, s[12:13]
	v_cmp_lt_f32_e64 s[12:13], 0, v84
	v_mul_f32_e32 v58, 0xbfb8aa3b, v58
	v_exp_f32_e32 v58, v58
	v_cndmask_b32_e64 v60, v60, v82, s[12:13]
	v_mul_f32_e32 v61, 0x37800000, v60
	v_cndmask_b32_e32 v60, v60, v61, vcc
	v_cmp_class_f32_e32 vcc, v56, v182
	v_cmp_gt_f32_e64 s[12:13], s82, v57
	v_add_f32_e32 v58, 1.0, v58
	v_cndmask_b32_e32 v56, v60, v56, vcc
	v_mul_f32_e32 v60, 0x4f800000, v57
	v_cndmask_b32_e64 v57, v57, v60, s[12:13]
	v_sqrt_f32_e32 v60, v57
	s_mov_b64 vcc, s[10:11]
	v_div_fmas_f32 v61, v91, v97, v103
	v_div_fixup_f32 v61, v61, v90, 1.0
	v_add_u32_e32 v82, -1, v60
	v_fma_f32 v83, -v82, v60, v57
	v_cmp_ge_f32_e32 vcc, 0, v83
	v_add_u32_e32 v83, 1, v60
	v_mul_f32_e32 v56, v92, v56
	v_cndmask_b32_e32 v82, v60, v82, vcc
	v_fma_f32 v60, -v83, v60, v57
	v_cmp_lt_f32_e32 vcc, 0, v60
	v_mul_f32_e32 v56, v56, v86
	v_add_f32_e32 v63, v63, v75
	v_cndmask_b32_e32 v60, v82, v83, vcc
	v_mul_f32_e32 v82, 0x37800000, v60
	v_cndmask_b32_e64 v60, v60, v82, s[12:13]
	v_cmp_class_f32_e32 vcc, v57, v182
	v_mul_f32_e32 v63, 0xbfb8aa3b, v63
	v_exp_f32_e32 v63, v63
	v_cndmask_b32_e32 v57, v60, v57, vcc
	v_add_f32_e32 v60, 1.0, v62
	v_mul_f32_e32 v57, v61, v57
	v_mul_f32_e32 v57, v57, v87
	v_add_f32_e32 v59, v59, v71
	v_rcp_f32_e32 v60, v60
	s_nop 0
	v_mul_f32_e64 v86, v60, -v66
	v_mul_f32_e32 v60, -2.0, v86
	v_mul_f32_e32 v61, 0x3e4ccccd, v60
	v_fma_f32 v157, v60, s81, 1.0
	v_pk_mul_f32 v[82:83], v[60:61], v[156:157]
	v_mul_f32_e32 v87, 0x3eaaaaab, v60
	v_sub_f32_e32 v61, 1.0, v83
	v_fma_f32 v159, -v82, v61, 1.0
	v_mov_b32_e32 v61, v87
	v_pk_mul_f32 v[82:83], v[60:61], v[158:159]
	v_sub_f32_e32 v61, 1.0, v83
	v_fma_f32 v61, -v82, v61, 1.0
	v_mul_f32_e32 v60, v60, v61
	v_max_f32_e32 v60, 0, v60
	v_mul_f32_e32 v61, 0x4f800000, v60
	v_cmp_gt_f32_e64 s[10:11], s82, v60
	v_rcp_f32_e32 v58, v58
	v_mul_f32_e32 v59, 0xbfb8aa3b, v59
	v_cndmask_b32_e64 v60, v60, v61, s[10:11]
	v_sqrt_f32_e32 v61, v60
	v_exp_f32_e32 v59, v59
	v_cvt_pk_bf16_f32 v56, v93, v56
	v_cvt_pk_bf16_f32 v57, v94, v57
	v_add_u32_e32 v62, -1, v61
	v_fma_f32 v82, -v62, v61, v60
	v_cmp_ge_f32_e32 vcc, 0, v82
	v_add_u32_e32 v82, 1, v61
	v_add_f32_e32 v59, 1.0, v59
	v_cndmask_b32_e32 v62, v61, v62, vcc
	v_fma_f32 v61, -v82, v61, v60
	v_cmp_lt_f32_e32 vcc, 0, v61
	s_nop 1
	v_cndmask_b32_e32 v61, v62, v82, vcc
	v_mul_f32_e32 v62, 0x37800000, v61
	v_cndmask_b32_e64 v61, v61, v62, s[10:11]
	v_cmp_class_f32_e32 vcc, v60, v182
	s_nop 1
	v_cndmask_b32_e32 v60, v61, v60, vcc
	v_add_f32_e32 v61, 1.0, v63
	v_mul_f32_e32 v58, v58, v60
	v_mul_f32_e32 v58, v58, v88
	v_cvt_pk_bf16_f32 v58, v86, v58
	v_rcp_f32_e32 v60, v61
	s_nop 0
	v_mul_f32_e64 v85, v60, -v67
	v_mul_f32_e32 v60, -2.0, v85
	v_mul_f32_e32 v61, 0x3e4ccccd, v60
	v_fma_f32 v157, v60, s81, 1.0
	v_pk_mul_f32 v[62:63], v[60:61], v[156:157]
	v_mul_f32_e32 v86, 0x3eaaaaab, v60
	v_sub_f32_e32 v61, 1.0, v63
	v_fma_f32 v159, -v62, v61, 1.0
	v_mov_b32_e32 v61, v86
	v_pk_mul_f32 v[62:63], v[60:61], v[158:159]
	s_nop 0
	v_sub_f32_e32 v61, 1.0, v63
; DI unsigned pk2(float a, float b) { f32x2 v = {a, b}; bf16v2_t r = __builtin_convertvector(v, bf16v2_t); return __builtin_bit_cast(unsigned, r); }
; DI float sigm(float x) { return 1.f / (1.f + __expf(-x)); }
;     DI void operator()(const Acc& acc, const Unit& u, int wr, int wc, int fr, int fq, const float (&pre)[8]) const {
;     ...
;                 for (int m = 0; m < 4; ++m) { const size_t o = (size_t)(row0 + ai * HALF + m * 16) * DM + f0 + 4 * n;
;                     const u32x2 xw = *(const u32x2*)(xc + o);
;                     const float xv[4] = {__uint_as_float(xw.x << 16), __uint_as_float(xw.x & 0xffff0000u), __uint_as_float(xw.y << 16), __uint_as_float(xw.y & 0xffff0000u)};
;                     u32x4 w;
; #pragma unroll
;                     for (int e = 0; e < 4; ++e) { const float r = sigm(acc[ai][0][m][n][e] + br[e]), ig = sigm(acc[ai][1][m][n][e] + bi[e]);
;                         const float la = -sp[e] * r, uu = -2.f * la;
;                         const float om = uu * (1.f - uu * 0.5f * (1.f - uu * (1.f / 3.f) * (1.f - uu * 0.25f * (1.f - uu * 0.2f * (1.f - uu * (1.f / 6.f))))));
;                         w[e] = pk2(la, sqrtf(fmaxf(om, 0.f)) * ig * xv[e]); }
;                     *(u32x4*)(ax + o) = w; __builtin_amdgcn_sched_barrier(0); }
	v_fma_f32 v61, -v62, v61, 1.0
	v_mul_f32_e32 v60, v60, v61
	v_max_f32_e32 v60, 0, v60
	v_mul_f32_e32 v61, 0x4f800000, v60
	v_cmp_gt_f32_e64 s[10:11], s82, v60
	v_rcp_f32_e32 v59, v59
	s_nop 0
	v_cndmask_b32_e64 v60, v60, v61, s[10:11]
	v_sqrt_f32_e32 v61, v60
	s_nop 0
	v_add_u32_e32 v62, -1, v61
	v_fma_f32 v63, -v62, v61, v60
	v_cmp_ge_f32_e32 vcc, 0, v63
	v_add_u32_e32 v63, 1, v61
	s_nop 0
	v_cndmask_b32_e32 v62, v61, v62, vcc
	v_fma_f32 v61, -v63, v61, v60
	v_cmp_lt_f32_e32 vcc, 0, v61
	s_nop 1
	v_cndmask_b32_e32 v61, v62, v63, vcc
	v_mul_f32_e32 v62, 0x37800000, v61
	v_cndmask_b32_e64 v61, v61, v62, s[10:11]
	v_cmp_class_f32_e32 vcc, v60, v182
	s_nop 1
	v_cndmask_b32_e32 v60, v61, v60, vcc
	v_mul_f32_e32 v59, v59, v60
	v_mul_f32_e32 v59, v59, v89
	v_cvt_pk_bf16_f32 v59, v85, v59
	v_lshl_add_u64 v[60:61], v[78:79], 2, s[36:37]
	flat_store_dwordx4 v[60:61], v[56:59]
	s_nop 1
	v_lshl_add_u64 v[56:57], v[132:133], 0, v[160:161]
	v_lshl_add_u64 v[58:59], v[56:57], 1, s[16:17]
	flat_load_dwordx2 v[58:59], v[58:59]
	v_add_f32_e32 v52, v52, v72
	v_add_f32_e32 v53, v53, v73
	v_mul_f32_e32 v52, 0xbfb8aa3b, v52
	v_mul_f32_e32 v53, 0xbfb8aa3b, v53
	v_exp_f32_e32 v52, v52
	v_exp_f32_e32 v53, v53
	v_add_f32_e32 v48, v48, v68
	v_mul_f32_e32 v48, 0xbfb8aa3b, v48
	v_add_f32_e32 v52, 1.0, v52
	v_add_f32_e32 v62, 1.0, v53
	v_exp_f32_e32 v48, v48
	s_nop 0
	v_add_f32_e32 v48, 1.0, v48
	v_div_scale_f32 v61, s[10:11], v48, v48, 1.0
	v_rcp_f32_e32 v79, v61
	s_nop 0
	v_fma_f32 v85, -v61, v79, 1.0
	v_div_scale_f32 v83, s[10:11], 1.0, v48, 1.0
	v_fmac_f32_e32 v79, v85, v79
	v_rcp_f32_e32 v52, v52
	v_mul_f32_e32 v85, v83, v79
	v_mul_f32_e64 v78, v52, -v64
	v_fma_f32 v87, -v61, v85, v83
	v_mul_f32_e32 v52, -2.0, v78
	v_fmac_f32_e32 v85, v87, v79
	v_mul_f32_e32 v53, 0x3e4ccccd, v52
	v_fma_f32 v157, v52, s81, 1.0
	v_fma_f32 v83, -v61, v85, v83
	v_pk_mul_f32 v[60:61], v[52:53], v[156:157]
	v_mul_f32_e32 v84, 0x3eaaaaab, v52
	v_sub_f32_e32 v61, 1.0, v61
	v_mov_b32_e32 v53, v84
	v_fma_f32 v159, -v60, v61, 1.0
	v_pk_mul_f32 v[60:61], v[52:53], v[158:159]
	s_mov_b64 vcc, s[10:11]
	v_sub_f32_e32 v53, 1.0, v61
	v_fma_f32 v53, -v60, v53, 1.0
	v_mul_f32_e32 v52, v52, v53
	v_max_f32_e32 v52, 0, v52
	v_mul_f32_e32 v53, 0x4f800000, v52
	v_cmp_gt_f32_e64 s[12:13], s82, v52
	v_div_fmas_f32 v60, v83, v79, v85
	v_div_fixup_f32 v48, v60, v48, 1.0
	v_cndmask_b32_e64 v52, v52, v53, s[12:13]
	v_sqrt_f32_e32 v53, v52
	v_add_f32_e32 v49, v49, v69
	v_mul_f32_e32 v49, 0xbfb8aa3b, v49
	v_exp_f32_e32 v49, v49
	v_add_u32_e32 v60, -1, v53
	v_add_u32_e32 v61, 1, v53
	v_fma_f32 v79, -v60, v53, v52
	v_fma_f32 v83, -v61, v53, v52
	v_cmp_ge_f32_e32 vcc, 0, v79
	v_add_f32_e32 v49, 1.0, v49
	v_add_f32_e32 v54, v54, v74
	v_cndmask_b32_e32 v53, v53, v60, vcc
	v_cmp_lt_f32_e32 vcc, 0, v83
	v_mul_f32_e32 v54, 0xbfb8aa3b, v54
	v_exp_f32_e32 v54, v54
	v_cndmask_b32_e32 v53, v53, v61, vcc
	v_mul_f32_e32 v60, 0x37800000, v53
	v_cndmask_b32_e64 v53, v53, v60, s[12:13]
	v_cmp_class_f32_e32 vcc, v52, v182
	s_waitcnt vmcnt(0) lgkmcnt(0)
	v_and_b32_e32 v60, 0xffff0000, v58
	v_lshlrev_b32_e32 v61, 16, v59
	v_cndmask_b32_e32 v52, v53, v52, vcc
	v_mul_f32_e32 v48, v48, v52
	v_lshlrev_b32_e32 v52, 16, v58
	v_mul_f32_e32 v48, v48, v52
	v_rcp_f32_e32 v52, v62
	v_and_b32_e32 v79, 0xffff0000, v59
	v_mul_f32_e64 v82, v52, -v65
	v_mul_f32_e32 v52, -2.0, v82
	v_cvt_pk_bf16_f32 v48, v78, v48
	v_mul_f32_e32 v53, 0x3e4ccccd, v52
	v_fma_f32 v157, v52, s81, 1.0
	v_pk_mul_f32 v[58:59], v[52:53], v[156:157]
	v_mul_f32_e32 v83, 0x3eaaaaab, v52
	v_sub_f32_e32 v53, 1.0, v59
	v_fma_f32 v159, -v58, v53, 1.0
	v_mov_b32_e32 v53, v83
	v_pk_mul_f32 v[58:59], v[52:53], v[158:159]
	v_add_f32_e32 v50, v50, v70
	v_sub_f32_e32 v53, 1.0, v59
	v_fma_f32 v53, -v58, v53, 1.0
	v_mul_f32_e32 v52, v52, v53
	v_max_f32_e32 v52, 0, v52
	v_mul_f32_e32 v53, 0x4f800000, v52
	v_cmp_gt_f32_e64 s[10:11], s82, v52
	v_rcp_f32_e32 v49, v49
	s_nop 0
	v_cndmask_b32_e64 v52, v52, v53, s[10:11]
	v_sqrt_f32_e32 v53, v52
	v_mul_f32_e32 v50, 0xbfb8aa3b, v50
	v_exp_f32_e32 v50, v50
	v_add_f32_e32 v55, v55, v75
	v_add_u32_e32 v58, -1, v53
	v_fma_f32 v59, -v58, v53, v52
	v_cmp_ge_f32_e32 vcc, 0, v59
	v_add_u32_e32 v59, 1, v53
	v_add_f32_e32 v50, 1.0, v50
	v_cndmask_b32_e32 v58, v53, v58, vcc
	v_fma_f32 v53, -v59, v53, v52
	v_cmp_lt_f32_e32 vcc, 0, v53
	v_mul_f32_e32 v55, 0xbfb8aa3b, v55
	v_exp_f32_e32 v55, v55
	v_cndmask_b32_e32 v53, v58, v59, vcc
	v_mul_f32_e32 v58, 0x37800000, v53
	v_cndmask_b32_e64 v53, v53, v58, s[10:11]
	v_cmp_class_f32_e32 vcc, v52, v182
	v_add_f32_e32 v51, v51, v71
	v_mul_f32_e32 v51, 0xbfb8aa3b, v51
	v_cndmask_b32_e32 v52, v53, v52, vcc
	v_add_f32_e32 v53, 1.0, v54
	v_mul_f32_e32 v49, v49, v52
	v_mul_f32_e32 v49, v49, v60
	v_exp_f32_e32 v51, v51
	v_rcp_f32_e32 v52, v53
	s_nop 0
	v_mul_f32_e64 v63, v52, -v66
	v_mul_f32_e32 v52, -2.0, v63
	v_mul_f32_e32 v53, 0x3e4ccccd, v52
	v_fma_f32 v157, v52, s81, 1.0
	v_pk_mul_f32 v[58:59], v[52:53], v[156:157]
	v_mul_f32_e32 v78, 0x3eaaaaab, v52
	v_sub_f32_e32 v53, 1.0, v59
	v_fma_f32 v159, -v58, v53, 1.0
	v_mov_b32_e32 v53, v78
	v_pk_mul_f32 v[58:59], v[52:53], v[158:159]
	v_sub_f32_e32 v53, 1.0, v59
	v_fma_f32 v53, -v58, v53, 1.0
	v_mul_f32_e32 v52, v52, v53
	v_max_f32_e32 v52, 0, v52
	v_mul_f32_e32 v53, 0x4f800000, v52
	v_cmp_gt_f32_e64 s[10:11], s82, v52
	v_rcp_f32_e32 v50, v50
	v_add_f32_e32 v51, 1.0, v51
	v_cndmask_b32_e64 v52, v52, v53, s[10:11]
	v_sqrt_f32_e32 v53, v52
	v_cvt_pk_bf16_f32 v49, v82, v49
	v_add_u32_e32 v54, -1, v53
	v_fma_f32 v58, -v54, v53, v52
	v_cmp_ge_f32_e32 vcc, 0, v58
	v_add_u32_e32 v58, 1, v53
	s_nop 0
	v_cndmask_b32_e32 v54, v53, v54, vcc
	v_fma_f32 v53, -v58, v53, v52
; DI unsigned pk2(float a, float b) { f32x2 v = {a, b}; bf16v2_t r = __builtin_convertvector(v, bf16v2_t); return __builtin_bit_cast(unsigned, r); }
; DI float sigm(float x) { return 1.f / (1.f + __expf(-x)); }
;     DI void operator()(const Acc& acc, const Unit& u, int wr, int wc, int fr, int fq, const float (&pre)[8]) const {
;     ...
;                 for (int m = 0; m < 4; ++m) { const size_t o = (size_t)(row0 + ai * HALF + m * 16) * DM + f0 + 4 * n;
;                     const u32x2 xw = *(const u32x2*)(xc + o);
;                     const float xv[4] = {__uint_as_float(xw.x << 16), __uint_as_float(xw.x & 0xffff0000u), __uint_as_float(xw.y << 16), __uint_as_float(xw.y & 0xffff0000u)};
;                     u32x4 w;
; #pragma unroll
;                     for (int e = 0; e < 4; ++e) { const float r = sigm(acc[ai][0][m][n][e] + br[e]), ig = sigm(acc[ai][1][m][n][e] + bi[e]);
;                         const float la = -sp[e] * r, uu = -2.f * la;
;                         const float om = uu * (1.f - uu * 0.5f * (1.f - uu * (1.f / 3.f) * (1.f - uu * 0.25f * (1.f - uu * 0.2f * (1.f - uu * (1.f / 6.f))))));
;                         w[e] = pk2(la, sqrtf(fmaxf(om, 0.f)) * ig * xv[e]); }
;                     *(u32x4*)(ax + o) = w; __builtin_amdgcn_sched_barrier(0); }
	v_cmp_lt_f32_e32 vcc, 0, v53
	s_nop 1
	v_cndmask_b32_e32 v53, v54, v58, vcc
	v_mul_f32_e32 v54, 0x37800000, v53
	v_cndmask_b32_e64 v53, v53, v54, s[10:11]
	v_cmp_class_f32_e32 vcc, v52, v182
	s_nop 1
	v_cndmask_b32_e32 v52, v53, v52, vcc
	v_add_f32_e32 v53, 1.0, v55
	v_mul_f32_e32 v50, v50, v52
	v_mul_f32_e32 v50, v50, v61
	v_cvt_pk_bf16_f32 v50, v63, v50
	v_rcp_f32_e32 v52, v53
	s_nop 0
	v_mul_f32_e64 v61, v52, -v67
	v_mul_f32_e32 v52, -2.0, v61
	v_mul_f32_e32 v53, 0x3e4ccccd, v52
	v_fma_f32 v157, v52, s81, 1.0
	v_pk_mul_f32 v[54:55], v[52:53], v[156:157]
	v_mul_f32_e32 v62, 0x3eaaaaab, v52
	v_sub_f32_e32 v53, 1.0, v55
	v_fma_f32 v159, -v54, v53, 1.0
	v_mov_b32_e32 v53, v62
	v_pk_mul_f32 v[54:55], v[52:53], v[158:159]
	s_nop 0
	v_sub_f32_e32 v53, 1.0, v55
	v_fma_f32 v53, -v54, v53, 1.0
	v_mul_f32_e32 v52, v52, v53
	v_max_f32_e32 v52, 0, v52
	v_mul_f32_e32 v53, 0x4f800000, v52
	v_cmp_gt_f32_e64 s[10:11], s82, v52
	v_rcp_f32_e32 v51, v51
	s_nop 0
	v_cndmask_b32_e64 v52, v52, v53, s[10:11]
	v_sqrt_f32_e32 v53, v52
	s_nop 0
	v_add_u32_e32 v54, -1, v53
	v_fma_f32 v55, -v54, v53, v52
	v_cmp_ge_f32_e32 vcc, 0, v55
	v_add_u32_e32 v55, 1, v53
	s_nop 0
	v_cndmask_b32_e32 v54, v53, v54, vcc
	v_fma_f32 v53, -v55, v53, v52
	v_cmp_lt_f32_e32 vcc, 0, v53
	s_nop 1
	v_cndmask_b32_e32 v53, v54, v55, vcc
	v_mul_f32_e32 v54, 0x37800000, v53
	v_cndmask_b32_e64 v53, v53, v54, s[10:11]
	v_cmp_class_f32_e32 vcc, v52, v182
	s_nop 1
	v_cndmask_b32_e32 v52, v53, v52, vcc
	v_mul_f32_e32 v51, v51, v52
	v_mul_f32_e32 v51, v51, v79
	v_cvt_pk_bf16_f32 v51, v61, v51
	v_lshl_add_u64 v[52:53], v[56:57], 2, s[36:37]
	flat_store_dwordx4 v[52:53], v[48:51]
	s_nop 1
	v_lshl_add_u64 v[48:49], v[124:125], 0, v[160:161]
	v_lshl_add_u64 v[50:51], v[48:49], 1, s[16:17]
	flat_load_dwordx2 v[50:51], v[50:51]
	v_add_f32_e32 v44, v44, v72
	v_add_f32_e32 v45, v45, v73
	v_mul_f32_e32 v44, 0xbfb8aa3b, v44
	v_mul_f32_e32 v45, 0xbfb8aa3b, v45
	v_exp_f32_e32 v44, v44
	v_exp_f32_e32 v45, v45
	v_add_f32_e32 v40, v40, v68
	v_mul_f32_e32 v40, 0xbfb8aa3b, v40
	v_add_f32_e32 v44, 1.0, v44
	v_add_f32_e32 v54, 1.0, v45
	v_exp_f32_e32 v40, v40
	s_nop 0
	v_add_f32_e32 v40, 1.0, v40
	v_div_scale_f32 v53, s[10:11], v40, v40, 1.0
	v_rcp_f32_e32 v57, v53
	s_nop 0
	v_fma_f32 v61, -v53, v57, 1.0
	v_div_scale_f32 v59, s[10:11], 1.0, v40, 1.0
	v_fmac_f32_e32 v57, v61, v57
	v_rcp_f32_e32 v44, v44
	v_mul_f32_e32 v61, v59, v57
	v_mul_f32_e64 v56, v44, -v64
	v_fma_f32 v63, -v53, v61, v59
	v_mul_f32_e32 v44, -2.0, v56
	v_fmac_f32_e32 v61, v63, v57
	v_mul_f32_e32 v45, 0x3e4ccccd, v44
	v_fma_f32 v157, v44, s81, 1.0
	v_fma_f32 v59, -v53, v61, v59
	v_pk_mul_f32 v[52:53], v[44:45], v[156:157]
	v_mul_f32_e32 v60, 0x3eaaaaab, v44
	v_sub_f32_e32 v53, 1.0, v53
	v_mov_b32_e32 v45, v60
	v_fma_f32 v159, -v52, v53, 1.0
	v_pk_mul_f32 v[52:53], v[44:45], v[158:159]
	s_mov_b64 vcc, s[10:11]
	v_sub_f32_e32 v45, 1.0, v53
	v_fma_f32 v45, -v52, v45, 1.0
	v_mul_f32_e32 v44, v44, v45
	v_max_f32_e32 v44, 0, v44
	v_mul_f32_e32 v45, 0x4f800000, v44
	v_cmp_gt_f32_e64 s[12:13], s82, v44
	v_div_fmas_f32 v52, v59, v57, v61
	v_div_fixup_f32 v40, v52, v40, 1.0
	v_cndmask_b32_e64 v44, v44, v45, s[12:13]
	v_sqrt_f32_e32 v45, v44
	v_add_f32_e32 v41, v41, v69
	v_mul_f32_e32 v41, 0xbfb8aa3b, v41
	v_exp_f32_e32 v41, v41
	v_add_u32_e32 v52, -1, v45
	v_add_u32_e32 v53, 1, v45
	v_fma_f32 v57, -v52, v45, v44
	v_fma_f32 v59, -v53, v45, v44
	v_cmp_ge_f32_e32 vcc, 0, v57
	v_add_f32_e32 v41, 1.0, v41
	v_add_f32_e32 v46, v46, v74
	v_cndmask_b32_e32 v45, v45, v52, vcc
	v_cmp_lt_f32_e32 vcc, 0, v59
	v_mul_f32_e32 v46, 0xbfb8aa3b, v46
	v_exp_f32_e32 v46, v46
	v_cndmask_b32_e32 v45, v45, v53, vcc
	v_mul_f32_e32 v52, 0x37800000, v45
	v_cndmask_b32_e64 v45, v45, v52, s[12:13]
	v_cmp_class_f32_e32 vcc, v44, v182
	s_waitcnt vmcnt(0) lgkmcnt(0)
	v_and_b32_e32 v52, 0xffff0000, v50
	v_lshlrev_b32_e32 v53, 16, v51
	v_cndmask_b32_e32 v44, v45, v44, vcc
	v_mul_f32_e32 v40, v40, v44
	v_lshlrev_b32_e32 v44, 16, v50
	v_mul_f32_e32 v40, v40, v44
	v_rcp_f32_e32 v44, v54
	v_and_b32_e32 v57, 0xffff0000, v51
	v_mul_f32_e64 v58, v44, -v65
	v_mul_f32_e32 v44, -2.0, v58
	v_cvt_pk_bf16_f32 v40, v56, v40
	v_mul_f32_e32 v45, 0x3e4ccccd, v44
	v_fma_f32 v157, v44, s81, 1.0
	v_pk_mul_f32 v[50:51], v[44:45], v[156:157]
	v_mul_f32_e32 v59, 0x3eaaaaab, v44
	v_sub_f32_e32 v45, 1.0, v51
	v_fma_f32 v159, -v50, v45, 1.0
	v_mov_b32_e32 v45, v59
	v_pk_mul_f32 v[50:51], v[44:45], v[158:159]
	v_add_f32_e32 v42, v42, v70
	v_sub_f32_e32 v45, 1.0, v51
	v_fma_f32 v45, -v50, v45, 1.0
	v_mul_f32_e32 v44, v44, v45
	v_max_f32_e32 v44, 0, v44
	v_mul_f32_e32 v45, 0x4f800000, v44
	v_cmp_gt_f32_e64 s[10:11], s82, v44
	v_rcp_f32_e32 v41, v41
	s_nop 0
	v_cndmask_b32_e64 v44, v44, v45, s[10:11]
	v_sqrt_f32_e32 v45, v44
	v_mul_f32_e32 v42, 0xbfb8aa3b, v42
	v_exp_f32_e32 v42, v42
	v_add_f32_e32 v47, v47, v75
	v_add_u32_e32 v50, -1, v45
	v_fma_f32 v51, -v50, v45, v44
	v_cmp_ge_f32_e32 vcc, 0, v51
	v_add_u32_e32 v51, 1, v45
	v_add_f32_e32 v42, 1.0, v42
	v_cndmask_b32_e32 v50, v45, v50, vcc
	v_fma_f32 v45, -v51, v45, v44
	v_cmp_lt_f32_e32 vcc, 0, v45
	v_mul_f32_e32 v47, 0xbfb8aa3b, v47
	v_exp_f32_e32 v47, v47
	v_cndmask_b32_e32 v45, v50, v51, vcc
	v_mul_f32_e32 v50, 0x37800000, v45
	v_cndmask_b32_e64 v45, v45, v50, s[10:11]
	v_cmp_class_f32_e32 vcc, v44, v182
	v_add_f32_e32 v43, v43, v71
	v_mul_f32_e32 v43, 0xbfb8aa3b, v43
	v_cndmask_b32_e32 v44, v45, v44, vcc
	v_add_f32_e32 v45, 1.0, v46
	v_mul_f32_e32 v41, v41, v44
	v_mul_f32_e32 v41, v41, v52
	v_exp_f32_e32 v43, v43
	v_rcp_f32_e32 v44, v45
	s_nop 0
	v_mul_f32_e64 v55, v44, -v66
	v_mul_f32_e32 v44, -2.0, v55
	v_mul_f32_e32 v45, 0x3e4ccccd, v44
	v_fma_f32 v157, v44, s81, 1.0
; DI unsigned pk2(float a, float b) { f32x2 v = {a, b}; bf16v2_t r = __builtin_convertvector(v, bf16v2_t); return __builtin_bit_cast(unsigned, r); }
; DI float sigm(float x) { return 1.f / (1.f + __expf(-x)); }
;     DI void operator()(const Acc& acc, const Unit& u, int wr, int wc, int fr, int fq, const float (&pre)[8]) const {
;     ...
;                 for (int m = 0; m < 4; ++m) { const size_t o = (size_t)(row0 + ai * HALF + m * 16) * DM + f0 + 4 * n;
;                     const u32x2 xw = *(const u32x2*)(xc + o);
;                     const float xv[4] = {__uint_as_float(xw.x << 16), __uint_as_float(xw.x & 0xffff0000u), __uint_as_float(xw.y << 16), __uint_as_float(xw.y & 0xffff0000u)};
;                     u32x4 w;
; #pragma unroll
;                     for (int e = 0; e < 4; ++e) { const float r = sigm(acc[ai][0][m][n][e] + br[e]), ig = sigm(acc[ai][1][m][n][e] + bi[e]);
;                         const float la = -sp[e] * r, uu = -2.f * la;
;                         const float om = uu * (1.f - uu * 0.5f * (1.f - uu * (1.f / 3.f) * (1.f - uu * 0.25f * (1.f - uu * 0.2f * (1.f - uu * (1.f / 6.f))))));
;                         w[e] = pk2(la, sqrtf(fmaxf(om, 0.f)) * ig * xv[e]); }
;                     *(u32x4*)(ax + o) = w; __builtin_amdgcn_sched_barrier(0); }
	v_pk_mul_f32 v[50:51], v[44:45], v[156:157]
	v_mul_f32_e32 v56, 0x3eaaaaab, v44
	v_sub_f32_e32 v45, 1.0, v51
	v_fma_f32 v159, -v50, v45, 1.0
	v_mov_b32_e32 v45, v56
	v_pk_mul_f32 v[50:51], v[44:45], v[158:159]
	v_sub_f32_e32 v45, 1.0, v51
	v_fma_f32 v45, -v50, v45, 1.0
	v_mul_f32_e32 v44, v44, v45
	v_max_f32_e32 v44, 0, v44
	v_mul_f32_e32 v45, 0x4f800000, v44
	v_cmp_gt_f32_e64 s[10:11], s82, v44
	v_rcp_f32_e32 v42, v42
	v_add_f32_e32 v43, 1.0, v43
	v_cndmask_b32_e64 v44, v44, v45, s[10:11]
	v_sqrt_f32_e32 v45, v44
	v_cvt_pk_bf16_f32 v41, v58, v41
	v_add_u32_e32 v46, -1, v45
	v_fma_f32 v50, -v46, v45, v44
	v_cmp_ge_f32_e32 vcc, 0, v50
	v_add_u32_e32 v50, 1, v45
	s_nop 0
	v_cndmask_b32_e32 v46, v45, v46, vcc
	v_fma_f32 v45, -v50, v45, v44
	v_cmp_lt_f32_e32 vcc, 0, v45
	s_nop 1
	v_cndmask_b32_e32 v45, v46, v50, vcc
	v_mul_f32_e32 v46, 0x37800000, v45
	v_cndmask_b32_e64 v45, v45, v46, s[10:11]
	v_cmp_class_f32_e32 vcc, v44, v182
	s_nop 1
	v_cndmask_b32_e32 v44, v45, v44, vcc
	v_add_f32_e32 v45, 1.0, v47
	v_mul_f32_e32 v42, v42, v44
	v_mul_f32_e32 v42, v42, v53
	v_cvt_pk_bf16_f32 v42, v55, v42
	v_rcp_f32_e32 v44, v45
	s_nop 0
	v_mul_f32_e64 v53, v44, -v67
	v_mul_f32_e32 v44, -2.0, v53
	v_mul_f32_e32 v45, 0x3e4ccccd, v44
	v_fma_f32 v157, v44, s81, 1.0
	v_pk_mul_f32 v[46:47], v[44:45], v[156:157]
	v_mul_f32_e32 v54, 0x3eaaaaab, v44
	v_sub_f32_e32 v45, 1.0, v47
	v_fma_f32 v159, -v46, v45, 1.0
	v_mov_b32_e32 v45, v54
	v_pk_mul_f32 v[46:47], v[44:45], v[158:159]
	s_nop 0
	v_sub_f32_e32 v45, 1.0, v47
	v_fma_f32 v45, -v46, v45, 1.0
	v_mul_f32_e32 v44, v44, v45
	v_max_f32_e32 v44, 0, v44
	v_mul_f32_e32 v45, 0x4f800000, v44
	v_cmp_gt_f32_e64 s[10:11], s82, v44
	v_rcp_f32_e32 v43, v43
	s_nop 0
	v_cndmask_b32_e64 v44, v44, v45, s[10:11]
	v_sqrt_f32_e32 v45, v44
	s_nop 0
	v_add_u32_e32 v46, -1, v45
	v_fma_f32 v47, -v46, v45, v44
	v_cmp_ge_f32_e32 vcc, 0, v47
	v_add_u32_e32 v47, 1, v45
	s_nop 0
	v_cndmask_b32_e32 v46, v45, v46, vcc
	v_fma_f32 v45, -v47, v45, v44
	v_cmp_lt_f32_e32 vcc, 0, v45
	s_nop 1
	v_cndmask_b32_e32 v45, v46, v47, vcc
	v_mul_f32_e32 v46, 0x37800000, v45
	v_cndmask_b32_e64 v45, v45, v46, s[10:11]
	v_cmp_class_f32_e32 vcc, v44, v182
	s_nop 1
	v_cndmask_b32_e32 v44, v45, v44, vcc
	v_mul_f32_e32 v43, v43, v44
	v_mul_f32_e32 v43, v43, v57
	v_cvt_pk_bf16_f32 v43, v53, v43
	v_lshl_add_u64 v[44:45], v[48:49], 2, s[36:37]
	flat_store_dwordx4 v[44:45], v[40:43]
	s_nop 1
	v_lshl_add_u64 v[40:41], v[116:117], 0, v[160:161]
	v_lshl_add_u64 v[42:43], v[40:41], 1, s[16:17]
	flat_load_dwordx2 v[42:43], v[42:43]
	v_add_f32_e32 v36, v36, v72
	v_add_f32_e32 v37, v37, v73
	v_mul_f32_e32 v36, 0xbfb8aa3b, v36
	v_mul_f32_e32 v37, 0xbfb8aa3b, v37
	v_exp_f32_e32 v36, v36
	v_exp_f32_e32 v37, v37
	v_add_f32_e32 v32, v32, v68
	v_mul_f32_e32 v32, 0xbfb8aa3b, v32
	v_add_f32_e32 v36, 1.0, v36
	v_add_f32_e32 v46, 1.0, v37
	v_exp_f32_e32 v32, v32
	s_nop 0
	v_add_f32_e32 v32, 1.0, v32
	v_div_scale_f32 v45, s[10:11], v32, v32, 1.0
	v_rcp_f32_e32 v49, v45
	s_nop 0
	v_fma_f32 v53, -v45, v49, 1.0
	v_div_scale_f32 v51, s[10:11], 1.0, v32, 1.0
	v_fmac_f32_e32 v49, v53, v49
	v_rcp_f32_e32 v36, v36
	v_mul_f32_e32 v53, v51, v49
	v_mul_f32_e64 v48, v36, -v64
	v_fma_f32 v55, -v45, v53, v51
	v_mul_f32_e32 v36, -2.0, v48
	v_fmac_f32_e32 v53, v55, v49
	v_mul_f32_e32 v37, 0x3e4ccccd, v36
	v_fma_f32 v157, v36, s81, 1.0
	v_fma_f32 v51, -v45, v53, v51
	v_pk_mul_f32 v[44:45], v[36:37], v[156:157]
	v_mul_f32_e32 v52, 0x3eaaaaab, v36
	v_sub_f32_e32 v45, 1.0, v45
	v_mov_b32_e32 v37, v52
	v_fma_f32 v159, -v44, v45, 1.0
	v_pk_mul_f32 v[44:45], v[36:37], v[158:159]
	s_mov_b64 vcc, s[10:11]
	v_sub_f32_e32 v37, 1.0, v45
	v_fma_f32 v37, -v44, v37, 1.0
	v_mul_f32_e32 v36, v36, v37
	v_max_f32_e32 v36, 0, v36
	v_mul_f32_e32 v37, 0x4f800000, v36
	v_cmp_gt_f32_e64 s[12:13], s82, v36
	v_div_fmas_f32 v44, v51, v49, v53
	v_div_fixup_f32 v32, v44, v32, 1.0
	v_cndmask_b32_e64 v36, v36, v37, s[12:13]
	v_sqrt_f32_e32 v37, v36
	v_add_f32_e32 v33, v33, v69
	v_mul_f32_e32 v33, 0xbfb8aa3b, v33
	v_exp_f32_e32 v33, v33
	v_add_u32_e32 v44, -1, v37
	v_add_u32_e32 v45, 1, v37
	v_fma_f32 v49, -v44, v37, v36
	v_fma_f32 v51, -v45, v37, v36
	v_cmp_ge_f32_e32 vcc, 0, v49
	v_add_f32_e32 v33, 1.0, v33
	v_add_f32_e32 v38, v38, v74
	v_cndmask_b32_e32 v37, v37, v44, vcc
	v_cmp_lt_f32_e32 vcc, 0, v51
	v_mul_f32_e32 v38, 0xbfb8aa3b, v38
	v_exp_f32_e32 v38, v38
	v_cndmask_b32_e32 v37, v37, v45, vcc
	v_mul_f32_e32 v44, 0x37800000, v37
	v_cndmask_b32_e64 v37, v37, v44, s[12:13]
	v_cmp_class_f32_e32 vcc, v36, v182
	s_waitcnt vmcnt(0) lgkmcnt(0)
; DI unsigned pk2(float a, float b) { f32x2 v = {a, b}; bf16v2_t r = __builtin_convertvector(v, bf16v2_t); return __builtin_bit_cast(unsigned, r); }
; DI float sigm(float x) { return 1.f / (1.f + __expf(-x)); }
;     DI void operator()(const Acc& acc, const Unit& u, int wr, int wc, int fr, int fq, const float (&pre)[8]) const {
;     ...
;                 for (int m = 0; m < 4; ++m) { const size_t o = (size_t)(row0 + ai * HALF + m * 16) * DM + f0 + 4 * n;
;                     const u32x2 xw = *(const u32x2*)(xc + o);
;                     const float xv[4] = {__uint_as_float(xw.x << 16), __uint_as_float(xw.x & 0xffff0000u), __uint_as_float(xw.y << 16), __uint_as_float(xw.y & 0xffff0000u)};
;                     u32x4 w;
; #pragma unroll
;                     for (int e = 0; e < 4; ++e) { const float r = sigm(acc[ai][0][m][n][e] + br[e]), ig = sigm(acc[ai][1][m][n][e] + bi[e]);
;                         const float la = -sp[e] * r, uu = -2.f * la;
;                         const float om = uu * (1.f - uu * 0.5f * (1.f - uu * (1.f / 3.f) * (1.f - uu * 0.25f * (1.f - uu * 0.2f * (1.f - uu * (1.f / 6.f))))));
;                         w[e] = pk2(la, sqrtf(fmaxf(om, 0.f)) * ig * xv[e]); }
;                     *(u32x4*)(ax + o) = w; __builtin_amdgcn_sched_barrier(0); }
	v_and_b32_e32 v44, 0xffff0000, v42
	v_lshlrev_b32_e32 v45, 16, v43
	v_cndmask_b32_e32 v36, v37, v36, vcc
	v_mul_f32_e32 v32, v32, v36
	v_lshlrev_b32_e32 v36, 16, v42
	v_mul_f32_e32 v32, v32, v36
	v_rcp_f32_e32 v36, v46
	v_and_b32_e32 v49, 0xffff0000, v43
	v_mul_f32_e64 v50, v36, -v65
	v_mul_f32_e32 v36, -2.0, v50
	v_cvt_pk_bf16_f32 v32, v48, v32
	v_mul_f32_e32 v37, 0x3e4ccccd, v36
	v_fma_f32 v157, v36, s81, 1.0
	v_pk_mul_f32 v[42:43], v[36:37], v[156:157]
	v_mul_f32_e32 v51, 0x3eaaaaab, v36
	v_sub_f32_e32 v37, 1.0, v43
	v_fma_f32 v159, -v42, v37, 1.0
	v_mov_b32_e32 v37, v51
	v_pk_mul_f32 v[42:43], v[36:37], v[158:159]
	v_add_f32_e32 v34, v34, v70
	v_sub_f32_e32 v37, 1.0, v43
	v_fma_f32 v37, -v42, v37, 1.0
	v_mul_f32_e32 v36, v36, v37
	v_max_f32_e32 v36, 0, v36
	v_mul_f32_e32 v37, 0x4f800000, v36
	v_cmp_gt_f32_e64 s[10:11], s82, v36
	v_rcp_f32_e32 v33, v33
	s_nop 0
	v_cndmask_b32_e64 v36, v36, v37, s[10:11]
	v_sqrt_f32_e32 v37, v36
	v_mul_f32_e32 v34, 0xbfb8aa3b, v34
	v_exp_f32_e32 v34, v34
	v_add_f32_e32 v39, v39, v75
	v_add_u32_e32 v42, -1, v37
	v_fma_f32 v43, -v42, v37, v36
	v_cmp_ge_f32_e32 vcc, 0, v43
	v_add_u32_e32 v43, 1, v37
	v_add_f32_e32 v34, 1.0, v34
	v_cndmask_b32_e32 v42, v37, v42, vcc
	v_fma_f32 v37, -v43, v37, v36
	v_cmp_lt_f32_e32 vcc, 0, v37
	v_mul_f32_e32 v39, 0xbfb8aa3b, v39
	v_exp_f32_e32 v39, v39
	v_cndmask_b32_e32 v37, v42, v43, vcc
	v_mul_f32_e32 v42, 0x37800000, v37
	v_cndmask_b32_e64 v37, v37, v42, s[10:11]
	v_cmp_class_f32_e32 vcc, v36, v182
	v_add_f32_e32 v35, v35, v71
	v_mul_f32_e32 v35, 0xbfb8aa3b, v35
	v_cndmask_b32_e32 v36, v37, v36, vcc
	v_add_f32_e32 v37, 1.0, v38
	v_mul_f32_e32 v33, v33, v36
	v_mul_f32_e32 v33, v33, v44
	v_exp_f32_e32 v35, v35
	v_rcp_f32_e32 v36, v37
	s_nop 0
	v_mul_f32_e64 v47, v36, -v66
	v_mul_f32_e32 v36, -2.0, v47
	v_mul_f32_e32 v37, 0x3e4ccccd, v36
	v_fma_f32 v157, v36, s81, 1.0
	v_pk_mul_f32 v[42:43], v[36:37], v[156:157]
	v_mul_f32_e32 v48, 0x3eaaaaab, v36
	v_sub_f32_e32 v37, 1.0, v43
	v_fma_f32 v159, -v42, v37, 1.0
	v_mov_b32_e32 v37, v48
	v_pk_mul_f32 v[42:43], v[36:37], v[158:159]
	v_sub_f32_e32 v37, 1.0, v43
	v_fma_f32 v37, -v42, v37, 1.0
	v_mul_f32_e32 v36, v36, v37
	v_max_f32_e32 v36, 0, v36
	v_mul_f32_e32 v37, 0x4f800000, v36
	v_cmp_gt_f32_e64 s[10:11], s82, v36
	v_rcp_f32_e32 v34, v34
	v_add_f32_e32 v35, 1.0, v35
	v_cndmask_b32_e64 v36, v36, v37, s[10:11]
	v_sqrt_f32_e32 v37, v36
	v_cvt_pk_bf16_f32 v33, v50, v33
	v_add_u32_e32 v38, -1, v37
	v_fma_f32 v42, -v38, v37, v36
	v_cmp_ge_f32_e32 vcc, 0, v42
	v_add_u32_e32 v42, 1, v37
	s_nop 0
	v_cndmask_b32_e32 v38, v37, v38, vcc
	v_fma_f32 v37, -v42, v37, v36
	v_cmp_lt_f32_e32 vcc, 0, v37
	s_nop 1
	v_cndmask_b32_e32 v37, v38, v42, vcc
	v_mul_f32_e32 v38, 0x37800000, v37
	v_cndmask_b32_e64 v37, v37, v38, s[10:11]
	v_cmp_class_f32_e32 vcc, v36, v182
	s_nop 1
	v_cndmask_b32_e32 v36, v37, v36, vcc
	v_add_f32_e32 v37, 1.0, v39
	v_mul_f32_e32 v34, v34, v36
	v_mul_f32_e32 v34, v34, v45
	v_cvt_pk_bf16_f32 v34, v47, v34
	v_rcp_f32_e32 v36, v37
	s_nop 0
	v_mul_f32_e64 v45, v36, -v67
	v_mul_f32_e32 v36, -2.0, v45
	v_mul_f32_e32 v37, 0x3e4ccccd, v36
	v_fma_f32 v157, v36, s81, 1.0
	v_pk_mul_f32 v[38:39], v[36:37], v[156:157]
	v_mul_f32_e32 v46, 0x3eaaaaab, v36
	v_sub_f32_e32 v37, 1.0, v39
	v_fma_f32 v159, -v38, v37, 1.0
	v_mov_b32_e32 v37, v46
	v_pk_mul_f32 v[38:39], v[36:37], v[158:159]
	s_nop 0
	v_sub_f32_e32 v37, 1.0, v39
	v_fma_f32 v37, -v38, v37, 1.0
	v_mul_f32_e32 v36, v36, v37
	v_max_f32_e32 v36, 0, v36
	v_mul_f32_e32 v37, 0x4f800000, v36
	v_cmp_gt_f32_e64 s[10:11], s82, v36
	v_rcp_f32_e32 v35, v35
	s_nop 0
	v_cndmask_b32_e64 v36, v36, v37, s[10:11]
	v_sqrt_f32_e32 v37, v36
	s_nop 0
	v_add_u32_e32 v38, -1, v37
	v_fma_f32 v39, -v38, v37, v36
	v_cmp_ge_f32_e32 vcc, 0, v39
	v_add_u32_e32 v39, 1, v37
	s_nop 0
	v_cndmask_b32_e32 v38, v37, v38, vcc
	v_fma_f32 v37, -v39, v37, v36
	v_cmp_lt_f32_e32 vcc, 0, v37
	s_nop 1
	v_cndmask_b32_e32 v37, v38, v39, vcc
	v_mul_f32_e32 v38, 0x37800000, v37
	v_cndmask_b32_e64 v37, v37, v38, s[10:11]
	v_cmp_class_f32_e32 vcc, v36, v182
	s_nop 1
	v_cndmask_b32_e32 v36, v37, v36, vcc
	v_mul_f32_e32 v35, v35, v36
	v_mul_f32_e32 v35, v35, v49
	v_cvt_pk_bf16_f32 v35, v45, v35
	v_lshl_add_u64 v[36:37], v[40:41], 2, s[36:37]
	flat_store_dwordx4 v[36:37], v[32:35]
	s_nop 1
	v_lshl_add_u64 v[32:33], v[108:109], 0, v[160:161]
	v_lshl_add_u64 v[34:35], v[32:33], 1, s[16:17]
	flat_load_dwordx2 v[34:35], v[34:35]
	v_add_f32_e32 v28, v28, v72
	v_add_f32_e32 v29, v29, v73
	v_mul_f32_e32 v28, 0xbfb8aa3b, v28
	v_mul_f32_e32 v29, 0xbfb8aa3b, v29
	v_exp_f32_e32 v28, v28
	v_exp_f32_e32 v29, v29
	v_add_f32_e32 v24, v24, v68
	v_mul_f32_e32 v24, 0xbfb8aa3b, v24
	v_add_f32_e32 v28, 1.0, v28
	v_add_f32_e32 v38, 1.0, v29
	v_exp_f32_e32 v24, v24
	s_nop 0
	v_add_f32_e32 v24, 1.0, v24
	v_div_scale_f32 v37, s[10:11], v24, v24, 1.0
	v_rcp_f32_e32 v41, v37
	s_nop 0
	v_fma_f32 v45, -v37, v41, 1.0
	v_div_scale_f32 v43, s[10:11], 1.0, v24, 1.0
	v_fmac_f32_e32 v41, v45, v41
	v_rcp_f32_e32 v28, v28
	v_mul_f32_e32 v45, v43, v41
	v_mul_f32_e64 v40, v28, -v64
	v_fma_f32 v47, -v37, v45, v43
	v_mul_f32_e32 v28, -2.0, v40
	v_fmac_f32_e32 v45, v47, v41
	v_mul_f32_e32 v29, 0x3e4ccccd, v28
	v_fma_f32 v157, v28, s81, 1.0
	v_fma_f32 v43, -v37, v45, v43
	v_pk_mul_f32 v[36:37], v[28:29], v[156:157]
	v_mul_f32_e32 v44, 0x3eaaaaab, v28
	v_sub_f32_e32 v37, 1.0, v37
	v_mov_b32_e32 v29, v44
	v_fma_f32 v159, -v36, v37, 1.0
	v_pk_mul_f32 v[36:37], v[28:29], v[158:159]
	s_mov_b64 vcc, s[10:11]
	v_sub_f32_e32 v29, 1.0, v37
	v_fma_f32 v29, -v36, v29, 1.0
	v_mul_f32_e32 v28, v28, v29
	v_max_f32_e32 v28, 0, v28
	v_mul_f32_e32 v29, 0x4f800000, v28
	v_cmp_gt_f32_e64 s[12:13], s82, v28
	v_div_fmas_f32 v36, v43, v41, v45
	v_div_fixup_f32 v24, v36, v24, 1.0
	v_cndmask_b32_e64 v28, v28, v29, s[12:13]
	v_sqrt_f32_e32 v29, v28
	v_add_f32_e32 v25, v25, v69
	v_mul_f32_e32 v25, 0xbfb8aa3b, v25
	v_exp_f32_e32 v25, v25
	v_add_u32_e32 v36, -1, v29
	v_add_u32_e32 v37, 1, v29
	v_fma_f32 v41, -v36, v29, v28
	v_fma_f32 v43, -v37, v29, v28
	v_cmp_ge_f32_e32 vcc, 0, v41
	v_add_f32_e32 v25, 1.0, v25
	v_add_f32_e32 v30, v30, v74
	v_cndmask_b32_e32 v29, v29, v36, vcc
	v_cmp_lt_f32_e32 vcc, 0, v43
	v_mul_f32_e32 v30, 0xbfb8aa3b, v30
	v_exp_f32_e32 v30, v30
	v_cndmask_b32_e32 v29, v29, v37, vcc
	v_mul_f32_e32 v36, 0x37800000, v29
	v_cndmask_b32_e64 v29, v29, v36, s[12:13]
	v_cmp_class_f32_e32 vcc, v28, v182
	s_waitcnt vmcnt(0) lgkmcnt(0)
; DI unsigned pk2(float a, float b) { f32x2 v = {a, b}; bf16v2_t r = __builtin_convertvector(v, bf16v2_t); return __builtin_bit_cast(unsigned, r); }
; DI float sigm(float x) { return 1.f / (1.f + __expf(-x)); }
;     DI void operator()(const Acc& acc, const Unit& u, int wr, int wc, int fr, int fq, const float (&pre)[8]) const {
;     ...
;                 for (int m = 0; m < 4; ++m) { const size_t o = (size_t)(row0 + ai * HALF + m * 16) * DM + f0 + 4 * n;
;                     const u32x2 xw = *(const u32x2*)(xc + o);
;                     const float xv[4] = {__uint_as_float(xw.x << 16), __uint_as_float(xw.x & 0xffff0000u), __uint_as_float(xw.y << 16), __uint_as_float(xw.y & 0xffff0000u)};
;                     u32x4 w;
; #pragma unroll
;                     for (int e = 0; e < 4; ++e) { const float r = sigm(acc[ai][0][m][n][e] + br[e]), ig = sigm(acc[ai][1][m][n][e] + bi[e]);
;                         const float la = -sp[e] * r, uu = -2.f * la;
;                         const float om = uu * (1.f - uu * 0.5f * (1.f - uu * (1.f / 3.f) * (1.f - uu * 0.25f * (1.f - uu * 0.2f * (1.f - uu * (1.f / 6.f))))));
;                         w[e] = pk2(la, sqrtf(fmaxf(om, 0.f)) * ig * xv[e]); }
;                     *(u32x4*)(ax + o) = w; __builtin_amdgcn_sched_barrier(0); }
	v_and_b32_e32 v36, 0xffff0000, v34
	v_lshlrev_b32_e32 v37, 16, v35
	v_cndmask_b32_e32 v28, v29, v28, vcc
	v_mul_f32_e32 v24, v24, v28
	v_lshlrev_b32_e32 v28, 16, v34
	v_mul_f32_e32 v24, v24, v28
	v_rcp_f32_e32 v28, v38
	v_and_b32_e32 v41, 0xffff0000, v35
	v_mul_f32_e64 v42, v28, -v65
	v_mul_f32_e32 v28, -2.0, v42
	v_cvt_pk_bf16_f32 v24, v40, v24
	v_mul_f32_e32 v29, 0x3e4ccccd, v28
	v_fma_f32 v157, v28, s81, 1.0
	v_pk_mul_f32 v[34:35], v[28:29], v[156:157]
	v_mul_f32_e32 v43, 0x3eaaaaab, v28
	v_sub_f32_e32 v29, 1.0, v35
	v_fma_f32 v159, -v34, v29, 1.0
	v_mov_b32_e32 v29, v43
	v_pk_mul_f32 v[34:35], v[28:29], v[158:159]
	v_add_f32_e32 v26, v26, v70
	v_sub_f32_e32 v29, 1.0, v35
	v_fma_f32 v29, -v34, v29, 1.0
	v_mul_f32_e32 v28, v28, v29
	v_max_f32_e32 v28, 0, v28
	v_mul_f32_e32 v29, 0x4f800000, v28
	v_cmp_gt_f32_e64 s[10:11], s82, v28
	v_rcp_f32_e32 v25, v25
	s_nop 0
	v_cndmask_b32_e64 v28, v28, v29, s[10:11]
	v_sqrt_f32_e32 v29, v28
	v_mul_f32_e32 v26, 0xbfb8aa3b, v26
	v_exp_f32_e32 v26, v26
	v_add_f32_e32 v31, v31, v75
	v_add_u32_e32 v34, -1, v29
	v_fma_f32 v35, -v34, v29, v28
	v_cmp_ge_f32_e32 vcc, 0, v35
	v_add_u32_e32 v35, 1, v29
	v_add_f32_e32 v26, 1.0, v26
	v_cndmask_b32_e32 v34, v29, v34, vcc
	v_fma_f32 v29, -v35, v29, v28
	v_cmp_lt_f32_e32 vcc, 0, v29
	v_mul_f32_e32 v31, 0xbfb8aa3b, v31
	v_exp_f32_e32 v31, v31
	v_cndmask_b32_e32 v29, v34, v35, vcc
	v_mul_f32_e32 v34, 0x37800000, v29
	v_cndmask_b32_e64 v29, v29, v34, s[10:11]
	v_cmp_class_f32_e32 vcc, v28, v182
	v_add_f32_e32 v27, v27, v71
	v_mul_f32_e32 v27, 0xbfb8aa3b, v27
	v_cndmask_b32_e32 v28, v29, v28, vcc
	v_add_f32_e32 v29, 1.0, v30
	v_mul_f32_e32 v25, v25, v28
	v_mul_f32_e32 v25, v25, v36
	v_exp_f32_e32 v27, v27
	v_rcp_f32_e32 v28, v29
	s_nop 0
	v_mul_f32_e64 v39, v28, -v66
	v_mul_f32_e32 v28, -2.0, v39
	v_mul_f32_e32 v29, 0x3e4ccccd, v28
	v_fma_f32 v157, v28, s81, 1.0
	v_pk_mul_f32 v[34:35], v[28:29], v[156:157]
	v_mul_f32_e32 v40, 0x3eaaaaab, v28
	v_sub_f32_e32 v29, 1.0, v35
	v_fma_f32 v159, -v34, v29, 1.0
	v_mov_b32_e32 v29, v40
	v_pk_mul_f32 v[34:35], v[28:29], v[158:159]
	v_sub_f32_e32 v29, 1.0, v35
	v_fma_f32 v29, -v34, v29, 1.0
	v_mul_f32_e32 v28, v28, v29
	v_max_f32_e32 v28, 0, v28
	v_mul_f32_e32 v29, 0x4f800000, v28
	v_cmp_gt_f32_e64 s[10:11], s82, v28
	v_rcp_f32_e32 v26, v26
	v_add_f32_e32 v27, 1.0, v27
	v_cndmask_b32_e64 v28, v28, v29, s[10:11]
	v_sqrt_f32_e32 v29, v28
	v_cvt_pk_bf16_f32 v25, v42, v25
	v_add_u32_e32 v30, -1, v29
	v_fma_f32 v34, -v30, v29, v28
	v_cmp_ge_f32_e32 vcc, 0, v34
	v_add_u32_e32 v34, 1, v29
	s_nop 0
	v_cndmask_b32_e32 v30, v29, v30, vcc
	v_fma_f32 v29, -v34, v29, v28
	v_cmp_lt_f32_e32 vcc, 0, v29
	s_nop 1
	v_cndmask_b32_e32 v29, v30, v34, vcc
	v_mul_f32_e32 v30, 0x37800000, v29
	v_cndmask_b32_e64 v29, v29, v30, s[10:11]
	v_cmp_class_f32_e32 vcc, v28, v182
	s_nop 1
	v_cndmask_b32_e32 v28, v29, v28, vcc
	v_add_f32_e32 v29, 1.0, v31
	v_mul_f32_e32 v26, v26, v28
	v_mul_f32_e32 v26, v26, v37
	v_cvt_pk_bf16_f32 v26, v39, v26
	v_rcp_f32_e32 v28, v29
	s_nop 0
	v_mul_f32_e64 v37, v28, -v67
	v_mul_f32_e32 v28, -2.0, v37
	v_mul_f32_e32 v29, 0x3e4ccccd, v28
	v_fma_f32 v157, v28, s81, 1.0
	v_pk_mul_f32 v[30:31], v[28:29], v[156:157]
	v_mul_f32_e32 v38, 0x3eaaaaab, v28
	v_sub_f32_e32 v29, 1.0, v31
	v_fma_f32 v159, -v30, v29, 1.0
	v_mov_b32_e32 v29, v38
	v_pk_mul_f32 v[30:31], v[28:29], v[158:159]
	s_nop 0
	v_sub_f32_e32 v29, 1.0, v31
	v_fma_f32 v29, -v30, v29, 1.0
	v_mul_f32_e32 v28, v28, v29
	v_max_f32_e32 v28, 0, v28
	v_mul_f32_e32 v29, 0x4f800000, v28
	v_cmp_gt_f32_e64 s[10:11], s82, v28
	v_rcp_f32_e32 v27, v27
	s_nop 0
	v_cndmask_b32_e64 v28, v28, v29, s[10:11]
	v_sqrt_f32_e32 v29, v28
	s_nop 0
	v_add_u32_e32 v30, -1, v29
	v_fma_f32 v31, -v30, v29, v28
	v_cmp_ge_f32_e32 vcc, 0, v31
	v_add_u32_e32 v31, 1, v29
	s_nop 0
	v_cndmask_b32_e32 v30, v29, v30, vcc
	v_fma_f32 v29, -v31, v29, v28
	v_cmp_lt_f32_e32 vcc, 0, v29
	s_nop 1
	v_cndmask_b32_e32 v29, v30, v31, vcc
	v_mul_f32_e32 v30, 0x37800000, v29
	v_cndmask_b32_e64 v29, v29, v30, s[10:11]
	v_cmp_class_f32_e32 vcc, v28, v182
	s_nop 1
	v_cndmask_b32_e32 v28, v29, v28, vcc
	v_mul_f32_e32 v27, v27, v28
	v_mul_f32_e32 v27, v27, v41
	v_cvt_pk_bf16_f32 v27, v37, v27
	v_lshl_add_u64 v[28:29], v[32:33], 2, s[36:37]
	flat_store_dwordx4 v[28:29], v[24:27]
	s_nop 1
	v_lshl_add_u64 v[24:25], v[100:101], 0, v[160:161]
	v_lshl_add_u64 v[26:27], v[24:25], 1, s[16:17]
	flat_load_dwordx2 v[26:27], v[26:27]
	v_add_f32_e32 v20, v20, v72
	v_add_f32_e32 v21, v21, v73
	v_mul_f32_e32 v20, 0xbfb8aa3b, v20
	v_mul_f32_e32 v21, 0xbfb8aa3b, v21
	v_exp_f32_e32 v20, v20
	v_exp_f32_e32 v21, v21
	v_add_f32_e32 v16, v16, v68
	v_mul_f32_e32 v16, 0xbfb8aa3b, v16
	v_add_f32_e32 v20, 1.0, v20
	v_add_f32_e32 v30, 1.0, v21
	v_exp_f32_e32 v16, v16
	s_nop 0
	v_add_f32_e32 v16, 1.0, v16
	v_div_scale_f32 v29, s[10:11], v16, v16, 1.0
	v_rcp_f32_e32 v33, v29
	s_nop 0
	v_fma_f32 v37, -v29, v33, 1.0
	v_div_scale_f32 v35, s[10:11], 1.0, v16, 1.0
	v_fmac_f32_e32 v33, v37, v33
	v_rcp_f32_e32 v20, v20
	v_mul_f32_e32 v37, v35, v33
	v_mul_f32_e64 v32, v20, -v64
	v_fma_f32 v39, -v29, v37, v35
	v_mul_f32_e32 v20, -2.0, v32
	v_fmac_f32_e32 v37, v39, v33
	v_mul_f32_e32 v21, 0x3e4ccccd, v20
	v_fma_f32 v157, v20, s81, 1.0
	v_fma_f32 v35, -v29, v37, v35
	v_pk_mul_f32 v[28:29], v[20:21], v[156:157]
	v_mul_f32_e32 v36, 0x3eaaaaab, v20
	v_sub_f32_e32 v29, 1.0, v29
	v_mov_b32_e32 v21, v36
	v_fma_f32 v159, -v28, v29, 1.0
	v_pk_mul_f32 v[28:29], v[20:21], v[158:159]
	s_mov_b64 vcc, s[10:11]
	v_sub_f32_e32 v21, 1.0, v29
	v_fma_f32 v21, -v28, v21, 1.0
	v_mul_f32_e32 v20, v20, v21
	v_max_f32_e32 v20, 0, v20
	v_mul_f32_e32 v21, 0x4f800000, v20
	v_cmp_gt_f32_e64 s[12:13], s82, v20
	v_div_fmas_f32 v28, v35, v33, v37
	v_div_fixup_f32 v16, v28, v16, 1.0
	v_cndmask_b32_e64 v20, v20, v21, s[12:13]
	v_sqrt_f32_e32 v21, v20
	v_add_f32_e32 v17, v17, v69
	v_mul_f32_e32 v17, 0xbfb8aa3b, v17
	v_exp_f32_e32 v17, v17
	v_add_u32_e32 v28, -1, v21
	v_add_u32_e32 v29, 1, v21
	v_fma_f32 v33, -v28, v21, v20
	v_fma_f32 v35, -v29, v21, v20
	v_cmp_ge_f32_e32 vcc, 0, v33
	v_add_f32_e32 v17, 1.0, v17
	v_add_f32_e32 v22, v22, v74
	v_cndmask_b32_e32 v21, v21, v28, vcc
	v_cmp_lt_f32_e32 vcc, 0, v35
	v_mul_f32_e32 v22, 0xbfb8aa3b, v22
	v_exp_f32_e32 v22, v22
	v_cndmask_b32_e32 v21, v21, v29, vcc
	v_mul_f32_e32 v28, 0x37800000, v21
	v_cndmask_b32_e64 v21, v21, v28, s[12:13]
	v_cmp_class_f32_e32 vcc, v20, v182
	s_waitcnt vmcnt(0) lgkmcnt(0)
; DI unsigned pk2(float a, float b) { f32x2 v = {a, b}; bf16v2_t r = __builtin_convertvector(v, bf16v2_t); return __builtin_bit_cast(unsigned, r); }
; DI float sigm(float x) { return 1.f / (1.f + __expf(-x)); }
;     DI void operator()(const Acc& acc, const Unit& u, int wr, int wc, int fr, int fq, const float (&pre)[8]) const {
;     ...
;                 for (int m = 0; m < 4; ++m) { const size_t o = (size_t)(row0 + ai * HALF + m * 16) * DM + f0 + 4 * n;
;                     const u32x2 xw = *(const u32x2*)(xc + o);
;                     const float xv[4] = {__uint_as_float(xw.x << 16), __uint_as_float(xw.x & 0xffff0000u), __uint_as_float(xw.y << 16), __uint_as_float(xw.y & 0xffff0000u)};
;                     u32x4 w;
; #pragma unroll
;                     for (int e = 0; e < 4; ++e) { const float r = sigm(acc[ai][0][m][n][e] + br[e]), ig = sigm(acc[ai][1][m][n][e] + bi[e]);
;                         const float la = -sp[e] * r, uu = -2.f * la;
;                         const float om = uu * (1.f - uu * 0.5f * (1.f - uu * (1.f / 3.f) * (1.f - uu * 0.25f * (1.f - uu * 0.2f * (1.f - uu * (1.f / 6.f))))));
;                         w[e] = pk2(la, sqrtf(fmaxf(om, 0.f)) * ig * xv[e]); }
;                     *(u32x4*)(ax + o) = w; __builtin_amdgcn_sched_barrier(0); }
	v_and_b32_e32 v28, 0xffff0000, v26
	v_lshlrev_b32_e32 v29, 16, v27
	v_cndmask_b32_e32 v20, v21, v20, vcc
	v_mul_f32_e32 v16, v16, v20
	v_lshlrev_b32_e32 v20, 16, v26
	v_mul_f32_e32 v16, v16, v20
	v_rcp_f32_e32 v20, v30
	v_and_b32_e32 v33, 0xffff0000, v27
	v_mul_f32_e64 v34, v20, -v65
	v_mul_f32_e32 v20, -2.0, v34
	v_cvt_pk_bf16_f32 v16, v32, v16
	v_mul_f32_e32 v21, 0x3e4ccccd, v20
	v_fma_f32 v157, v20, s81, 1.0
	v_pk_mul_f32 v[26:27], v[20:21], v[156:157]
	v_mul_f32_e32 v35, 0x3eaaaaab, v20
	v_sub_f32_e32 v21, 1.0, v27
	v_fma_f32 v159, -v26, v21, 1.0
	v_mov_b32_e32 v21, v35
	v_pk_mul_f32 v[26:27], v[20:21], v[158:159]
	v_add_f32_e32 v18, v18, v70
	v_sub_f32_e32 v21, 1.0, v27
	v_fma_f32 v21, -v26, v21, 1.0
	v_mul_f32_e32 v20, v20, v21
	v_max_f32_e32 v20, 0, v20
	v_mul_f32_e32 v21, 0x4f800000, v20
	v_cmp_gt_f32_e64 s[10:11], s82, v20
	v_rcp_f32_e32 v17, v17
	s_nop 0
	v_cndmask_b32_e64 v20, v20, v21, s[10:11]
	v_sqrt_f32_e32 v21, v20
	v_mul_f32_e32 v18, 0xbfb8aa3b, v18
	v_exp_f32_e32 v18, v18
	v_add_f32_e32 v23, v23, v75
	v_add_u32_e32 v26, -1, v21
	v_fma_f32 v27, -v26, v21, v20
	v_cmp_ge_f32_e32 vcc, 0, v27
	v_add_u32_e32 v27, 1, v21
	v_add_f32_e32 v18, 1.0, v18
	v_cndmask_b32_e32 v26, v21, v26, vcc
	v_fma_f32 v21, -v27, v21, v20
	v_cmp_lt_f32_e32 vcc, 0, v21
	v_mul_f32_e32 v23, 0xbfb8aa3b, v23
	v_exp_f32_e32 v23, v23
	v_cndmask_b32_e32 v21, v26, v27, vcc
	v_mul_f32_e32 v26, 0x37800000, v21
	v_cndmask_b32_e64 v21, v21, v26, s[10:11]
	v_cmp_class_f32_e32 vcc, v20, v182
	v_add_f32_e32 v19, v19, v71
	v_mul_f32_e32 v19, 0xbfb8aa3b, v19
	v_cndmask_b32_e32 v20, v21, v20, vcc
	v_add_f32_e32 v21, 1.0, v22
	v_mul_f32_e32 v17, v17, v20
	v_mul_f32_e32 v17, v17, v28
	v_exp_f32_e32 v19, v19
	v_rcp_f32_e32 v20, v21
	s_nop 0
	v_mul_f32_e64 v31, v20, -v66
	v_mul_f32_e32 v20, -2.0, v31
	v_mul_f32_e32 v21, 0x3e4ccccd, v20
	v_fma_f32 v157, v20, s81, 1.0
	v_pk_mul_f32 v[26:27], v[20:21], v[156:157]
	v_mul_f32_e32 v32, 0x3eaaaaab, v20
	v_sub_f32_e32 v21, 1.0, v27
	v_fma_f32 v159, -v26, v21, 1.0
	v_mov_b32_e32 v21, v32
	v_pk_mul_f32 v[26:27], v[20:21], v[158:159]
	v_sub_f32_e32 v21, 1.0, v27
	v_fma_f32 v21, -v26, v21, 1.0
	v_mul_f32_e32 v20, v20, v21
	v_max_f32_e32 v20, 0, v20
	v_mul_f32_e32 v21, 0x4f800000, v20
	v_cmp_gt_f32_e64 s[10:11], s82, v20
	v_rcp_f32_e32 v18, v18
	v_add_f32_e32 v19, 1.0, v19
	v_cndmask_b32_e64 v20, v20, v21, s[10:11]
	v_sqrt_f32_e32 v21, v20
	v_cvt_pk_bf16_f32 v17, v34, v17
	v_add_u32_e32 v22, -1, v21
	v_fma_f32 v26, -v22, v21, v20
	v_cmp_ge_f32_e32 vcc, 0, v26
	v_add_u32_e32 v26, 1, v21
	s_nop 0
	v_cndmask_b32_e32 v22, v21, v22, vcc
	v_fma_f32 v21, -v26, v21, v20
	v_cmp_lt_f32_e32 vcc, 0, v21
	s_nop 1
	v_cndmask_b32_e32 v21, v22, v26, vcc
	v_mul_f32_e32 v22, 0x37800000, v21
	v_cndmask_b32_e64 v21, v21, v22, s[10:11]
	v_cmp_class_f32_e32 vcc, v20, v182
	s_nop 1
	v_cndmask_b32_e32 v20, v21, v20, vcc
	v_add_f32_e32 v21, 1.0, v23
	v_mul_f32_e32 v18, v18, v20
	v_mul_f32_e32 v18, v18, v29
	v_cvt_pk_bf16_f32 v18, v31, v18
	v_rcp_f32_e32 v20, v21
	s_nop 0
	v_mul_f32_e64 v29, v20, -v67
	v_mul_f32_e32 v20, -2.0, v29
	v_mul_f32_e32 v21, 0x3e4ccccd, v20
	v_fma_f32 v157, v20, s81, 1.0
	v_pk_mul_f32 v[22:23], v[20:21], v[156:157]
	v_mul_f32_e32 v30, 0x3eaaaaab, v20
	v_sub_f32_e32 v21, 1.0, v23
	v_fma_f32 v159, -v22, v21, 1.0
	v_mov_b32_e32 v21, v30
	v_pk_mul_f32 v[22:23], v[20:21], v[158:159]
	s_nop 0
	v_sub_f32_e32 v21, 1.0, v23
	v_fma_f32 v21, -v22, v21, 1.0
	v_mul_f32_e32 v20, v20, v21
	v_max_f32_e32 v20, 0, v20
	v_mul_f32_e32 v21, 0x4f800000, v20
	v_cmp_gt_f32_e64 s[10:11], s82, v20
	v_rcp_f32_e32 v19, v19
	s_nop 0
	v_cndmask_b32_e64 v20, v20, v21, s[10:11]
	v_sqrt_f32_e32 v21, v20
	s_nop 0
	v_add_u32_e32 v22, -1, v21
	v_fma_f32 v23, -v22, v21, v20
	v_cmp_ge_f32_e32 vcc, 0, v23
	v_add_u32_e32 v23, 1, v21
	s_nop 0
	v_cndmask_b32_e32 v22, v21, v22, vcc
	v_fma_f32 v21, -v23, v21, v20
	v_cmp_lt_f32_e32 vcc, 0, v21
	s_nop 1
	v_cndmask_b32_e32 v21, v22, v23, vcc
	v_mul_f32_e32 v22, 0x37800000, v21
	v_cndmask_b32_e64 v21, v21, v22, s[10:11]
	v_cmp_class_f32_e32 vcc, v20, v182
	s_nop 1
	v_cndmask_b32_e32 v20, v21, v20, vcc
	v_mul_f32_e32 v19, v19, v20
	v_mul_f32_e32 v19, v19, v33
	v_cvt_pk_bf16_f32 v19, v29, v19
	v_lshl_add_u64 v[20:21], v[24:25], 2, s[36:37]
	flat_store_dwordx4 v[20:21], v[16:19]
	s_nop 1
	v_lshl_add_u64 v[16:17], v[80:81], 0, v[160:161]
	v_lshl_add_u64 v[18:19], v[16:17], 1, s[16:17]
	flat_load_dwordx2 v[18:19], v[18:19]
	v_add_f32_e32 v12, v12, v72
	v_add_f32_e32 v13, v13, v73
	v_mul_f32_e32 v12, 0xbfb8aa3b, v12
	v_mul_f32_e32 v13, 0xbfb8aa3b, v13
	v_exp_f32_e32 v12, v12
	v_exp_f32_e32 v13, v13
	v_add_f32_e32 v8, v8, v68
	v_mul_f32_e32 v8, 0xbfb8aa3b, v8
	v_add_f32_e32 v12, 1.0, v12
	v_add_f32_e32 v22, 1.0, v13
	v_exp_f32_e32 v8, v8
	s_nop 0
	v_add_f32_e32 v8, 1.0, v8
	v_div_scale_f32 v21, s[10:11], v8, v8, 1.0
	v_rcp_f32_e32 v25, v21
	s_nop 0
	v_fma_f32 v29, -v21, v25, 1.0
	v_div_scale_f32 v27, s[10:11], 1.0, v8, 1.0
	v_fmac_f32_e32 v25, v29, v25
	v_rcp_f32_e32 v12, v12
	v_mul_f32_e32 v29, v27, v25
	v_mul_f32_e64 v24, v12, -v64
	v_fma_f32 v31, -v21, v29, v27
	v_mul_f32_e32 v12, -2.0, v24
	v_fmac_f32_e32 v29, v31, v25
	v_mul_f32_e32 v13, 0x3e4ccccd, v12
	v_fma_f32 v157, v12, s81, 1.0
	v_fma_f32 v27, -v21, v29, v27
	v_pk_mul_f32 v[20:21], v[12:13], v[156:157]
	v_mul_f32_e32 v28, 0x3eaaaaab, v12
	v_sub_f32_e32 v21, 1.0, v21
	v_mov_b32_e32 v13, v28
	v_fma_f32 v159, -v20, v21, 1.0
	v_pk_mul_f32 v[20:21], v[12:13], v[158:159]
	s_mov_b64 vcc, s[10:11]
	v_sub_f32_e32 v13, 1.0, v21
	v_fma_f32 v13, -v20, v13, 1.0
	v_mul_f32_e32 v12, v12, v13
	v_max_f32_e32 v12, 0, v12
	v_mul_f32_e32 v13, 0x4f800000, v12
	v_cmp_gt_f32_e64 s[12:13], s82, v12
	v_div_fmas_f32 v20, v27, v25, v29
	v_div_fixup_f32 v8, v20, v8, 1.0
	v_cndmask_b32_e64 v12, v12, v13, s[12:13]
	v_sqrt_f32_e32 v13, v12
	v_add_f32_e32 v9, v9, v69
	v_mul_f32_e32 v9, 0xbfb8aa3b, v9
	v_exp_f32_e32 v9, v9
	v_add_u32_e32 v20, -1, v13
	v_add_u32_e32 v21, 1, v13
	v_fma_f32 v25, -v20, v13, v12
	v_fma_f32 v27, -v21, v13, v12
	v_cmp_ge_f32_e32 vcc, 0, v25
	v_add_f32_e32 v9, 1.0, v9
	v_add_f32_e32 v14, v14, v74
	v_cndmask_b32_e32 v13, v13, v20, vcc
	v_cmp_lt_f32_e32 vcc, 0, v27
	v_mul_f32_e32 v14, 0xbfb8aa3b, v14
	v_exp_f32_e32 v14, v14
	v_cndmask_b32_e32 v13, v13, v21, vcc
	v_mul_f32_e32 v20, 0x37800000, v13
	v_cndmask_b32_e64 v13, v13, v20, s[12:13]
	v_cmp_class_f32_e32 vcc, v12, v182
	s_waitcnt vmcnt(0) lgkmcnt(0)
; DI unsigned pk2(float a, float b) { f32x2 v = {a, b}; bf16v2_t r = __builtin_convertvector(v, bf16v2_t); return __builtin_bit_cast(unsigned, r); }
; DI float sigm(float x) { return 1.f / (1.f + __expf(-x)); }
;     DI void operator()(const Acc& acc, const Unit& u, int wr, int wc, int fr, int fq, const float (&pre)[8]) const {
;     ...
;                 for (int m = 0; m < 4; ++m) { const size_t o = (size_t)(row0 + ai * HALF + m * 16) * DM + f0 + 4 * n;
;                     const u32x2 xw = *(const u32x2*)(xc + o);
;                     const float xv[4] = {__uint_as_float(xw.x << 16), __uint_as_float(xw.x & 0xffff0000u), __uint_as_float(xw.y << 16), __uint_as_float(xw.y & 0xffff0000u)};
;                     u32x4 w;
; #pragma unroll
;                     for (int e = 0; e < 4; ++e) { const float r = sigm(acc[ai][0][m][n][e] + br[e]), ig = sigm(acc[ai][1][m][n][e] + bi[e]);
;                         const float la = -sp[e] * r, uu = -2.f * la;
;                         const float om = uu * (1.f - uu * 0.5f * (1.f - uu * (1.f / 3.f) * (1.f - uu * 0.25f * (1.f - uu * 0.2f * (1.f - uu * (1.f / 6.f))))));
;                         w[e] = pk2(la, sqrtf(fmaxf(om, 0.f)) * ig * xv[e]); }
;                     *(u32x4*)(ax + o) = w; __builtin_amdgcn_sched_barrier(0); }
	v_and_b32_e32 v20, 0xffff0000, v18
	v_lshlrev_b32_e32 v21, 16, v19
	v_cndmask_b32_e32 v12, v13, v12, vcc
	v_mul_f32_e32 v8, v8, v12
	v_lshlrev_b32_e32 v12, 16, v18
	v_mul_f32_e32 v8, v8, v12
	v_rcp_f32_e32 v12, v22
	v_and_b32_e32 v25, 0xffff0000, v19
	v_mul_f32_e64 v26, v12, -v65
	v_mul_f32_e32 v12, -2.0, v26
	v_cvt_pk_bf16_f32 v8, v24, v8
	v_mul_f32_e32 v13, 0x3e4ccccd, v12
	v_fma_f32 v157, v12, s81, 1.0
	v_pk_mul_f32 v[18:19], v[12:13], v[156:157]
	v_mul_f32_e32 v27, 0x3eaaaaab, v12
	v_sub_f32_e32 v13, 1.0, v19
	v_fma_f32 v159, -v18, v13, 1.0
	v_mov_b32_e32 v13, v27
	v_pk_mul_f32 v[18:19], v[12:13], v[158:159]
	v_add_f32_e32 v10, v10, v70
	v_sub_f32_e32 v13, 1.0, v19
	v_fma_f32 v13, -v18, v13, 1.0
	v_mul_f32_e32 v12, v12, v13
	v_max_f32_e32 v12, 0, v12
	v_mul_f32_e32 v13, 0x4f800000, v12
	v_cmp_gt_f32_e64 s[10:11], s82, v12
	v_rcp_f32_e32 v9, v9
	s_nop 0
	v_cndmask_b32_e64 v12, v12, v13, s[10:11]
	v_sqrt_f32_e32 v13, v12
	v_mul_f32_e32 v10, 0xbfb8aa3b, v10
	v_exp_f32_e32 v10, v10
	v_add_f32_e32 v15, v15, v75
	v_add_u32_e32 v18, -1, v13
	v_fma_f32 v19, -v18, v13, v12
	v_cmp_ge_f32_e32 vcc, 0, v19
	v_add_u32_e32 v19, 1, v13
	v_add_f32_e32 v10, 1.0, v10
	v_cndmask_b32_e32 v18, v13, v18, vcc
	v_fma_f32 v13, -v19, v13, v12
	v_cmp_lt_f32_e32 vcc, 0, v13
	v_mul_f32_e32 v15, 0xbfb8aa3b, v15
	v_exp_f32_e32 v15, v15
	v_cndmask_b32_e32 v13, v18, v19, vcc
	v_mul_f32_e32 v18, 0x37800000, v13
	v_cndmask_b32_e64 v13, v13, v18, s[10:11]
	v_cmp_class_f32_e32 vcc, v12, v182
	v_add_f32_e32 v11, v11, v71
	v_mul_f32_e32 v11, 0xbfb8aa3b, v11
	v_cndmask_b32_e32 v12, v13, v12, vcc
	v_add_f32_e32 v13, 1.0, v14
	v_mul_f32_e32 v9, v9, v12
	v_mul_f32_e32 v9, v9, v20
	v_exp_f32_e32 v11, v11
	v_rcp_f32_e32 v12, v13
	s_nop 0
	v_mul_f32_e64 v23, v12, -v66
	v_mul_f32_e32 v12, -2.0, v23
	v_mul_f32_e32 v13, 0x3e4ccccd, v12
	v_fma_f32 v157, v12, s81, 1.0
	v_pk_mul_f32 v[18:19], v[12:13], v[156:157]
	v_mul_f32_e32 v24, 0x3eaaaaab, v12
	v_sub_f32_e32 v13, 1.0, v19
	v_fma_f32 v159, -v18, v13, 1.0
	v_mov_b32_e32 v13, v24
	v_pk_mul_f32 v[18:19], v[12:13], v[158:159]
	v_sub_f32_e32 v13, 1.0, v19
	v_fma_f32 v13, -v18, v13, 1.0
	v_mul_f32_e32 v12, v12, v13
	v_max_f32_e32 v12, 0, v12
	v_mul_f32_e32 v13, 0x4f800000, v12
	v_cmp_gt_f32_e64 s[10:11], s82, v12
	v_rcp_f32_e32 v10, v10
	v_add_f32_e32 v11, 1.0, v11
	v_cndmask_b32_e64 v12, v12, v13, s[10:11]
	v_sqrt_f32_e32 v13, v12
	v_cvt_pk_bf16_f32 v9, v26, v9
	v_add_u32_e32 v14, -1, v13
	v_fma_f32 v18, -v14, v13, v12
	v_cmp_ge_f32_e32 vcc, 0, v18
	v_add_u32_e32 v18, 1, v13
	s_nop 0
	v_cndmask_b32_e32 v14, v13, v14, vcc
	v_fma_f32 v13, -v18, v13, v12
	v_cmp_lt_f32_e32 vcc, 0, v13
	s_nop 1
	v_cndmask_b32_e32 v13, v14, v18, vcc
	v_mul_f32_e32 v14, 0x37800000, v13
	v_cndmask_b32_e64 v13, v13, v14, s[10:11]
	v_cmp_class_f32_e32 vcc, v12, v182
	s_nop 1
	v_cndmask_b32_e32 v12, v13, v12, vcc
	v_add_f32_e32 v13, 1.0, v15
	v_mul_f32_e32 v10, v10, v12
	v_mul_f32_e32 v10, v10, v21
	v_cvt_pk_bf16_f32 v10, v23, v10
	v_rcp_f32_e32 v12, v13
	s_nop 0
	v_mul_f32_e64 v21, v12, -v67
	v_mul_f32_e32 v12, -2.0, v21
	v_mul_f32_e32 v13, 0x3e4ccccd, v12
	v_fma_f32 v157, v12, s81, 1.0
	v_pk_mul_f32 v[14:15], v[12:13], v[156:157]
	v_mul_f32_e32 v22, 0x3eaaaaab, v12
	v_sub_f32_e32 v13, 1.0, v15
	v_fma_f32 v159, -v14, v13, 1.0
	v_mov_b32_e32 v13, v22
	v_pk_mul_f32 v[14:15], v[12:13], v[158:159]
	s_nop 0
	v_sub_f32_e32 v13, 1.0, v15
	v_fma_f32 v13, -v14, v13, 1.0
	v_mul_f32_e32 v12, v12, v13
	v_max_f32_e32 v12, 0, v12
	v_mul_f32_e32 v13, 0x4f800000, v12
	v_cmp_gt_f32_e64 s[10:11], s82, v12
	v_rcp_f32_e32 v11, v11
	s_nop 0
	v_cndmask_b32_e64 v12, v12, v13, s[10:11]
	v_sqrt_f32_e32 v13, v12
	s_nop 0
	v_add_u32_e32 v14, -1, v13
	v_fma_f32 v15, -v14, v13, v12
	v_cmp_ge_f32_e32 vcc, 0, v15
	v_add_u32_e32 v15, 1, v13
	s_nop 0
	v_cndmask_b32_e32 v14, v13, v14, vcc
	v_fma_f32 v13, -v15, v13, v12
	v_cmp_lt_f32_e32 vcc, 0, v13
	s_nop 1
	v_cndmask_b32_e32 v13, v14, v15, vcc
	v_mul_f32_e32 v14, 0x37800000, v13
	v_cndmask_b32_e64 v13, v13, v14, s[10:11]
	v_cmp_class_f32_e32 vcc, v12, v182
	s_nop 1
	v_cndmask_b32_e32 v12, v13, v12, vcc
	v_mul_f32_e32 v11, v11, v12
	v_mul_f32_e32 v11, v11, v25
	v_cvt_pk_bf16_f32 v11, v21, v11
	v_lshl_add_u64 v[12:13], v[16:17], 2, s[36:37]
	flat_store_dwordx4 v[12:13], v[8:11]
	s_nop 1
	v_lshl_add_u64 v[8:9], v[76:77], 0, v[160:161]
	v_lshl_add_u64 v[10:11], v[8:9], 1, s[16:17]
	flat_load_dwordx2 v[10:11], v[10:11]
	v_add_f32_e32 v4, v4, v72
	v_add_f32_e32 v5, v5, v73
	v_mul_f32_e32 v4, 0xbfb8aa3b, v4
	v_mul_f32_e32 v5, 0xbfb8aa3b, v5
	v_exp_f32_e32 v4, v4
	v_exp_f32_e32 v5, v5
	v_add_f32_e32 v0, v0, v68
	v_mul_f32_e32 v0, 0xbfb8aa3b, v0
	v_add_f32_e32 v4, 1.0, v4
	v_add_f32_e32 v14, 1.0, v5
	v_exp_f32_e32 v0, v0
	s_nop 0
	v_add_f32_e32 v0, 1.0, v0
	v_div_scale_f32 v13, s[10:11], v0, v0, 1.0
	v_rcp_f32_e32 v17, v13
	s_nop 0
	v_fma_f32 v21, -v13, v17, 1.0
	v_div_scale_f32 v19, s[10:11], 1.0, v0, 1.0
	v_fmac_f32_e32 v17, v21, v17
	v_rcp_f32_e32 v4, v4
	v_mul_f32_e32 v21, v19, v17
	v_mul_f32_e64 v16, v4, -v64
	v_fma_f32 v23, -v13, v21, v19
	v_mul_f32_e32 v4, -2.0, v16
	v_fmac_f32_e32 v21, v23, v17
	v_mul_f32_e32 v5, 0x3e4ccccd, v4
	v_fma_f32 v157, v4, s81, 1.0
	v_fma_f32 v19, -v13, v21, v19
	v_pk_mul_f32 v[12:13], v[4:5], v[156:157]
	v_mul_f32_e32 v20, 0x3eaaaaab, v4
	v_sub_f32_e32 v13, 1.0, v13
	v_mov_b32_e32 v5, v20
	v_fma_f32 v159, -v12, v13, 1.0
	v_pk_mul_f32 v[12:13], v[4:5], v[158:159]
	s_mov_b64 vcc, s[10:11]
	v_sub_f32_e32 v5, 1.0, v13
	v_fma_f32 v5, -v12, v5, 1.0
	v_mul_f32_e32 v4, v4, v5
	v_max_f32_e32 v4, 0, v4
	v_mul_f32_e32 v5, 0x4f800000, v4
	v_cmp_gt_f32_e64 s[12:13], s82, v4
	v_div_fmas_f32 v12, v19, v17, v21
	v_div_fixup_f32 v0, v12, v0, 1.0
	v_cndmask_b32_e64 v4, v4, v5, s[12:13]
	v_sqrt_f32_e32 v5, v4
	v_add_f32_e32 v1, v1, v69
	v_mul_f32_e32 v1, 0xbfb8aa3b, v1
	v_exp_f32_e32 v1, v1
	v_add_u32_e32 v12, -1, v5
	v_add_u32_e32 v13, 1, v5
	v_fma_f32 v17, -v12, v5, v4
	v_fma_f32 v19, -v13, v5, v4
	v_cmp_ge_f32_e32 vcc, 0, v17
	v_add_f32_e32 v1, 1.0, v1
	v_add_f32_e32 v6, v6, v74
	v_cndmask_b32_e32 v5, v5, v12, vcc
	v_cmp_lt_f32_e32 vcc, 0, v19
	v_mul_f32_e32 v6, 0xbfb8aa3b, v6
	v_exp_f32_e32 v6, v6
	v_cndmask_b32_e32 v5, v5, v13, vcc
	v_mul_f32_e32 v12, 0x37800000, v5
	v_cndmask_b32_e64 v5, v5, v12, s[12:13]
	v_cmp_class_f32_e32 vcc, v4, v182
	s_waitcnt vmcnt(0) lgkmcnt(0)
; DI unsigned pk2(float a, float b) { f32x2 v = {a, b}; bf16v2_t r = __builtin_convertvector(v, bf16v2_t); return __builtin_bit_cast(unsigned, r); }
; DI float sigm(float x) { return 1.f / (1.f + __expf(-x)); }
;     DI void operator()(const Acc& acc, const Unit& u, int wr, int wc, int fr, int fq, const float (&pre)[8]) const {
;     ...
;                 for (int m = 0; m < 4; ++m) { const size_t o = (size_t)(row0 + ai * HALF + m * 16) * DM + f0 + 4 * n;
;                     const u32x2 xw = *(const u32x2*)(xc + o);
;                     const float xv[4] = {__uint_as_float(xw.x << 16), __uint_as_float(xw.x & 0xffff0000u), __uint_as_float(xw.y << 16), __uint_as_float(xw.y & 0xffff0000u)};
;                     u32x4 w;
; #pragma unroll
;                     for (int e = 0; e < 4; ++e) { const float r = sigm(acc[ai][0][m][n][e] + br[e]), ig = sigm(acc[ai][1][m][n][e] + bi[e]);
;                         const float la = -sp[e] * r, uu = -2.f * la;
;                         const float om = uu * (1.f - uu * 0.5f * (1.f - uu * (1.f / 3.f) * (1.f - uu * 0.25f * (1.f - uu * 0.2f * (1.f - uu * (1.f / 6.f))))));
;                         w[e] = pk2(la, sqrtf(fmaxf(om, 0.f)) * ig * xv[e]); }
;                     *(u32x4*)(ax + o) = w; __builtin_amdgcn_sched_barrier(0); }
	v_and_b32_e32 v12, 0xffff0000, v10
	v_lshlrev_b32_e32 v13, 16, v11
	v_cndmask_b32_e32 v4, v5, v4, vcc
	v_mul_f32_e32 v0, v0, v4
	v_lshlrev_b32_e32 v4, 16, v10
	v_mul_f32_e32 v0, v0, v4
	v_rcp_f32_e32 v4, v14
	v_and_b32_e32 v17, 0xffff0000, v11
	v_mul_f32_e64 v18, v4, -v65
	v_mul_f32_e32 v4, -2.0, v18
	v_cvt_pk_bf16_f32 v0, v16, v0
	v_mul_f32_e32 v5, 0x3e4ccccd, v4
	v_fma_f32 v157, v4, s81, 1.0
	v_pk_mul_f32 v[10:11], v[4:5], v[156:157]
	v_mul_f32_e32 v19, 0x3eaaaaab, v4
	v_sub_f32_e32 v5, 1.0, v11
	v_fma_f32 v159, -v10, v5, 1.0
	v_mov_b32_e32 v5, v19
	v_pk_mul_f32 v[10:11], v[4:5], v[158:159]
	v_add_f32_e32 v2, v2, v70
	v_sub_f32_e32 v5, 1.0, v11
	v_fma_f32 v5, -v10, v5, 1.0
	v_mul_f32_e32 v4, v4, v5
	v_max_f32_e32 v4, 0, v4
	v_mul_f32_e32 v5, 0x4f800000, v4
	v_cmp_gt_f32_e64 s[10:11], s82, v4
	v_rcp_f32_e32 v1, v1
	s_nop 0
	v_cndmask_b32_e64 v4, v4, v5, s[10:11]
	v_sqrt_f32_e32 v5, v4
	v_mul_f32_e32 v2, 0xbfb8aa3b, v2
	v_exp_f32_e32 v2, v2
	v_add_f32_e32 v7, v7, v75
	v_add_u32_e32 v10, -1, v5
	v_fma_f32 v11, -v10, v5, v4
	v_cmp_ge_f32_e32 vcc, 0, v11
	v_add_u32_e32 v11, 1, v5
	v_add_f32_e32 v2, 1.0, v2
	v_cndmask_b32_e32 v10, v5, v10, vcc
	v_fma_f32 v5, -v11, v5, v4
	v_cmp_lt_f32_e32 vcc, 0, v5
	v_mul_f32_e32 v7, 0xbfb8aa3b, v7
	v_exp_f32_e32 v7, v7
	v_cndmask_b32_e32 v5, v10, v11, vcc
	v_mul_f32_e32 v10, 0x37800000, v5
	v_cndmask_b32_e64 v5, v5, v10, s[10:11]
	v_cmp_class_f32_e32 vcc, v4, v182
	v_add_f32_e32 v3, v3, v71
	v_mul_f32_e32 v3, 0xbfb8aa3b, v3
	v_cndmask_b32_e32 v4, v5, v4, vcc
	v_add_f32_e32 v5, 1.0, v6
	v_mul_f32_e32 v1, v1, v4
	v_mul_f32_e32 v1, v1, v12
	v_exp_f32_e32 v3, v3
	v_rcp_f32_e32 v4, v5
	s_nop 0
	v_mul_f32_e64 v15, v4, -v66
	v_mul_f32_e32 v4, -2.0, v15
	v_mul_f32_e32 v5, 0x3e4ccccd, v4
	v_fma_f32 v157, v4, s81, 1.0
	v_pk_mul_f32 v[10:11], v[4:5], v[156:157]
	v_mul_f32_e32 v16, 0x3eaaaaab, v4
	v_sub_f32_e32 v5, 1.0, v11
	v_fma_f32 v159, -v10, v5, 1.0
	v_mov_b32_e32 v5, v16
	v_pk_mul_f32 v[10:11], v[4:5], v[158:159]
	v_sub_f32_e32 v5, 1.0, v11
	v_fma_f32 v5, -v10, v5, 1.0
	v_mul_f32_e32 v4, v4, v5
	v_max_f32_e32 v4, 0, v4
	v_mul_f32_e32 v5, 0x4f800000, v4
	v_cmp_gt_f32_e64 s[10:11], s82, v4
	v_rcp_f32_e32 v2, v2
	v_add_f32_e32 v3, 1.0, v3
	v_cndmask_b32_e64 v4, v4, v5, s[10:11]
	v_sqrt_f32_e32 v5, v4
	v_cvt_pk_bf16_f32 v1, v18, v1
	v_add_u32_e32 v6, -1, v5
	v_fma_f32 v10, -v6, v5, v4
	v_cmp_ge_f32_e32 vcc, 0, v10
	v_add_u32_e32 v10, 1, v5
	s_nop 0
	v_cndmask_b32_e32 v6, v5, v6, vcc
	v_fma_f32 v5, -v10, v5, v4
	v_cmp_lt_f32_e32 vcc, 0, v5
	s_nop 1
	v_cndmask_b32_e32 v5, v6, v10, vcc
	v_mul_f32_e32 v6, 0x37800000, v5
	v_cndmask_b32_e64 v5, v5, v6, s[10:11]
	v_cmp_class_f32_e32 vcc, v4, v182
	s_nop 1
	v_cndmask_b32_e32 v4, v5, v4, vcc
	v_add_f32_e32 v5, 1.0, v7
	v_mul_f32_e32 v2, v2, v4
	v_mul_f32_e32 v2, v2, v13
	v_cvt_pk_bf16_f32 v2, v15, v2
	v_rcp_f32_e32 v4, v5
	s_nop 0
	v_mul_f32_e64 v13, v4, -v67
	v_mul_f32_e32 v4, -2.0, v13
	v_mul_f32_e32 v5, 0x3e4ccccd, v4
	v_fma_f32 v157, v4, s81, 1.0
	v_pk_mul_f32 v[6:7], v[4:5], v[156:157]
	v_mul_f32_e32 v14, 0x3eaaaaab, v4
	v_sub_f32_e32 v5, 1.0, v7
	v_fma_f32 v159, -v6, v5, 1.0
	v_mov_b32_e32 v5, v14
	v_pk_mul_f32 v[6:7], v[4:5], v[158:159]
	s_nop 0
	v_sub_f32_e32 v5, 1.0, v7
	v_fma_f32 v5, -v6, v5, 1.0
	v_mul_f32_e32 v4, v4, v5
	v_max_f32_e32 v4, 0, v4
	v_mul_f32_e32 v5, 0x4f800000, v4
	v_cmp_gt_f32_e64 s[10:11], s82, v4
	v_rcp_f32_e32 v3, v3
	s_nop 0
	v_cndmask_b32_e64 v4, v4, v5, s[10:11]
	v_sqrt_f32_e32 v5, v4
	s_nop 0
	v_add_u32_e32 v6, -1, v5
	v_fma_f32 v7, -v6, v5, v4
	v_cmp_ge_f32_e32 vcc, 0, v7
	v_add_u32_e32 v7, 1, v5
	s_nop 0
	v_cndmask_b32_e32 v6, v5, v6, vcc
	v_fma_f32 v5, -v7, v5, v4
	v_cmp_lt_f32_e32 vcc, 0, v5
	s_nop 1
	v_cndmask_b32_e32 v5, v6, v7, vcc
	v_mul_f32_e32 v6, 0x37800000, v5
	v_cndmask_b32_e64 v5, v5, v6, s[10:11]
	v_cmp_class_f32_e32 vcc, v4, v182
	s_nop 1
	v_cndmask_b32_e32 v4, v5, v4, vcc
	v_mul_f32_e32 v3, v3, v4
	v_mul_f32_e32 v3, v3, v17
	v_cvt_pk_bf16_f32 v3, v13, v3
	v_lshl_add_u64 v[4:5], v[8:9], 2, s[36:37]
	flat_store_dwordx4 v[4:5], v[0:3]
	s_and_b64 vcc, exec, s[8:9]
	s_mov_b32 s84, s83
	s_mov_b32 s12, s50
	s_mov_b64 s[14:15], s[58:59]
	s_mov_b64 s[60:61], s[56:57]
	s_cbranch_vccnz .LBB0_954

; DI float bf2f(bf16_t v) { return __uint_as_float((unsigned)v << 16); }
; DI bf16_t f2bf(float a) { return (bf16_t)(pk2(a, 0.f) & 0xffffu); }
; DI float silu(float x) { return x / (1.f + __expf(-x)); }
; DI void phase_lru_scan(const Params& p, LAS unsigned char* lds) {
;     ...
;             float hc = sC[chl];
;             for (int sg = 0; sg < seg; ++sg) hc = sP[sg * 32 + chl] * hc + sH[sg * 32 + chl];
; #pragma unroll
;             for (int t = 0; t < 32; ++t) { const unsigned w = tile[(seg * 32 + t) * 32 + chl]; hc = __expf(__uint_as_float(w << 16)) * hc + __uint_as_float(w & 0xffff0000u);
;                 y[(r0 + t) * DM + ch] = f2bf(hc * silu(bf2f(gq[t]))); }
.LBB0_1024:
	s_or_b64 exec, exec, s[28:29]
	s_waitcnt vmcnt(31)
	v_lshlrev_b32_e32 v79, 16, v152
	ds_read2_b32 v[154:155], v88 offset1:32
	v_mul_f32_e32 v152, 0xbfb8aa3b, v79
	v_exp_f32_e32 v152, v152
	v_lshlrev_b64 v[76:77], 12, v[76:77]
	v_lshl_add_u64 v[76:77], v[12:13], 0, v[76:77]
	s_waitcnt lgkmcnt(0)
	v_lshlrev_b32_e32 v153, 16, v154
	v_add_f32_e32 v152, 1.0, v152
	v_mul_f32_e32 v153, 0x3fb8aa3b, v153
	v_exp_f32_e32 v153, v153
	v_and_b32_e32 v154, 0xffff0000, v154
	s_waitcnt vmcnt(29)
	v_lshlrev_b32_e32 v150, 16, v150
	v_fmac_f32_e32 v154, v78, v153
	v_rcp_f32_e32 v78, v152
	s_nop 0
	v_mul_f32_e32 v78, v79, v78
	v_lshlrev_b32_e32 v79, 16, v151
	v_mul_f32_e32 v151, 0xbfb8aa3b, v79
	v_exp_f32_e32 v151, v151
	v_lshlrev_b32_e32 v152, 16, v155
	v_mul_f32_e32 v78, v78, v154
	v_mul_f32_e32 v152, 0x3fb8aa3b, v152
	v_add_f32_e32 v151, 1.0, v151
	v_cvt_pk_bf16_f32 v78, v78, s0
	v_exp_f32_e32 v152, v152
	global_store_short v[76:77], v78, off
	v_and_b32_e32 v78, 0xffff0000, v155
	v_fmac_f32_e32 v78, v154, v152
	v_rcp_f32_e32 v76, v151
	s_nop 0
	v_mul_f32_e32 v76, v79, v76
	v_mul_f32_e32 v151, 0xbfb8aa3b, v150
	v_exp_f32_e32 v151, v151
	v_mul_f32_e32 v76, v76, v78
	v_cvt_pk_bf16_f32 v79, v76, s0
	ds_read2_b32 v[76:77], v88 offset0:64 offset1:96
	v_add_f32_e32 v151, 1.0, v151
	s_waitcnt lgkmcnt(0)
	v_lshlrev_b32_e32 v152, 16, v76
	v_lshlrev_b64 v[74:75], 12, v[74:75]
	v_mul_f32_e32 v152, 0x3fb8aa3b, v152
	v_lshl_add_u64 v[74:75], v[12:13], 0, v[74:75]
	v_exp_f32_e32 v152, v152
	global_store_short v[74:75], v79, off
	v_and_b32_e32 v74, 0xffff0000, v76
	v_fmac_f32_e32 v74, v78, v152
	s_waitcnt vmcnt(30)
	v_lshlrev_b32_e32 v76, 16, v149
	v_mul_f32_e32 v78, 0xbfb8aa3b, v76
	v_exp_f32_e32 v78, v78
	v_rcp_f32_e32 v75, v151
	s_nop 0
	v_mul_f32_e32 v75, v150, v75
	v_lshlrev_b32_e32 v79, 16, v77
	v_mul_f32_e32 v75, v75, v74
	v_add_f32_e32 v78, 1.0, v78
	v_lshlrev_b64 v[72:73], 12, v[72:73]
	v_mul_f32_e32 v79, 0x3fb8aa3b, v79
	v_cvt_pk_bf16_f32 v75, v75, s0
	v_lshl_add_u64 v[72:73], v[12:13], 0, v[72:73]
	v_exp_f32_e32 v79, v79
	global_store_short v[72:73], v75, off
	v_and_b32_e32 v75, 0xffff0000, v77
	v_fmac_f32_e32 v75, v74, v79
	v_rcp_f32_e32 v72, v78
	s_nop 0
	v_mul_f32_e32 v72, v76, v72
	s_waitcnt vmcnt(30)
	v_lshlrev_b32_e32 v76, 16, v148
	v_mul_f32_e32 v77, 0xbfb8aa3b, v76
	v_exp_f32_e32 v77, v77
	v_mul_f32_e32 v72, v72, v75
	v_cvt_pk_bf16_f32 v74, v72, s0
	ds_read2_b32 v[72:73], v88 offset0:128 offset1:160
	v_add_f32_e32 v77, 1.0, v77
	v_lshlrev_b64 v[70:71], 12, v[70:71]
	v_lshl_add_u64 v[70:71], v[12:13], 0, v[70:71]
	global_store_short v[70:71], v74, off
	s_waitcnt lgkmcnt(0)
	v_lshlrev_b32_e32 v78, 16, v72
	v_and_b32_e32 v70, 0xffff0000, v72
	s_waitcnt vmcnt(30)
	v_lshlrev_b32_e32 v72, 16, v147
	v_mul_f32_e32 v74, 0xbfb8aa3b, v72
	v_exp_f32_e32 v74, v74
	v_mul_f32_e32 v78, 0x3fb8aa3b, v78
	v_exp_f32_e32 v78, v78
	v_rcp_f32_e32 v71, v77
	s_nop 0
	v_mul_f32_e32 v71, v76, v71
	v_add_f32_e32 v74, 1.0, v74
	v_fmac_f32_e32 v70, v75, v78
	v_lshlrev_b32_e32 v75, 16, v73
	v_mul_f32_e32 v71, v71, v70
	v_lshlrev_b64 v[68:69], 12, v[68:69]
	v_mul_f32_e32 v75, 0x3fb8aa3b, v75
	v_cvt_pk_bf16_f32 v71, v71, s0
	v_lshl_add_u64 v[68:69], v[12:13], 0, v[68:69]
	v_exp_f32_e32 v75, v75
	global_store_short v[68:69], v71, off
	v_and_b32_e32 v71, 0xffff0000, v73
	v_fmac_f32_e32 v71, v70, v75
	v_rcp_f32_e32 v68, v74
	s_nop 0
	v_mul_f32_e32 v68, v72, v68
	s_waitcnt vmcnt(30)
	v_lshlrev_b32_e32 v72, 16, v146
	v_mul_f32_e32 v73, 0xbfb8aa3b, v72
	v_exp_f32_e32 v73, v73
	v_mul_f32_e32 v68, v68, v71
	v_cvt_pk_bf16_f32 v70, v68, s0
	ds_read2_b32 v[68:69], v88 offset0:192 offset1:224
	v_add_f32_e32 v73, 1.0, v73
	v_lshlrev_b64 v[66:67], 12, v[66:67]
	v_lshl_add_u64 v[66:67], v[12:13], 0, v[66:67]
	global_store_short v[66:67], v70, off
	s_waitcnt lgkmcnt(0)
	v_lshlrev_b32_e32 v74, 16, v68
	v_and_b32_e32 v66, 0xffff0000, v68
	s_waitcnt vmcnt(30)
	v_lshlrev_b32_e32 v68, 16, v144
	v_mul_f32_e32 v70, 0xbfb8aa3b, v68
	v_exp_f32_e32 v70, v70
	v_mul_f32_e32 v74, 0x3fb8aa3b, v74
	v_exp_f32_e32 v74, v74
	v_rcp_f32_e32 v67, v73
	s_nop 0
	v_mul_f32_e32 v67, v72, v67
	v_add_f32_e32 v70, 1.0, v70
	v_fmac_f32_e32 v66, v71, v74
	v_lshlrev_b32_e32 v71, 16, v69
	v_mul_f32_e32 v67, v67, v66
	v_lshlrev_b64 v[64:65], 12, v[64:65]
	v_mul_f32_e32 v71, 0x3fb8aa3b, v71
	v_cvt_pk_bf16_f32 v67, v67, s0
	v_lshl_add_u64 v[64:65], v[12:13], 0, v[64:65]
	v_exp_f32_e32 v71, v71
	global_store_short v[64:65], v67, off
	v_and_b32_e32 v67, 0xffff0000, v69
	v_fmac_f32_e32 v67, v66, v71
	s_waitcnt vmcnt(30)
	v_lshlrev_b32_e32 v69, 16, v145
	v_rcp_f32_e32 v64, v70
	s_nop 0
	v_mul_f32_e32 v64, v68, v64
	v_mul_f32_e32 v70, 0xbfb8aa3b, v69
	v_exp_f32_e32 v70, v70
	v_mul_f32_e32 v64, v64, v67
	v_add_u32_e32 v68, 0x400, v88
	v_cvt_pk_bf16_f32 v66, v64, s0
	v_add_f32_e32 v70, 1.0, v70
	ds_read2_b32 v[64:65], v68 offset1:32
	v_lshlrev_b64 v[62:63], 12, v[62:63]
	v_lshl_add_u64 v[62:63], v[12:13], 0, v[62:63]
	global_store_short v[62:63], v66, off
	s_waitcnt lgkmcnt(0)
	v_lshlrev_b32_e32 v71, 16, v64
	v_and_b32_e32 v62, 0xffff0000, v64
	s_waitcnt vmcnt(30)
	v_lshlrev_b32_e32 v64, 16, v143
	v_mul_f32_e32 v66, 0xbfb8aa3b, v64
	v_exp_f32_e32 v66, v66
	v_mul_f32_e32 v71, 0x3fb8aa3b, v71
	v_exp_f32_e32 v71, v71
	v_rcp_f32_e32 v63, v70
	s_nop 0
	v_mul_f32_e32 v63, v69, v63
	v_add_f32_e32 v66, 1.0, v66
	v_fmac_f32_e32 v62, v67, v71
	v_lshlrev_b32_e32 v67, 16, v65
	v_mul_f32_e32 v63, v63, v62
	v_lshlrev_b64 v[60:61], 12, v[60:61]
	v_mul_f32_e32 v67, 0x3fb8aa3b, v67
	v_cvt_pk_bf16_f32 v63, v63, s0
	v_lshl_add_u64 v[60:61], v[12:13], 0, v[60:61]
	v_exp_f32_e32 v67, v67
	global_store_short v[60:61], v63, off
	v_and_b32_e32 v63, 0xffff0000, v65
	v_fmac_f32_e32 v63, v62, v67
	v_rcp_f32_e32 v60, v66
	s_nop 0
	v_mul_f32_e32 v60, v64, v60
	s_waitcnt vmcnt(30)
; DI float bf2f(bf16_t v) { return __uint_as_float((unsigned)v << 16); }
; DI bf16_t f2bf(float a) { return (bf16_t)(pk2(a, 0.f) & 0xffffu); }
; DI float silu(float x) { return x / (1.f + __expf(-x)); }
; DI void phase_lru_scan(const Params& p, LAS unsigned char* lds) {
;     ...
;             float hc = sC[chl];
;             for (int sg = 0; sg < seg; ++sg) hc = sP[sg * 32 + chl] * hc + sH[sg * 32 + chl];
; #pragma unroll
;             for (int t = 0; t < 32; ++t) { const unsigned w = tile[(seg * 32 + t) * 32 + chl]; hc = __expf(__uint_as_float(w << 16)) * hc + __uint_as_float(w & 0xffff0000u);
;                 y[(r0 + t) * DM + ch] = f2bf(hc * silu(bf2f(gq[t]))); }
	v_lshlrev_b32_e32 v64, 16, v142
	v_mul_f32_e32 v65, 0xbfb8aa3b, v64
	v_exp_f32_e32 v65, v65
	v_mul_f32_e32 v60, v60, v63
	v_cvt_pk_bf16_f32 v62, v60, s0
	ds_read2_b32 v[60:61], v68 offset0:64 offset1:96
	v_add_f32_e32 v65, 1.0, v65
	v_lshlrev_b64 v[58:59], 12, v[58:59]
	v_lshl_add_u64 v[58:59], v[12:13], 0, v[58:59]
	global_store_short v[58:59], v62, off
	s_waitcnt lgkmcnt(0)
	v_lshlrev_b32_e32 v66, 16, v60
	v_and_b32_e32 v58, 0xffff0000, v60
	s_waitcnt vmcnt(30)
	v_lshlrev_b32_e32 v60, 16, v141
	v_mul_f32_e32 v62, 0xbfb8aa3b, v60
	v_exp_f32_e32 v62, v62
	v_mul_f32_e32 v66, 0x3fb8aa3b, v66
	v_exp_f32_e32 v66, v66
	v_rcp_f32_e32 v59, v65
	s_nop 0
	v_mul_f32_e32 v59, v64, v59
	v_add_f32_e32 v62, 1.0, v62
	v_fmac_f32_e32 v58, v63, v66
	v_lshlrev_b32_e32 v63, 16, v61
	v_mul_f32_e32 v59, v59, v58
	v_lshlrev_b64 v[56:57], 12, v[56:57]
	v_mul_f32_e32 v63, 0x3fb8aa3b, v63
	v_cvt_pk_bf16_f32 v59, v59, s0
	v_lshl_add_u64 v[56:57], v[12:13], 0, v[56:57]
	v_exp_f32_e32 v63, v63
	global_store_short v[56:57], v59, off
	v_and_b32_e32 v59, 0xffff0000, v61
	v_fmac_f32_e32 v59, v58, v63
	v_rcp_f32_e32 v56, v62
	s_nop 0
	v_mul_f32_e32 v56, v60, v56
	s_waitcnt vmcnt(30)
	v_lshlrev_b32_e32 v60, 16, v140
	v_mul_f32_e32 v61, 0xbfb8aa3b, v60
	v_exp_f32_e32 v61, v61
	v_mul_f32_e32 v56, v56, v59
	v_cvt_pk_bf16_f32 v58, v56, s0
	ds_read2_b32 v[56:57], v68 offset0:128 offset1:160
	v_add_f32_e32 v61, 1.0, v61
	v_lshlrev_b64 v[54:55], 12, v[54:55]
	v_lshl_add_u64 v[54:55], v[12:13], 0, v[54:55]
	global_store_short v[54:55], v58, off
	s_waitcnt lgkmcnt(0)
	v_lshlrev_b32_e32 v62, 16, v56
	v_and_b32_e32 v54, 0xffff0000, v56
	s_waitcnt vmcnt(30)
	v_lshlrev_b32_e32 v56, 16, v139
	v_mul_f32_e32 v58, 0xbfb8aa3b, v56
	v_exp_f32_e32 v58, v58
	v_mul_f32_e32 v62, 0x3fb8aa3b, v62
	v_exp_f32_e32 v62, v62
	v_rcp_f32_e32 v55, v61
	s_nop 0
	v_mul_f32_e32 v55, v60, v55
	v_add_f32_e32 v58, 1.0, v58
	v_fmac_f32_e32 v54, v59, v62
	v_lshlrev_b32_e32 v59, 16, v57
	v_mul_f32_e32 v55, v55, v54
	v_lshlrev_b64 v[52:53], 12, v[52:53]
	v_mul_f32_e32 v59, 0x3fb8aa3b, v59
	v_cvt_pk_bf16_f32 v55, v55, s0
	v_lshl_add_u64 v[52:53], v[12:13], 0, v[52:53]
	v_exp_f32_e32 v59, v59
	global_store_short v[52:53], v55, off
	v_and_b32_e32 v55, 0xffff0000, v57
	v_fmac_f32_e32 v55, v54, v59
	v_rcp_f32_e32 v52, v58
	s_nop 0
	v_mul_f32_e32 v52, v56, v52
	s_waitcnt vmcnt(30)
	v_lshlrev_b32_e32 v56, 16, v138
	v_mul_f32_e32 v57, 0xbfb8aa3b, v56
	v_exp_f32_e32 v57, v57
	v_mul_f32_e32 v52, v52, v55
	v_cvt_pk_bf16_f32 v54, v52, s0
	ds_read2_b32 v[52:53], v68 offset0:192 offset1:224
	v_add_f32_e32 v57, 1.0, v57
	v_lshlrev_b64 v[50:51], 12, v[50:51]
	v_lshl_add_u64 v[50:51], v[12:13], 0, v[50:51]
	global_store_short v[50:51], v54, off
	s_waitcnt lgkmcnt(0)
	v_lshlrev_b32_e32 v58, 16, v52
	v_and_b32_e32 v50, 0xffff0000, v52
	s_waitcnt vmcnt(30)
	v_lshlrev_b32_e32 v52, 16, v136
	v_mul_f32_e32 v54, 0xbfb8aa3b, v52
	v_exp_f32_e32 v54, v54
	v_mul_f32_e32 v58, 0x3fb8aa3b, v58
	v_exp_f32_e32 v58, v58
	v_rcp_f32_e32 v51, v57
	s_nop 0
	v_mul_f32_e32 v51, v56, v51
	v_add_f32_e32 v54, 1.0, v54
	v_fmac_f32_e32 v50, v55, v58
	v_lshlrev_b32_e32 v55, 16, v53
	v_mul_f32_e32 v51, v51, v50
	v_lshlrev_b64 v[48:49], 12, v[48:49]
	v_mul_f32_e32 v55, 0x3fb8aa3b, v55
	v_cvt_pk_bf16_f32 v51, v51, s0
	v_lshl_add_u64 v[48:49], v[12:13], 0, v[48:49]
	v_exp_f32_e32 v55, v55
	global_store_short v[48:49], v51, off
	v_and_b32_e32 v51, 0xffff0000, v53
	v_fmac_f32_e32 v51, v50, v55
	s_waitcnt vmcnt(30)
	v_lshlrev_b32_e32 v53, 16, v137
	v_rcp_f32_e32 v48, v54
	s_nop 0
	v_mul_f32_e32 v48, v52, v48
	v_mul_f32_e32 v54, 0xbfb8aa3b, v53
	v_exp_f32_e32 v54, v54
	v_mul_f32_e32 v48, v48, v51
	v_add_u32_e32 v52, 0x800, v88
	v_cvt_pk_bf16_f32 v50, v48, s0
	v_add_f32_e32 v54, 1.0, v54
	ds_read2_b32 v[48:49], v52 offset1:32
	v_lshlrev_b64 v[46:47], 12, v[46:47]
	v_lshl_add_u64 v[46:47], v[12:13], 0, v[46:47]
	global_store_short v[46:47], v50, off
	s_waitcnt lgkmcnt(0)
	v_lshlrev_b32_e32 v55, 16, v48
	v_and_b32_e32 v46, 0xffff0000, v48
	s_waitcnt vmcnt(30)
	v_lshlrev_b32_e32 v48, 16, v135
	v_mul_f32_e32 v50, 0xbfb8aa3b, v48
	v_exp_f32_e32 v50, v50
	v_mul_f32_e32 v55, 0x3fb8aa3b, v55
	v_exp_f32_e32 v55, v55
	v_rcp_f32_e32 v47, v54
	s_nop 0
	v_mul_f32_e32 v47, v53, v47
	v_add_f32_e32 v50, 1.0, v50
	v_fmac_f32_e32 v46, v51, v55
	v_lshlrev_b32_e32 v51, 16, v49
	v_mul_f32_e32 v47, v47, v46
	v_lshlrev_b64 v[44:45], 12, v[44:45]
	v_mul_f32_e32 v51, 0x3fb8aa3b, v51
	v_cvt_pk_bf16_f32 v47, v47, s0
	v_lshl_add_u64 v[44:45], v[12:13], 0, v[44:45]
	v_exp_f32_e32 v51, v51
	global_store_short v[44:45], v47, off
	v_and_b32_e32 v47, 0xffff0000, v49
	v_fmac_f32_e32 v47, v46, v51
	v_rcp_f32_e32 v44, v50
	s_nop 0
	v_mul_f32_e32 v44, v48, v44
	s_waitcnt vmcnt(30)
	v_lshlrev_b32_e32 v48, 16, v134
	v_mul_f32_e32 v49, 0xbfb8aa3b, v48
	v_exp_f32_e32 v49, v49
	v_mul_f32_e32 v44, v44, v47
	v_cvt_pk_bf16_f32 v46, v44, s0
	ds_read2_b32 v[44:45], v52 offset0:64 offset1:96
	v_add_f32_e32 v49, 1.0, v49
	v_lshlrev_b64 v[42:43], 12, v[42:43]
	v_lshl_add_u64 v[42:43], v[12:13], 0, v[42:43]
	global_store_short v[42:43], v46, off
	s_waitcnt lgkmcnt(0)
	v_lshlrev_b32_e32 v50, 16, v44
	v_and_b32_e32 v42, 0xffff0000, v44
	s_waitcnt vmcnt(30)
	v_lshlrev_b32_e32 v44, 16, v133
	v_mul_f32_e32 v46, 0xbfb8aa3b, v44
	v_exp_f32_e32 v46, v46
	v_mul_f32_e32 v50, 0x3fb8aa3b, v50
	v_exp_f32_e32 v50, v50
	v_rcp_f32_e32 v43, v49
	s_nop 0
	v_mul_f32_e32 v43, v48, v43
	v_add_f32_e32 v46, 1.0, v46
	v_fmac_f32_e32 v42, v47, v50
	v_lshlrev_b32_e32 v47, 16, v45
	v_mul_f32_e32 v43, v43, v42
	v_lshlrev_b64 v[40:41], 12, v[40:41]
	v_mul_f32_e32 v47, 0x3fb8aa3b, v47
	v_cvt_pk_bf16_f32 v43, v43, s0
	v_lshl_add_u64 v[40:41], v[12:13], 0, v[40:41]
	v_exp_f32_e32 v47, v47
	global_store_short v[40:41], v43, off
	v_and_b32_e32 v43, 0xffff0000, v45
	v_fmac_f32_e32 v43, v42, v47
	v_rcp_f32_e32 v40, v46
	s_nop 0
	v_mul_f32_e32 v40, v44, v40
	s_waitcnt vmcnt(30)
; DI float bf2f(bf16_t v) { return __uint_as_float((unsigned)v << 16); }
; DI bf16_t f2bf(float a) { return (bf16_t)(pk2(a, 0.f) & 0xffffu); }
; DI float silu(float x) { return x / (1.f + __expf(-x)); }
; DI void phase_lru_scan(const Params& p, LAS unsigned char* lds) {
;     ...
;             float hc = sC[chl];
;             for (int sg = 0; sg < seg; ++sg) hc = sP[sg * 32 + chl] * hc + sH[sg * 32 + chl];
; #pragma unroll
;             for (int t = 0; t < 32; ++t) { const unsigned w = tile[(seg * 32 + t) * 32 + chl]; hc = __expf(__uint_as_float(w << 16)) * hc + __uint_as_float(w & 0xffff0000u);
;                 y[(r0 + t) * DM + ch] = f2bf(hc * silu(bf2f(gq[t]))); }
	v_lshlrev_b32_e32 v44, 16, v132
	v_mul_f32_e32 v45, 0xbfb8aa3b, v44
	v_exp_f32_e32 v45, v45
	v_mul_f32_e32 v40, v40, v43
	v_cvt_pk_bf16_f32 v42, v40, s0
	ds_read2_b32 v[40:41], v52 offset0:128 offset1:160
	v_add_f32_e32 v45, 1.0, v45
	v_lshlrev_b64 v[38:39], 12, v[38:39]
	v_lshl_add_u64 v[38:39], v[12:13], 0, v[38:39]
	global_store_short v[38:39], v42, off
	s_waitcnt lgkmcnt(0)
	v_lshlrev_b32_e32 v46, 16, v40
	v_and_b32_e32 v38, 0xffff0000, v40
	s_waitcnt vmcnt(30)
	v_lshlrev_b32_e32 v40, 16, v131
	v_mul_f32_e32 v42, 0xbfb8aa3b, v40
	v_exp_f32_e32 v42, v42
	v_mul_f32_e32 v46, 0x3fb8aa3b, v46
	v_exp_f32_e32 v46, v46
	v_rcp_f32_e32 v39, v45
	s_nop 0
	v_mul_f32_e32 v39, v44, v39
	v_add_f32_e32 v42, 1.0, v42
	v_fmac_f32_e32 v38, v43, v46
	v_lshlrev_b32_e32 v43, 16, v41
	v_mul_f32_e32 v39, v39, v38
	v_lshlrev_b64 v[36:37], 12, v[36:37]
	v_mul_f32_e32 v43, 0x3fb8aa3b, v43
	v_cvt_pk_bf16_f32 v39, v39, s0
	v_lshl_add_u64 v[36:37], v[12:13], 0, v[36:37]
	v_exp_f32_e32 v43, v43
	global_store_short v[36:37], v39, off
	v_and_b32_e32 v39, 0xffff0000, v41
	v_fmac_f32_e32 v39, v38, v43
	v_rcp_f32_e32 v36, v42
	s_nop 0
	v_mul_f32_e32 v36, v40, v36
	s_waitcnt vmcnt(30)
	v_lshlrev_b32_e32 v40, 16, v130
	v_mul_f32_e32 v41, 0xbfb8aa3b, v40
	v_exp_f32_e32 v41, v41
	v_mul_f32_e32 v36, v36, v39
	v_cvt_pk_bf16_f32 v38, v36, s0
	ds_read2_b32 v[36:37], v52 offset0:192 offset1:224
	v_add_f32_e32 v41, 1.0, v41
	v_lshlrev_b64 v[34:35], 12, v[34:35]
	v_lshl_add_u64 v[34:35], v[12:13], 0, v[34:35]
	global_store_short v[34:35], v38, off
	s_waitcnt lgkmcnt(0)
	v_lshlrev_b32_e32 v42, 16, v36
	v_and_b32_e32 v34, 0xffff0000, v36
	s_waitcnt vmcnt(30)
	v_lshlrev_b32_e32 v36, 16, v128
	v_mul_f32_e32 v38, 0xbfb8aa3b, v36
	v_exp_f32_e32 v38, v38
	v_mul_f32_e32 v42, 0x3fb8aa3b, v42
	v_exp_f32_e32 v42, v42
	v_rcp_f32_e32 v35, v41
	s_nop 0
	v_mul_f32_e32 v35, v40, v35
	v_add_f32_e32 v38, 1.0, v38
	v_fmac_f32_e32 v34, v39, v42
	v_lshlrev_b32_e32 v39, 16, v37
	v_mul_f32_e32 v35, v35, v34
	v_lshlrev_b64 v[32:33], 12, v[32:33]
	v_mul_f32_e32 v39, 0x3fb8aa3b, v39
	v_cvt_pk_bf16_f32 v35, v35, s0
	v_lshl_add_u64 v[32:33], v[12:13], 0, v[32:33]
	v_exp_f32_e32 v39, v39
	global_store_short v[32:33], v35, off
	v_and_b32_e32 v35, 0xffff0000, v37
	v_fmac_f32_e32 v35, v34, v39
	s_waitcnt vmcnt(30)
	v_lshlrev_b32_e32 v37, 16, v129
	v_rcp_f32_e32 v32, v38
	s_nop 0
	v_mul_f32_e32 v32, v36, v32
	v_mul_f32_e32 v38, 0xbfb8aa3b, v37
	v_exp_f32_e32 v38, v38
	v_mul_f32_e32 v32, v32, v35
	v_add_u32_e32 v36, 0xc00, v88
	v_cvt_pk_bf16_f32 v34, v32, s0
	v_add_f32_e32 v38, 1.0, v38
	ds_read2_b32 v[32:33], v36 offset1:32
	v_lshlrev_b64 v[30:31], 12, v[30:31]
	v_lshl_add_u64 v[30:31], v[12:13], 0, v[30:31]
	global_store_short v[30:31], v34, off
	s_waitcnt lgkmcnt(0)
	v_lshlrev_b32_e32 v39, 16, v32
	v_and_b32_e32 v30, 0xffff0000, v32
	s_waitcnt vmcnt(30)
	v_lshlrev_b32_e32 v32, 16, v127
	v_mul_f32_e32 v34, 0xbfb8aa3b, v32
	v_exp_f32_e32 v34, v34
	v_mul_f32_e32 v39, 0x3fb8aa3b, v39
	v_exp_f32_e32 v39, v39
	v_rcp_f32_e32 v31, v38
	s_nop 0
	v_mul_f32_e32 v31, v37, v31
	v_add_f32_e32 v34, 1.0, v34
	v_fmac_f32_e32 v30, v35, v39
	v_lshlrev_b32_e32 v35, 16, v33
	v_mul_f32_e32 v31, v31, v30
	v_lshlrev_b64 v[28:29], 12, v[28:29]
	v_mul_f32_e32 v35, 0x3fb8aa3b, v35
	v_cvt_pk_bf16_f32 v31, v31, s0
	v_lshl_add_u64 v[28:29], v[12:13], 0, v[28:29]
	v_exp_f32_e32 v35, v35
	global_store_short v[28:29], v31, off
	v_and_b32_e32 v31, 0xffff0000, v33
	v_fmac_f32_e32 v31, v30, v35
	v_rcp_f32_e32 v28, v34
	s_nop 0
	v_mul_f32_e32 v28, v32, v28
	s_waitcnt vmcnt(30)
; DI float bf2f(bf16_t v) { return __uint_as_float((unsigned)v << 16); }
; DI bf16_t f2bf(float a) { return (bf16_t)(pk2(a, 0.f) & 0xffffu); }
; DI float silu(float x) { return x / (1.f + __expf(-x)); }
; DI void phase_lru_scan(const Params& p, LAS unsigned char* lds) {
;     ...
;             for (int t = 0; t < 32; ++t) { const unsigned w = tile[(seg * 32 + t) * 32 + chl]; hc = __expf(__uint_as_float(w << 16)) * hc + __uint_as_float(w & 0xffff0000u);
;                 y[(r0 + t) * DM + ch] = f2bf(hc * silu(bf2f(gq[t]))); }
;             __syncthreads();
;             if (seg == 15) sC[chl] = hc;
	v_lshlrev_b32_e32 v32, 16, v126
	v_mul_f32_e32 v33, 0xbfb8aa3b, v32
	v_exp_f32_e32 v33, v33
	v_mul_f32_e32 v28, v28, v31
	v_cvt_pk_bf16_f32 v30, v28, s0
	ds_read2_b32 v[28:29], v36 offset0:64 offset1:96
	v_add_f32_e32 v33, 1.0, v33
	v_lshlrev_b64 v[26:27], 12, v[26:27]
	v_lshl_add_u64 v[26:27], v[12:13], 0, v[26:27]
	global_store_short v[26:27], v30, off
	s_waitcnt lgkmcnt(0)
	v_lshlrev_b32_e32 v34, 16, v28
	v_and_b32_e32 v26, 0xffff0000, v28
	s_waitcnt vmcnt(30)
	v_lshlrev_b32_e32 v28, 16, v125
	v_mul_f32_e32 v30, 0xbfb8aa3b, v28
	v_exp_f32_e32 v30, v30
	v_mul_f32_e32 v34, 0x3fb8aa3b, v34
	v_exp_f32_e32 v34, v34
	v_rcp_f32_e32 v27, v33
	s_nop 0
	v_mul_f32_e32 v27, v32, v27
	v_add_f32_e32 v30, 1.0, v30
	v_fmac_f32_e32 v26, v31, v34
	v_lshlrev_b32_e32 v31, 16, v29
	v_mul_f32_e32 v27, v27, v26
	v_lshlrev_b64 v[24:25], 12, v[24:25]
	v_mul_f32_e32 v31, 0x3fb8aa3b, v31
	v_cvt_pk_bf16_f32 v27, v27, s0
	v_lshl_add_u64 v[24:25], v[12:13], 0, v[24:25]
	v_exp_f32_e32 v31, v31
	global_store_short v[24:25], v27, off
	v_and_b32_e32 v27, 0xffff0000, v29
	v_fmac_f32_e32 v27, v26, v31
	v_rcp_f32_e32 v24, v30
	s_nop 0
	v_mul_f32_e32 v24, v28, v24
	s_waitcnt vmcnt(30)
	v_lshlrev_b32_e32 v28, 16, v124
	v_mul_f32_e32 v29, 0xbfb8aa3b, v28
	v_exp_f32_e32 v29, v29
	v_mul_f32_e32 v24, v24, v27
	v_cvt_pk_bf16_f32 v26, v24, s0
	ds_read2_b32 v[24:25], v36 offset0:128 offset1:160
	v_add_f32_e32 v29, 1.0, v29
	v_lshlrev_b64 v[22:23], 12, v[22:23]
	v_lshl_add_u64 v[22:23], v[12:13], 0, v[22:23]
	global_store_short v[22:23], v26, off
	s_waitcnt lgkmcnt(0)
	v_lshlrev_b32_e32 v30, 16, v24
	v_and_b32_e32 v22, 0xffff0000, v24
	s_waitcnt vmcnt(30)
	v_lshlrev_b32_e32 v24, 16, v123
	v_mul_f32_e32 v26, 0xbfb8aa3b, v24
	v_exp_f32_e32 v26, v26
	v_mul_f32_e32 v30, 0x3fb8aa3b, v30
	v_exp_f32_e32 v30, v30
	v_rcp_f32_e32 v23, v29
	s_nop 0
	v_mul_f32_e32 v23, v28, v23
	v_add_f32_e32 v26, 1.0, v26
	v_fmac_f32_e32 v22, v27, v30
	v_lshlrev_b32_e32 v27, 16, v25
	v_mul_f32_e32 v27, 0x3fb8aa3b, v27
	v_mul_f32_e32 v23, v23, v22
	v_lshlrev_b64 v[20:21], 12, v[20:21]
	v_exp_f32_e32 v27, v27
	v_cvt_pk_bf16_f32 v23, v23, s0
	v_lshl_add_u64 v[20:21], v[12:13], 0, v[20:21]
	global_store_short v[20:21], v23, off
	v_and_b32_e32 v20, 0xffff0000, v25
	v_fmac_f32_e32 v20, v22, v27
	s_waitcnt vmcnt(30)
	v_lshlrev_b32_e32 v23, 16, v122
	v_rcp_f32_e32 v21, v26
	s_nop 0
	v_mul_f32_e32 v21, v24, v21
	v_mul_f32_e32 v24, 0xbfb8aa3b, v23
	v_exp_f32_e32 v24, v24
	ds_read_b32 v22, v88 offset:3840
	ds_read_b32 v25, v89
	v_mul_f32_e32 v21, v21, v20
	v_add_f32_e32 v24, 1.0, v24
	s_waitcnt lgkmcnt(1)
	v_lshlrev_b32_e32 v26, 16, v22
	v_mul_f32_e32 v26, 0x3fb8aa3b, v26
	v_lshlrev_b64 v[18:19], 12, v[18:19]
	v_exp_f32_e32 v26, v26
	v_cvt_pk_bf16_f32 v21, v21, s0
	v_lshl_add_u64 v[18:19], v[12:13], 0, v[18:19]
	global_store_short v[18:19], v21, off
	v_and_b32_e32 v18, 0xffff0000, v22
	v_fmac_f32_e32 v18, v20, v26
	s_waitcnt vmcnt(30)
	v_lshlrev_b32_e32 v20, 16, v4
	v_mul_f32_e32 v4, 0xbfb8aa3b, v20
	v_exp_f32_e32 v4, v4
	v_rcp_f32_e32 v19, v24
	s_nop 0
	v_mul_f32_e32 v19, v23, v19
	s_waitcnt lgkmcnt(0)
	v_lshlrev_b32_e32 v21, 16, v25
	v_mul_f32_e32 v19, v19, v18
	v_add_f32_e32 v22, 1.0, v4
	v_lshlrev_b64 v[16:17], 12, v[16:17]
	v_mul_f32_e32 v21, 0x3fb8aa3b, v21
	v_cvt_pk_bf16_f32 v19, v19, s0
	v_lshl_add_u64 v[16:17], v[12:13], 0, v[16:17]
	v_exp_f32_e32 v21, v21
	global_store_short v[16:17], v19, off
	v_and_b32_e32 v4, 0xffff0000, v25
	v_fmac_f32_e32 v4, v18, v21
	v_rcp_f32_e32 v16, v22
	s_nop 0
	v_mul_f32_e32 v16, v20, v16
	v_mul_f32_e32 v16, v16, v4
	v_lshlrev_b64 v[14:15], 12, v[14:15]
	v_cvt_pk_bf16_f32 v16, v16, s0
	v_lshl_add_u64 v[14:15], v[12:13], 0, v[14:15]
	global_store_short v[14:15], v16, off
	s_barrier
	s_and_saveexec_b64 s[28:29], s[10:11]
	s_cbranch_execz .LBB0_1015
	ds_write_b32 v85, v4
	s_branch .LBB0_1015
